# GEMM K-loop back-edge rotation: counter/pointer SALU + s_cmp moved before the iteration-end s_barrier (8 loops), on top of v14
# speedup vs baseline: 1.0048x; 1.0048x over previous
; #define PG8_STAGE(bufoff, gbase, voff) do { _Pragma("unroll") for (int _i = 0; _i < 2; ++_i) \
;         __builtin_amdgcn_global_load_lds((const unsigned*)((const char*)(gbase) + (voff)[_i]), (LAS unsigned*)(lds + (bufoff) + ldsw + _i * 8192), 16, 0, 0); } while (0)
; #define PG8_LDA(dst, b, h) do { _Pragma("unroll") for (int m = 0; m < 4; ++m) _Pragma("unroll") for (int k = 0; k < 2; ++k) dst[m][k] = *(const LAS bf16x8*)(lds + PG8_SA(b, h) + aoff + m * 2048 + k * 1024); } while (0)
; #define PG8_LDB(dst, b, h) do { _Pragma("unroll") for (int n = 0; n < 2; ++n) _Pragma("unroll") for (int k = 0; k < 2; ++k) dst[n][k] = *(const LAS bf16x8*)(lds + PG8_SB(b, h) + boff + n * 2048 + k * 1024); } while (0)
; #define PG8_MMA(ai, bj, At, Bt) do { __builtin_amdgcn_s_setprio(1); _Pragma("unroll") for (int m = 0; m < 4; ++m) _Pragma("unroll") for (int n = 0; n < 2; ++n) _Pragma("unroll") for (int k = 0; k < 2; ++k) \
;         acc[ai][bj][m][n] = __builtin_amdgcn_mfma_f32_16x16x32_bf16(Bt[n][k], At[m][k], acc[ai][bj][m][n], 0, 0, 0); __builtin_amdgcn_s_setprio(0); } while (0)
; #define PG8_WAIT_V(n) asm volatile("s_waitcnt vmcnt(" #n ")" ::: "memory")
; #define PG8_WAIT_L(n) asm volatile("s_waitcnt lgkmcnt(" #n ")" ::: "memory")
; #define PG8_BAR __builtin_amdgcn_s_barrier()
; #define PG8_SCHED __builtin_amdgcn_sched_barrier(0)
; template <class Epi, bool HALO>
; __device__ __forceinline__ void gemm_phase(LAS unsigned char* lds, const Gemm g, const StaticOrder& S, const Epi& E) {
;     ...
;         for (int t = 0; t < nt; t += 2) {
;             const bool last = (t == nt - 2);
;             const char* a1 = cA + (size_t)(t + 1) * kstep;
;             const char* a2 = last ? nA : cA + (size_t)(t + 2) * kstep; const char* b2 = last ? nB : cB + (size_t)(t + 2) * kstepB;
;             const char* a3 = a2 + kstep; const char* b3 = b2 + kstepB;
;             PG8_LDB(B0, 0, 0); PG8_LDB(B1, 0, 1); PG8_SCHED; PG8_LDA(At, 0, 0); PG8_STAGE(PG8_SA(1, 1), a1 + hstepA, voffA);
;             PG8_WAIT_V(8); PG8_WAIT_L(0); PG8_BAR; PG8_MMA(0, 0, At, B0); PG8_MMA(0, 1, At, B1); PG8_BAR; PG8_SCHED;
;             PG8_LDA(At, 0, 1); PG8_STAGE(PG8_SB(0, 0), b2, voffB); PG8_STAGE(PG8_SB(0, 1), b2 + hstepB, voffB); PG8_STAGE(PG8_SA(0, 0), a2, voffA);
.LBB0_217:
	ds_read_b128 v[128:131], v173
	ds_read_b128 v[132:135], v173 offset:1024
	ds_read_b128 v[136:139], v173 offset:2048
	ds_read_b128 v[140:143], v173 offset:3072
	ds_read_b128 v[162:165], v174
	ds_read_b128 v[166:169], v174 offset:1024
	ds_read_b128 v[180:183], v174 offset:2048
	ds_read_b128 v[184:187], v174 offset:3072
	s_add_u32 s38, s36, 0xfffc0080
	s_addc_u32 s39, s37, -1
	s_cmp_eq_u32 s89, 12
	s_cselect_b32 s41, s27, s39
	s_cselect_b32 s40, s35, s38
	s_cselect_b32 s39, s25, s88
	s_cselect_b32 s38, s86, s87
	v_lshl_add_u64 v[170:171], s[36:37], 0, v[154:155]
	s_add_i32 m0, s56, 0xc000
	ds_read_b128 v[188:191], v175
	ds_read_b128 v[192:195], v175 offset:1024
	ds_read_b128 v[196:199], v175 offset:2048
	ds_read_b128 v[200:203], v175 offset:3072
	ds_read_b128 v[204:207], v175 offset:4096
	ds_read_b128 v[208:211], v175 offset:5120
	ds_read_b128 v[212:215], v175 offset:6144
	ds_read_b128 v[216:219], v175 offset:7168
	global_load_lds_dwordx4 v[170:171], off
	v_lshl_add_u64 v[170:171], s[36:37], 0, v[156:157]
	s_add_i32 m0, s56, 0xe000
	s_nop 0
	global_load_lds_dwordx4 v[170:171], off
	s_waitcnt vmcnt(8)
	s_waitcnt lgkmcnt(0)
	s_barrier
	s_setprio 1
	s_waitcnt lgkmcnt(0)
	v_mfma_f32_16x16x32_bf16 v[124:127], v[128:131], v[188:191], v[124:127]
	v_mfma_f32_16x16x32_bf16 v[120:123], v[136:139], v[188:191], v[120:123]
	v_mfma_f32_16x16x32_bf16 v[108:111], v[128:131], v[196:199], v[108:111]
	v_mfma_f32_16x16x32_bf16 v[104:107], v[136:139], v[196:199], v[104:107]
	v_mfma_f32_16x16x32_bf16 v[92:95], v[128:131], v[204:207], v[92:95]
	v_mfma_f32_16x16x32_bf16 v[88:91], v[136:139], v[204:207], v[88:91]
	v_mfma_f32_16x16x32_bf16 v[76:79], v[128:131], v[212:215], v[76:79]
	v_mfma_f32_16x16x32_bf16 v[72:75], v[136:139], v[212:215], v[72:75]
	v_mfma_f32_16x16x32_bf16 v[124:127], v[132:135], v[192:195], v[124:127]
	v_mfma_f32_16x16x32_bf16 v[120:123], v[140:143], v[192:195], v[120:123]
	v_mfma_f32_16x16x32_bf16 v[108:111], v[132:135], v[200:203], v[108:111]
	v_mfma_f32_16x16x32_bf16 v[104:107], v[140:143], v[200:203], v[104:107]
	v_mfma_f32_16x16x32_bf16 v[92:95], v[132:135], v[208:211], v[92:95]
	v_mfma_f32_16x16x32_bf16 v[88:91], v[140:143], v[208:211], v[88:91]
	v_mfma_f32_16x16x32_bf16 v[76:79], v[132:135], v[216:219], v[76:79]
	v_mfma_f32_16x16x32_bf16 v[72:75], v[140:143], v[216:219], v[72:75]
	s_setprio 0
	s_setprio 1
	v_mfma_f32_16x16x32_bf16 v[116:119], v[162:165], v[188:191], v[116:119]
	v_mfma_f32_16x16x32_bf16 v[112:115], v[180:183], v[188:191], v[112:115]
	v_mfma_f32_16x16x32_bf16 v[100:103], v[162:165], v[196:199], v[100:103]
	v_mfma_f32_16x16x32_bf16 v[96:99], v[180:183], v[196:199], v[96:99]
	v_mfma_f32_16x16x32_bf16 v[84:87], v[162:165], v[204:207], v[84:87]
	v_mfma_f32_16x16x32_bf16 v[80:83], v[180:183], v[204:207], v[80:83]
	v_mfma_f32_16x16x32_bf16 v[68:71], v[162:165], v[212:215], v[68:71]
	v_mfma_f32_16x16x32_bf16 v[64:67], v[180:183], v[212:215], v[64:67]
	v_mfma_f32_16x16x32_bf16 v[116:119], v[166:169], v[192:195], v[116:119]
	v_mfma_f32_16x16x32_bf16 v[112:115], v[184:187], v[192:195], v[112:115]
	v_mfma_f32_16x16x32_bf16 v[100:103], v[166:169], v[200:203], v[100:103]
	v_mfma_f32_16x16x32_bf16 v[96:99], v[184:187], v[200:203], v[96:99]
	v_mfma_f32_16x16x32_bf16 v[84:87], v[166:169], v[208:211], v[84:87]
	v_mfma_f32_16x16x32_bf16 v[80:83], v[184:187], v[208:211], v[80:83]
	v_mfma_f32_16x16x32_bf16 v[68:71], v[166:169], v[216:219], v[68:71]
	v_mfma_f32_16x16x32_bf16 v[64:67], v[184:187], v[216:219], v[64:67]
	s_setprio 0
	s_barrier
	s_add_i32 s90, s65, s51
	v_lshl_add_u64 v[170:171], s[38:39], 0, v[144:145]
	s_mov_b32 m0, s90
	ds_read_b128 v[188:191], v175 offset:16384
	ds_read_b128 v[192:195], v175 offset:17408
	ds_read_b128 v[196:199], v175 offset:18432
	ds_read_b128 v[200:203], v175 offset:19456
	ds_read_b128 v[204:207], v175 offset:20480
	ds_read_b128 v[208:211], v175 offset:21504
	ds_read_b128 v[212:215], v175 offset:22528
	ds_read_b128 v[216:219], v175 offset:23552
	global_load_lds_dwordx4 v[170:171], off
	s_add_i32 m0, s90, 0x2000
	s_add_u32 s90, s38, 0x4000
	v_lshl_add_u64 v[170:171], s[38:39], 0, v[148:149]
	s_addc_u32 s91, s39, 0
	s_add_i32 s92, s66, s51
	global_load_lds_dwordx4 v[170:171], off
	v_lshl_add_u64 v[170:171], s[90:91], 0, v[144:145]
	s_mov_b32 m0, s92
	v_lshl_add_u64 v[222:223], s[40:41], 0, v[150:151]
	global_load_lds_dwordx4 v[170:171], off
	v_lshl_add_u64 v[170:171], s[90:91], 0, v[148:149]
	s_add_i32 m0, s92, 0x2000
	s_nop 0
	global_load_lds_dwordx4 v[170:171], off
	v_lshl_add_u64 v[170:171], s[40:41], 0, v[146:147]
	s_mov_b32 m0, s56
	s_nop 0
	global_load_lds_dwordx4 v[170:171], off
	s_mov_b32 m0, s57
	s_nop 0
	global_load_lds_dwordx4 v[222:223], off
	s_waitcnt vmcnt(8)
	s_waitcnt lgkmcnt(0)
	s_barrier
; #define PG8_STAGE(bufoff, gbase, voff) do { _Pragma("unroll") for (int _i = 0; _i < 2; ++_i) \
;         __builtin_amdgcn_global_load_lds((const unsigned*)((const char*)(gbase) + (voff)[_i]), (LAS unsigned*)(lds + (bufoff) + ldsw + _i * 8192), 16, 0, 0); } while (0)
; #define PG8_LDA(dst, b, h) do { _Pragma("unroll") for (int m = 0; m < 4; ++m) _Pragma("unroll") for (int k = 0; k < 2; ++k) dst[m][k] = *(const LAS bf16x8*)(lds + PG8_SA(b, h) + aoff + m * 2048 + k * 1024); } while (0)
; #define PG8_LDB(dst, b, h) do { _Pragma("unroll") for (int n = 0; n < 2; ++n) _Pragma("unroll") for (int k = 0; k < 2; ++k) dst[n][k] = *(const LAS bf16x8*)(lds + PG8_SB(b, h) + boff + n * 2048 + k * 1024); } while (0)
; #define PG8_MMA(ai, bj, At, Bt) do { __builtin_amdgcn_s_setprio(1); _Pragma("unroll") for (int m = 0; m < 4; ++m) _Pragma("unroll") for (int n = 0; n < 2; ++n) _Pragma("unroll") for (int k = 0; k < 2; ++k) \
;         acc[ai][bj][m][n] = __builtin_amdgcn_mfma_f32_16x16x32_bf16(Bt[n][k], At[m][k], acc[ai][bj][m][n], 0, 0, 0); __builtin_amdgcn_s_setprio(0); } while (0)
; #define PG8_WAIT_V(n) asm volatile("s_waitcnt vmcnt(" #n ")" ::: "memory")
; #define PG8_WAIT_L(n) asm volatile("s_waitcnt lgkmcnt(" #n ")" ::: "memory")
; #define PG8_BAR __builtin_amdgcn_s_barrier()
; #define PG8_SCHED __builtin_amdgcn_sched_barrier(0)
; template <class Epi, bool HALO>
; __device__ __forceinline__ void gemm_phase(LAS unsigned char* lds, const Gemm g, const StaticOrder& S, const Epi& E) {
;     ...
;             PG8_WAIT_V(8); PG8_WAIT_L(0); PG8_BAR; PG8_MMA(1, 0, At, B0); PG8_MMA(1, 1, At, B1); PG8_BAR; PG8_SCHED;
;             PG8_LDB(B0, 1, 0); PG8_LDB(B1, 1, 1); PG8_SCHED; PG8_LDA(At, 1, 0); PG8_STAGE(PG8_SA(0, 1), a2 + hstepA, voffA);
;             PG8_WAIT_V(8); PG8_WAIT_L(0); PG8_BAR; PG8_MMA(0, 0, At, B0); PG8_MMA(0, 1, At, B1); PG8_BAR; PG8_SCHED;
	s_setprio 1
	s_waitcnt lgkmcnt(0)
	v_mfma_f32_16x16x32_bf16 v[60:63], v[128:131], v[188:191], v[60:63]
	v_mfma_f32_16x16x32_bf16 v[56:59], v[136:139], v[188:191], v[56:59]
	v_mfma_f32_16x16x32_bf16 v[44:47], v[128:131], v[196:199], v[44:47]
	v_mfma_f32_16x16x32_bf16 v[40:43], v[136:139], v[196:199], v[40:43]
	v_mfma_f32_16x16x32_bf16 v[28:31], v[128:131], v[204:207], v[28:31]
	v_mfma_f32_16x16x32_bf16 v[24:27], v[136:139], v[204:207], v[24:27]
	v_mfma_f32_16x16x32_bf16 v[12:15], v[128:131], v[212:215], v[12:15]
	v_mfma_f32_16x16x32_bf16 v[8:11], v[136:139], v[212:215], v[8:11]
	v_mfma_f32_16x16x32_bf16 v[60:63], v[132:135], v[192:195], v[60:63]
	v_mfma_f32_16x16x32_bf16 v[56:59], v[140:143], v[192:195], v[56:59]
	v_mfma_f32_16x16x32_bf16 v[44:47], v[132:135], v[200:203], v[44:47]
	v_mfma_f32_16x16x32_bf16 v[40:43], v[140:143], v[200:203], v[40:43]
	v_mfma_f32_16x16x32_bf16 v[28:31], v[132:135], v[208:211], v[28:31]
	v_mfma_f32_16x16x32_bf16 v[24:27], v[140:143], v[208:211], v[24:27]
	v_mfma_f32_16x16x32_bf16 v[12:15], v[132:135], v[216:219], v[12:15]
	v_mfma_f32_16x16x32_bf16 v[8:11], v[140:143], v[216:219], v[8:11]
	s_setprio 0
	s_setprio 1
	v_mfma_f32_16x16x32_bf16 v[52:55], v[162:165], v[188:191], v[52:55]
	v_mfma_f32_16x16x32_bf16 v[48:51], v[180:183], v[188:191], v[48:51]
	v_mfma_f32_16x16x32_bf16 v[36:39], v[162:165], v[196:199], v[36:39]
	v_mfma_f32_16x16x32_bf16 v[32:35], v[180:183], v[196:199], v[32:35]
	v_mfma_f32_16x16x32_bf16 v[20:23], v[162:165], v[204:207], v[20:23]
	v_mfma_f32_16x16x32_bf16 v[16:19], v[180:183], v[204:207], v[16:19]
	v_mfma_f32_16x16x32_bf16 v[4:7], v[162:165], v[212:215], v[4:7]
	v_mfma_f32_16x16x32_bf16 v[0:3], v[180:183], v[212:215], v[0:3]
	v_mfma_f32_16x16x32_bf16 v[52:55], v[166:169], v[192:195], v[52:55]
	v_mfma_f32_16x16x32_bf16 v[48:51], v[184:187], v[192:195], v[48:51]
	v_mfma_f32_16x16x32_bf16 v[36:39], v[166:169], v[200:203], v[36:39]
	v_mfma_f32_16x16x32_bf16 v[32:35], v[184:187], v[200:203], v[32:35]
	v_mfma_f32_16x16x32_bf16 v[20:23], v[166:169], v[208:211], v[20:23]
	v_mfma_f32_16x16x32_bf16 v[16:19], v[184:187], v[208:211], v[16:19]
	v_mfma_f32_16x16x32_bf16 v[4:7], v[166:169], v[216:219], v[4:7]
	v_mfma_f32_16x16x32_bf16 v[0:3], v[184:187], v[216:219], v[0:3]
	s_setprio 0
	s_barrier
	s_add_i32 s90, 0, 0x18000
	s_add_i32 s91, 0, 0x1c000
	v_add_u32_e32 v140, s90, v172
	v_add_u32_e32 v152, s91, v172
	ds_read_b128 v[128:131], v140
	ds_read_b128 v[132:135], v140 offset:1024
	ds_read_b128 v[136:139], v140 offset:2048
	ds_read_b128 v[140:143], v140 offset:3072
	ds_read_b128 v[162:165], v152
	ds_read_b128 v[166:169], v152 offset:1024
	ds_read_b128 v[180:183], v152 offset:2048
	ds_read_b128 v[184:187], v152 offset:3072
	s_add_u32 s40, s40, 0x40000
	s_addc_u32 s41, s41, 0
	s_mov_b32 m0, s58
	v_lshl_add_u64 v[224:225], s[40:41], 0, v[146:147]
	ds_read_b128 v[188:191], v175 offset:32768
	ds_read_b128 v[192:195], v175 offset:33792
	ds_read_b128 v[196:199], v175 offset:34816
	ds_read_b128 v[200:203], v175 offset:35840
	ds_read_b128 v[204:207], v175 offset:36864
	ds_read_b128 v[208:211], v175 offset:37888
	ds_read_b128 v[212:215], v175 offset:38912
	ds_read_b128 v[216:219], v175 offset:39936
	global_load_lds_dwordx4 v[224:225], off
	v_lshl_add_u64 v[224:225], s[40:41], 0, v[150:151]
	s_mov_b32 m0, s59
	s_nop 0
	global_load_lds_dwordx4 v[224:225], off
	s_waitcnt vmcnt(8)
	s_waitcnt lgkmcnt(0)
	s_barrier
	s_setprio 1
	s_waitcnt lgkmcnt(0)
	v_mfma_f32_16x16x32_bf16 v[124:127], v[128:131], v[188:191], v[124:127]
	v_mfma_f32_16x16x32_bf16 v[120:123], v[136:139], v[188:191], v[120:123]
	v_mfma_f32_16x16x32_bf16 v[108:111], v[128:131], v[196:199], v[108:111]
	v_mfma_f32_16x16x32_bf16 v[104:107], v[136:139], v[196:199], v[104:107]
	v_mfma_f32_16x16x32_bf16 v[92:95], v[128:131], v[204:207], v[92:95]
	v_mfma_f32_16x16x32_bf16 v[88:91], v[136:139], v[204:207], v[88:91]
	v_mfma_f32_16x16x32_bf16 v[76:79], v[128:131], v[212:215], v[76:79]
	v_mfma_f32_16x16x32_bf16 v[72:75], v[136:139], v[212:215], v[72:75]
	v_mfma_f32_16x16x32_bf16 v[124:127], v[132:135], v[192:195], v[124:127]
	v_mfma_f32_16x16x32_bf16 v[120:123], v[140:143], v[192:195], v[120:123]
	v_mfma_f32_16x16x32_bf16 v[108:111], v[132:135], v[200:203], v[108:111]
	v_mfma_f32_16x16x32_bf16 v[104:107], v[140:143], v[200:203], v[104:107]
	v_mfma_f32_16x16x32_bf16 v[92:95], v[132:135], v[208:211], v[92:95]
	v_mfma_f32_16x16x32_bf16 v[88:91], v[140:143], v[208:211], v[88:91]
	v_mfma_f32_16x16x32_bf16 v[76:79], v[132:135], v[216:219], v[76:79]
	v_mfma_f32_16x16x32_bf16 v[72:75], v[140:143], v[216:219], v[72:75]
	s_setprio 0
	s_setprio 1
	v_mfma_f32_16x16x32_bf16 v[116:119], v[162:165], v[188:191], v[116:119]
	v_mfma_f32_16x16x32_bf16 v[112:115], v[180:183], v[188:191], v[112:115]
	v_mfma_f32_16x16x32_bf16 v[100:103], v[162:165], v[196:199], v[100:103]
	v_mfma_f32_16x16x32_bf16 v[96:99], v[180:183], v[196:199], v[96:99]
	v_mfma_f32_16x16x32_bf16 v[84:87], v[162:165], v[204:207], v[84:87]
	v_mfma_f32_16x16x32_bf16 v[80:83], v[180:183], v[204:207], v[80:83]
	v_mfma_f32_16x16x32_bf16 v[68:71], v[162:165], v[212:215], v[68:71]
	v_mfma_f32_16x16x32_bf16 v[64:67], v[180:183], v[212:215], v[64:67]
	v_mfma_f32_16x16x32_bf16 v[116:119], v[166:169], v[192:195], v[116:119]
	v_mfma_f32_16x16x32_bf16 v[112:115], v[184:187], v[192:195], v[112:115]
	v_mfma_f32_16x16x32_bf16 v[100:103], v[166:169], v[200:203], v[100:103]
	v_mfma_f32_16x16x32_bf16 v[96:99], v[184:187], v[200:203], v[96:99]
	v_mfma_f32_16x16x32_bf16 v[84:87], v[166:169], v[208:211], v[84:87]
	v_mfma_f32_16x16x32_bf16 v[80:83], v[184:187], v[208:211], v[80:83]
	v_mfma_f32_16x16x32_bf16 v[68:71], v[166:169], v[216:219], v[68:71]
	v_mfma_f32_16x16x32_bf16 v[64:67], v[184:187], v[216:219], v[64:67]
	s_setprio 0
	s_barrier
; #define PG8_STAGE(bufoff, gbase, voff) do { _Pragma("unroll") for (int _i = 0; _i < 2; ++_i) \
;         __builtin_amdgcn_global_load_lds((const unsigned*)((const char*)(gbase) + (voff)[_i]), (LAS unsigned*)(lds + (bufoff) + ldsw + _i * 8192), 16, 0, 0); } while (0)
; #define PG8_LDA(dst, b, h) do { _Pragma("unroll") for (int m = 0; m < 4; ++m) _Pragma("unroll") for (int k = 0; k < 2; ++k) dst[m][k] = *(const LAS bf16x8*)(lds + PG8_SA(b, h) + aoff + m * 2048 + k * 1024); } while (0)
; #define PG8_MMA(ai, bj, At, Bt) do { __builtin_amdgcn_s_setprio(1); _Pragma("unroll") for (int m = 0; m < 4; ++m) _Pragma("unroll") for (int n = 0; n < 2; ++n) _Pragma("unroll") for (int k = 0; k < 2; ++k) \
;         acc[ai][bj][m][n] = __builtin_amdgcn_mfma_f32_16x16x32_bf16(Bt[n][k], At[m][k], acc[ai][bj][m][n], 0, 0, 0); __builtin_amdgcn_s_setprio(0); } while (0)
; #define PG8_WAIT_V(n) asm volatile("s_waitcnt vmcnt(" #n ")" ::: "memory")
; #define PG8_WAIT_L(n) asm volatile("s_waitcnt lgkmcnt(" #n ")" ::: "memory")
; #define PG8_BAR __builtin_amdgcn_s_barrier()
; #define PG8_SCHED __builtin_amdgcn_sched_barrier(0)
; template <class Epi, bool HALO>
; __device__ __forceinline__ void gemm_phase(LAS unsigned char* lds, const Gemm g, const StaticOrder& S, const Epi& E) {
;     ...
;             PG8_LDA(At, 1, 1); PG8_STAGE(PG8_SB(1, 0), b3, voffB); PG8_STAGE(PG8_SB(1, 1), b3 + hstepB, voffB); PG8_STAGE(PG8_SA(1, 0), a3, voffA);
;             PG8_WAIT_V(8); PG8_WAIT_L(0); PG8_BAR; PG8_MMA(1, 0, At, B0); PG8_MMA(1, 1, At, B1); PG8_BAR; PG8_SCHED;
;         }
;         if (wr == 0) PG8_BAR;
	s_add_u32 s40, s38, 0x8000
	s_addc_u32 s41, s39, 0
	s_add_i32 s90, s90, s51
	v_lshl_add_u64 v[224:225], s[40:41], 0, v[144:145]
	s_mov_b32 m0, s90
	ds_read_b128 v[188:191], v175 offset:49152
	ds_read_b128 v[192:195], v175 offset:50176
	ds_read_b128 v[196:199], v175 offset:51200
	ds_read_b128 v[200:203], v175 offset:52224
	ds_read_b128 v[204:207], v175 offset:53248
	ds_read_b128 v[208:211], v175 offset:54272
	ds_read_b128 v[212:215], v175 offset:55296
	ds_read_b128 v[216:219], v175 offset:56320
	global_load_lds_dwordx4 v[224:225], off
	s_add_i32 m0, s90, 0x2000
	s_add_u32 s38, s38, 0xc000
	v_lshl_add_u64 v[224:225], s[40:41], 0, v[148:149]
	s_addc_u32 s39, s39, 0
	s_add_i32 s40, s91, s51
	global_load_lds_dwordx4 v[224:225], off
	v_lshl_add_u64 v[224:225], s[38:39], 0, v[144:145]
	s_mov_b32 m0, s40
	v_lshl_add_u64 v[170:171], v[170:171], 0, s[18:19]
	global_load_lds_dwordx4 v[224:225], off
	v_lshl_add_u64 v[224:225], s[38:39], 0, v[148:149]
	s_add_i32 m0, s40, 0x2000
	s_nop 0
	global_load_lds_dwordx4 v[224:225], off
	s_mov_b32 m0, s63
	s_nop 0
	global_load_lds_dwordx4 v[170:171], off
	v_lshl_add_u64 v[170:171], v[222:223], 0, s[18:19]
	s_mov_b32 m0, s64
	s_nop 0
	global_load_lds_dwordx4 v[170:171], off
	s_waitcnt vmcnt(8)
	s_waitcnt lgkmcnt(0)
	s_barrier
	s_setprio 1
	s_waitcnt lgkmcnt(0)
	v_mfma_f32_16x16x32_bf16 v[60:63], v[128:131], v[188:191], v[60:63]
	v_mfma_f32_16x16x32_bf16 v[56:59], v[136:139], v[188:191], v[56:59]
	v_mfma_f32_16x16x32_bf16 v[44:47], v[128:131], v[196:199], v[44:47]
	v_mfma_f32_16x16x32_bf16 v[40:43], v[136:139], v[196:199], v[40:43]
	v_mfma_f32_16x16x32_bf16 v[28:31], v[128:131], v[204:207], v[28:31]
	v_mfma_f32_16x16x32_bf16 v[24:27], v[136:139], v[204:207], v[24:27]
	v_mfma_f32_16x16x32_bf16 v[12:15], v[128:131], v[212:215], v[12:15]
	v_mfma_f32_16x16x32_bf16 v[8:11], v[136:139], v[212:215], v[8:11]
	v_mfma_f32_16x16x32_bf16 v[60:63], v[132:135], v[192:195], v[60:63]
	v_mfma_f32_16x16x32_bf16 v[56:59], v[140:143], v[192:195], v[56:59]
	v_mfma_f32_16x16x32_bf16 v[44:47], v[132:135], v[200:203], v[44:47]
	v_mfma_f32_16x16x32_bf16 v[40:43], v[140:143], v[200:203], v[40:43]
	v_mfma_f32_16x16x32_bf16 v[28:31], v[132:135], v[208:211], v[28:31]
	v_mfma_f32_16x16x32_bf16 v[24:27], v[140:143], v[208:211], v[24:27]
	v_mfma_f32_16x16x32_bf16 v[12:15], v[132:135], v[216:219], v[12:15]
	v_mfma_f32_16x16x32_bf16 v[8:11], v[140:143], v[216:219], v[8:11]
	s_setprio 0
	s_setprio 1
	v_mfma_f32_16x16x32_bf16 v[52:55], v[162:165], v[188:191], v[52:55]
	v_mfma_f32_16x16x32_bf16 v[48:51], v[180:183], v[188:191], v[48:51]
	v_mfma_f32_16x16x32_bf16 v[36:39], v[162:165], v[196:199], v[36:39]
	v_mfma_f32_16x16x32_bf16 v[32:35], v[180:183], v[196:199], v[32:35]
	v_mfma_f32_16x16x32_bf16 v[20:23], v[162:165], v[204:207], v[20:23]
	v_mfma_f32_16x16x32_bf16 v[16:19], v[180:183], v[204:207], v[16:19]
	v_mfma_f32_16x16x32_bf16 v[4:7], v[162:165], v[212:215], v[4:7]
	v_mfma_f32_16x16x32_bf16 v[0:3], v[180:183], v[212:215], v[0:3]
	v_mfma_f32_16x16x32_bf16 v[52:55], v[166:169], v[192:195], v[52:55]
	v_mfma_f32_16x16x32_bf16 v[48:51], v[184:187], v[192:195], v[48:51]
	v_mfma_f32_16x16x32_bf16 v[36:39], v[166:169], v[200:203], v[36:39]
	v_mfma_f32_16x16x32_bf16 v[32:35], v[184:187], v[200:203], v[32:35]
	v_mfma_f32_16x16x32_bf16 v[20:23], v[166:169], v[208:211], v[20:23]
	v_mfma_f32_16x16x32_bf16 v[16:19], v[184:187], v[208:211], v[16:19]
	s_add_i32 s89, s89, 2
	s_add_u32 s87, s87, 0x10000
	s_addc_u32 s88, s88, 0
	s_add_u32 s36, s36, 0x100
	s_addc_u32 s37, s37, 0
	s_cmp_gt_u32 s89, 13
	v_mfma_f32_16x16x32_bf16 v[4:7], v[166:169], v[216:219], v[4:7]
	v_mfma_f32_16x16x32_bf16 v[0:3], v[184:187], v[216:219], v[0:3]
	s_setprio 0
	s_barrier
	s_cbranch_scc0 .LBB0_217
	s_and_b64 vcc, exec, s[20:21]
	s_cbranch_vccz .LBB0_220
	s_barrier

; #define PG8_STAGE(bufoff, gbase, voff) do { _Pragma("unroll") for (int _i = 0; _i < 2; ++_i) \
;         __builtin_amdgcn_global_load_lds((const unsigned*)((const char*)(gbase) + (voff)[_i]), (LAS unsigned*)(lds + (bufoff) + ldsw + _i * 8192), 16, 0, 0); } while (0)
; #define PG8_LDA(dst, b, h) do { _Pragma("unroll") for (int m = 0; m < 4; ++m) _Pragma("unroll") for (int k = 0; k < 2; ++k) dst[m][k] = *(const LAS bf16x8*)(lds + PG8_SA(b, h) + aoff + m * 2048 + k * 1024); } while (0)
; #define PG8_LDB(dst, b, h) do { _Pragma("unroll") for (int n = 0; n < 2; ++n) _Pragma("unroll") for (int k = 0; k < 2; ++k) dst[n][k] = *(const LAS bf16x8*)(lds + PG8_SB(b, h) + boff + n * 2048 + k * 1024); } while (0)
; #define PG8_MMA(ai, bj, At, Bt) do { __builtin_amdgcn_s_setprio(1); _Pragma("unroll") for (int m = 0; m < 4; ++m) _Pragma("unroll") for (int n = 0; n < 2; ++n) _Pragma("unroll") for (int k = 0; k < 2; ++k) \
;         acc[ai][bj][m][n] = __builtin_amdgcn_mfma_f32_16x16x32_bf16(Bt[n][k], At[m][k], acc[ai][bj][m][n], 0, 0, 0); __builtin_amdgcn_s_setprio(0); } while (0)
; #define PG8_WAIT_V(n) asm volatile("s_waitcnt vmcnt(" #n ")" ::: "memory")
; #define PG8_WAIT_L(n) asm volatile("s_waitcnt lgkmcnt(" #n ")" ::: "memory")
; #define PG8_BAR __builtin_amdgcn_s_barrier()
; #define PG8_SCHED __builtin_amdgcn_sched_barrier(0)
; template <class Epi, bool HALO>
; __device__ __forceinline__ void gemm_phase(LAS unsigned char* lds, const Gemm g, const StaticOrder& S, const Epi& E) {
;     ...
;         for (int t = 0; t < nt; t += 2) {
;             const bool last = (t == nt - 2);
;             const char* a1 = cA + (size_t)(t + 1) * kstep;
;             const char* a2 = last ? nA : cA + (size_t)(t + 2) * kstep; const char* b2 = last ? nB : cB + (size_t)(t + 2) * kstepB;
;             const char* a3 = a2 + kstep; const char* b3 = b2 + kstepB;
;             PG8_LDB(B0, 0, 0); PG8_LDB(B1, 0, 1); PG8_SCHED; PG8_LDA(At, 0, 0); PG8_STAGE(PG8_SA(1, 1), a1 + hstepA, voffA);
;             PG8_WAIT_V(8); PG8_WAIT_L(0); PG8_BAR; PG8_MMA(0, 0, At, B0); PG8_MMA(0, 1, At, B1); PG8_BAR; PG8_SCHED;
;             PG8_LDA(At, 0, 1); PG8_STAGE(PG8_SB(0, 0), b2, voffB); PG8_STAGE(PG8_SB(0, 1), b2 + hstepB, voffB); PG8_STAGE(PG8_SA(0, 0), a2, voffA);
.LBB0_499:
	ds_read_b128 v[154:157], v149
	ds_read_b128 v[158:161], v149 offset:1024
	ds_read_b128 v[162:165], v149 offset:2048
	ds_read_b128 v[166:169], v149 offset:3072
	ds_read_b128 v[170:173], v150
	ds_read_b128 v[174:177], v150 offset:1024
	ds_read_b128 v[178:181], v150 offset:2048
	ds_read_b128 v[182:185], v150 offset:3072
	s_add_u32 s36, s34, 0xfffc0080
	s_addc_u32 s37, s35, -1
	s_cmp_eq_u32 s66, 12
	s_cselect_b32 s39, s23, s37
	s_cselect_b32 s38, s29, s36
	s_cselect_b32 s37, s21, s65
	s_cselect_b32 s36, s31, s64
	v_lshl_add_u64 v[146:147], s[34:35], 0, v[138:139]
	s_add_i32 m0, s52, 0xc000
	ds_read_b128 v[186:189], v151
	ds_read_b128 v[190:193], v151 offset:1024
	ds_read_b128 v[194:197], v151 offset:2048
	ds_read_b128 v[198:201], v151 offset:3072
	ds_read_b128 v[202:205], v151 offset:4096
	ds_read_b128 v[206:209], v151 offset:5120
	ds_read_b128 v[210:213], v151 offset:6144
	ds_read_b128 v[214:217], v151 offset:7168
	global_load_lds_dwordx4 v[146:147], off
	v_lshl_add_u64 v[146:147], s[34:35], 0, v[140:141]
	s_add_i32 m0, s52, 0xe000
	s_nop 0
	global_load_lds_dwordx4 v[146:147], off
	s_waitcnt vmcnt(8)
	s_waitcnt lgkmcnt(0)
	s_barrier
	s_setprio 1
	s_waitcnt lgkmcnt(0)
	v_mfma_f32_16x16x32_bf16 v[124:127], v[154:157], v[186:189], v[124:127]
	v_mfma_f32_16x16x32_bf16 v[120:123], v[162:165], v[186:189], v[120:123]
	v_mfma_f32_16x16x32_bf16 v[108:111], v[154:157], v[194:197], v[108:111]
	v_mfma_f32_16x16x32_bf16 v[104:107], v[162:165], v[194:197], v[104:107]
	v_mfma_f32_16x16x32_bf16 v[92:95], v[154:157], v[202:205], v[92:95]
	v_mfma_f32_16x16x32_bf16 v[88:91], v[162:165], v[202:205], v[88:91]
	v_mfma_f32_16x16x32_bf16 v[76:79], v[154:157], v[210:213], v[76:79]
	v_mfma_f32_16x16x32_bf16 v[72:75], v[162:165], v[210:213], v[72:75]
	v_mfma_f32_16x16x32_bf16 v[124:127], v[158:161], v[190:193], v[124:127]
	v_mfma_f32_16x16x32_bf16 v[120:123], v[166:169], v[190:193], v[120:123]
	v_mfma_f32_16x16x32_bf16 v[108:111], v[158:161], v[198:201], v[108:111]
	v_mfma_f32_16x16x32_bf16 v[104:107], v[166:169], v[198:201], v[104:107]
	v_mfma_f32_16x16x32_bf16 v[92:95], v[158:161], v[206:209], v[92:95]
	v_mfma_f32_16x16x32_bf16 v[88:91], v[166:169], v[206:209], v[88:91]
	v_mfma_f32_16x16x32_bf16 v[76:79], v[158:161], v[214:217], v[76:79]
	v_mfma_f32_16x16x32_bf16 v[72:75], v[166:169], v[214:217], v[72:75]
	s_setprio 0
	s_setprio 1
	v_mfma_f32_16x16x32_bf16 v[116:119], v[170:173], v[186:189], v[116:119]
	v_mfma_f32_16x16x32_bf16 v[112:115], v[178:181], v[186:189], v[112:115]
	v_mfma_f32_16x16x32_bf16 v[100:103], v[170:173], v[194:197], v[100:103]
	v_mfma_f32_16x16x32_bf16 v[96:99], v[178:181], v[194:197], v[96:99]
	v_mfma_f32_16x16x32_bf16 v[84:87], v[170:173], v[202:205], v[84:87]
	v_mfma_f32_16x16x32_bf16 v[80:83], v[178:181], v[202:205], v[80:83]
	v_mfma_f32_16x16x32_bf16 v[68:71], v[170:173], v[210:213], v[68:71]
	v_mfma_f32_16x16x32_bf16 v[64:67], v[178:181], v[210:213], v[64:67]
	v_mfma_f32_16x16x32_bf16 v[116:119], v[174:177], v[190:193], v[116:119]
	v_mfma_f32_16x16x32_bf16 v[112:115], v[182:185], v[190:193], v[112:115]
	v_mfma_f32_16x16x32_bf16 v[100:103], v[174:177], v[198:201], v[100:103]
	v_mfma_f32_16x16x32_bf16 v[96:99], v[182:185], v[198:201], v[96:99]
	v_mfma_f32_16x16x32_bf16 v[84:87], v[174:177], v[206:209], v[84:87]
	v_mfma_f32_16x16x32_bf16 v[80:83], v[182:185], v[206:209], v[80:83]
	v_mfma_f32_16x16x32_bf16 v[68:71], v[174:177], v[214:217], v[68:71]
	v_mfma_f32_16x16x32_bf16 v[64:67], v[182:185], v[214:217], v[64:67]
	s_setprio 0
	s_barrier
	s_add_i32 s67, s62, s51
	v_lshl_add_u64 v[146:147], s[36:37], 0, v[128:129]
	s_mov_b32 m0, s67
	ds_read_b128 v[186:189], v151 offset:16384
	ds_read_b128 v[190:193], v151 offset:17408
	ds_read_b128 v[194:197], v151 offset:18432
	ds_read_b128 v[198:201], v151 offset:19456
	ds_read_b128 v[202:205], v151 offset:20480
	ds_read_b128 v[206:209], v151 offset:21504
	ds_read_b128 v[210:213], v151 offset:22528
	ds_read_b128 v[214:217], v151 offset:23552
	global_load_lds_dwordx4 v[146:147], off
	s_add_i32 m0, s67, 0x2000
	s_add_u32 s68, s36, 0x4000
	v_lshl_add_u64 v[146:147], s[36:37], 0, v[132:133]
	s_addc_u32 s69, s37, 0
	s_add_i32 s67, s63, s51
	global_load_lds_dwordx4 v[146:147], off
	v_lshl_add_u64 v[146:147], s[68:69], 0, v[128:129]
	s_mov_b32 m0, s67
	v_lshl_add_u64 v[218:219], s[38:39], 0, v[134:135]
	global_load_lds_dwordx4 v[146:147], off
	v_lshl_add_u64 v[146:147], s[68:69], 0, v[132:133]
	s_add_i32 m0, s67, 0x2000
	s_nop 0
	global_load_lds_dwordx4 v[146:147], off
	v_lshl_add_u64 v[146:147], s[38:39], 0, v[130:131]
	s_mov_b32 m0, s52
	s_nop 0
	global_load_lds_dwordx4 v[146:147], off
	s_mov_b32 m0, s53
	s_nop 0
	global_load_lds_dwordx4 v[218:219], off
	s_waitcnt vmcnt(8)
	s_waitcnt lgkmcnt(0)
	s_barrier
; #define PG8_STAGE(bufoff, gbase, voff) do { _Pragma("unroll") for (int _i = 0; _i < 2; ++_i) \
;         __builtin_amdgcn_global_load_lds((const unsigned*)((const char*)(gbase) + (voff)[_i]), (LAS unsigned*)(lds + (bufoff) + ldsw + _i * 8192), 16, 0, 0); } while (0)
; #define PG8_LDA(dst, b, h) do { _Pragma("unroll") for (int m = 0; m < 4; ++m) _Pragma("unroll") for (int k = 0; k < 2; ++k) dst[m][k] = *(const LAS bf16x8*)(lds + PG8_SA(b, h) + aoff + m * 2048 + k * 1024); } while (0)
; #define PG8_LDB(dst, b, h) do { _Pragma("unroll") for (int n = 0; n < 2; ++n) _Pragma("unroll") for (int k = 0; k < 2; ++k) dst[n][k] = *(const LAS bf16x8*)(lds + PG8_SB(b, h) + boff + n * 2048 + k * 1024); } while (0)
; #define PG8_MMA(ai, bj, At, Bt) do { __builtin_amdgcn_s_setprio(1); _Pragma("unroll") for (int m = 0; m < 4; ++m) _Pragma("unroll") for (int n = 0; n < 2; ++n) _Pragma("unroll") for (int k = 0; k < 2; ++k) \
;         acc[ai][bj][m][n] = __builtin_amdgcn_mfma_f32_16x16x32_bf16(Bt[n][k], At[m][k], acc[ai][bj][m][n], 0, 0, 0); __builtin_amdgcn_s_setprio(0); } while (0)
; #define PG8_WAIT_V(n) asm volatile("s_waitcnt vmcnt(" #n ")" ::: "memory")
; #define PG8_WAIT_L(n) asm volatile("s_waitcnt lgkmcnt(" #n ")" ::: "memory")
; #define PG8_BAR __builtin_amdgcn_s_barrier()
; #define PG8_SCHED __builtin_amdgcn_sched_barrier(0)
; template <class Epi, bool HALO>
; __device__ __forceinline__ void gemm_phase(LAS unsigned char* lds, const Gemm g, const StaticOrder& S, const Epi& E) {
;     ...
;             PG8_WAIT_V(8); PG8_WAIT_L(0); PG8_BAR; PG8_MMA(1, 0, At, B0); PG8_MMA(1, 1, At, B1); PG8_BAR; PG8_SCHED;
;             PG8_LDB(B0, 1, 0); PG8_LDB(B1, 1, 1); PG8_SCHED; PG8_LDA(At, 1, 0); PG8_STAGE(PG8_SA(0, 1), a2 + hstepA, voffA);
;             PG8_WAIT_V(8); PG8_WAIT_L(0); PG8_BAR; PG8_MMA(0, 0, At, B0); PG8_MMA(0, 1, At, B1); PG8_BAR; PG8_SCHED;
	s_setprio 1
	s_waitcnt lgkmcnt(0)
	v_mfma_f32_16x16x32_bf16 v[60:63], v[154:157], v[186:189], v[60:63]
	v_mfma_f32_16x16x32_bf16 v[56:59], v[162:165], v[186:189], v[56:59]
	v_mfma_f32_16x16x32_bf16 v[44:47], v[154:157], v[194:197], v[44:47]
	v_mfma_f32_16x16x32_bf16 v[40:43], v[162:165], v[194:197], v[40:43]
	v_mfma_f32_16x16x32_bf16 v[28:31], v[154:157], v[202:205], v[28:31]
	v_mfma_f32_16x16x32_bf16 v[24:27], v[162:165], v[202:205], v[24:27]
	v_mfma_f32_16x16x32_bf16 v[12:15], v[154:157], v[210:213], v[12:15]
	v_mfma_f32_16x16x32_bf16 v[8:11], v[162:165], v[210:213], v[8:11]
	v_mfma_f32_16x16x32_bf16 v[60:63], v[158:161], v[190:193], v[60:63]
	v_mfma_f32_16x16x32_bf16 v[56:59], v[166:169], v[190:193], v[56:59]
	v_mfma_f32_16x16x32_bf16 v[44:47], v[158:161], v[198:201], v[44:47]
	v_mfma_f32_16x16x32_bf16 v[40:43], v[166:169], v[198:201], v[40:43]
	v_mfma_f32_16x16x32_bf16 v[28:31], v[158:161], v[206:209], v[28:31]
	v_mfma_f32_16x16x32_bf16 v[24:27], v[166:169], v[206:209], v[24:27]
	v_mfma_f32_16x16x32_bf16 v[12:15], v[158:161], v[214:217], v[12:15]
	v_mfma_f32_16x16x32_bf16 v[8:11], v[166:169], v[214:217], v[8:11]
	s_setprio 0
	s_setprio 1
	v_mfma_f32_16x16x32_bf16 v[52:55], v[170:173], v[186:189], v[52:55]
	v_mfma_f32_16x16x32_bf16 v[48:51], v[178:181], v[186:189], v[48:51]
	v_mfma_f32_16x16x32_bf16 v[36:39], v[170:173], v[194:197], v[36:39]
	v_mfma_f32_16x16x32_bf16 v[32:35], v[178:181], v[194:197], v[32:35]
	v_mfma_f32_16x16x32_bf16 v[20:23], v[170:173], v[202:205], v[20:23]
	v_mfma_f32_16x16x32_bf16 v[16:19], v[178:181], v[202:205], v[16:19]
	v_mfma_f32_16x16x32_bf16 v[4:7], v[170:173], v[210:213], v[4:7]
	v_mfma_f32_16x16x32_bf16 v[0:3], v[178:181], v[210:213], v[0:3]
	v_mfma_f32_16x16x32_bf16 v[52:55], v[174:177], v[190:193], v[52:55]
	v_mfma_f32_16x16x32_bf16 v[48:51], v[182:185], v[190:193], v[48:51]
	v_mfma_f32_16x16x32_bf16 v[36:39], v[174:177], v[198:201], v[36:39]
	v_mfma_f32_16x16x32_bf16 v[32:35], v[182:185], v[198:201], v[32:35]
	v_mfma_f32_16x16x32_bf16 v[20:23], v[174:177], v[206:209], v[20:23]
	v_mfma_f32_16x16x32_bf16 v[16:19], v[182:185], v[206:209], v[16:19]
	v_mfma_f32_16x16x32_bf16 v[4:7], v[174:177], v[214:217], v[4:7]
	v_mfma_f32_16x16x32_bf16 v[0:3], v[182:185], v[214:217], v[0:3]
	s_setprio 0
	s_barrier
	s_add_i32 s67, 0, 0x18000
	v_add_u32_e32 v136, s67, v148
	s_add_i32 s68, 0, 0x1c000
	ds_read_b128 v[154:157], v136
	ds_read_b128 v[158:161], v136 offset:1024
	ds_read_b128 v[162:165], v136 offset:2048
	ds_read_b128 v[166:169], v136 offset:3072
	v_add_u32_e32 v136, s68, v148
	ds_read_b128 v[170:173], v136
	ds_read_b128 v[174:177], v136 offset:1024
	ds_read_b128 v[178:181], v136 offset:2048
	ds_read_b128 v[182:185], v136 offset:3072
	s_add_u32 s38, s38, 0x40000
	s_addc_u32 s39, s39, 0
	s_mov_b32 m0, s54
	v_lshl_add_u64 v[222:223], s[38:39], 0, v[130:131]
	ds_read_b128 v[186:189], v151 offset:32768
	ds_read_b128 v[190:193], v151 offset:33792
	ds_read_b128 v[194:197], v151 offset:34816
	ds_read_b128 v[198:201], v151 offset:35840
	ds_read_b128 v[202:205], v151 offset:36864
	ds_read_b128 v[206:209], v151 offset:37888
	ds_read_b128 v[210:213], v151 offset:38912
	ds_read_b128 v[214:217], v151 offset:39936
	global_load_lds_dwordx4 v[222:223], off
	v_lshl_add_u64 v[222:223], s[38:39], 0, v[134:135]
	s_mov_b32 m0, s55
	s_nop 0
	global_load_lds_dwordx4 v[222:223], off
	s_waitcnt vmcnt(8)
	s_waitcnt lgkmcnt(0)
	s_barrier
	s_setprio 1
	s_waitcnt lgkmcnt(0)
	v_mfma_f32_16x16x32_bf16 v[124:127], v[154:157], v[186:189], v[124:127]
	v_mfma_f32_16x16x32_bf16 v[120:123], v[162:165], v[186:189], v[120:123]
	v_mfma_f32_16x16x32_bf16 v[108:111], v[154:157], v[194:197], v[108:111]
	v_mfma_f32_16x16x32_bf16 v[104:107], v[162:165], v[194:197], v[104:107]
	v_mfma_f32_16x16x32_bf16 v[92:95], v[154:157], v[202:205], v[92:95]
	v_mfma_f32_16x16x32_bf16 v[88:91], v[162:165], v[202:205], v[88:91]
	v_mfma_f32_16x16x32_bf16 v[76:79], v[154:157], v[210:213], v[76:79]
	v_mfma_f32_16x16x32_bf16 v[72:75], v[162:165], v[210:213], v[72:75]
	v_mfma_f32_16x16x32_bf16 v[124:127], v[158:161], v[190:193], v[124:127]
	v_mfma_f32_16x16x32_bf16 v[120:123], v[166:169], v[190:193], v[120:123]
	v_mfma_f32_16x16x32_bf16 v[108:111], v[158:161], v[198:201], v[108:111]
	v_mfma_f32_16x16x32_bf16 v[104:107], v[166:169], v[198:201], v[104:107]
	v_mfma_f32_16x16x32_bf16 v[92:95], v[158:161], v[206:209], v[92:95]
	v_mfma_f32_16x16x32_bf16 v[88:91], v[166:169], v[206:209], v[88:91]
	v_mfma_f32_16x16x32_bf16 v[76:79], v[158:161], v[214:217], v[76:79]
	v_mfma_f32_16x16x32_bf16 v[72:75], v[166:169], v[214:217], v[72:75]
	s_setprio 0
	s_setprio 1
	v_mfma_f32_16x16x32_bf16 v[116:119], v[170:173], v[186:189], v[116:119]
	v_mfma_f32_16x16x32_bf16 v[112:115], v[178:181], v[186:189], v[112:115]
	v_mfma_f32_16x16x32_bf16 v[100:103], v[170:173], v[194:197], v[100:103]
	v_mfma_f32_16x16x32_bf16 v[96:99], v[178:181], v[194:197], v[96:99]
	v_mfma_f32_16x16x32_bf16 v[84:87], v[170:173], v[202:205], v[84:87]
	v_mfma_f32_16x16x32_bf16 v[80:83], v[178:181], v[202:205], v[80:83]
	v_mfma_f32_16x16x32_bf16 v[68:71], v[170:173], v[210:213], v[68:71]
	v_mfma_f32_16x16x32_bf16 v[64:67], v[178:181], v[210:213], v[64:67]
	v_mfma_f32_16x16x32_bf16 v[116:119], v[174:177], v[190:193], v[116:119]
	v_mfma_f32_16x16x32_bf16 v[112:115], v[182:185], v[190:193], v[112:115]
	v_mfma_f32_16x16x32_bf16 v[100:103], v[174:177], v[198:201], v[100:103]
	v_mfma_f32_16x16x32_bf16 v[96:99], v[182:185], v[198:201], v[96:99]
	v_mfma_f32_16x16x32_bf16 v[84:87], v[174:177], v[206:209], v[84:87]
	v_mfma_f32_16x16x32_bf16 v[80:83], v[182:185], v[206:209], v[80:83]
	v_mfma_f32_16x16x32_bf16 v[68:71], v[174:177], v[214:217], v[68:71]
	v_mfma_f32_16x16x32_bf16 v[64:67], v[182:185], v[214:217], v[64:67]
	s_setprio 0
	s_barrier
; #define PG8_STAGE(bufoff, gbase, voff) do { _Pragma("unroll") for (int _i = 0; _i < 2; ++_i) \
;         __builtin_amdgcn_global_load_lds((const unsigned*)((const char*)(gbase) + (voff)[_i]), (LAS unsigned*)(lds + (bufoff) + ldsw + _i * 8192), 16, 0, 0); } while (0)
; #define PG8_LDA(dst, b, h) do { _Pragma("unroll") for (int m = 0; m < 4; ++m) _Pragma("unroll") for (int k = 0; k < 2; ++k) dst[m][k] = *(const LAS bf16x8*)(lds + PG8_SA(b, h) + aoff + m * 2048 + k * 1024); } while (0)
; #define PG8_MMA(ai, bj, At, Bt) do { __builtin_amdgcn_s_setprio(1); _Pragma("unroll") for (int m = 0; m < 4; ++m) _Pragma("unroll") for (int n = 0; n < 2; ++n) _Pragma("unroll") for (int k = 0; k < 2; ++k) \
;         acc[ai][bj][m][n] = __builtin_amdgcn_mfma_f32_16x16x32_bf16(Bt[n][k], At[m][k], acc[ai][bj][m][n], 0, 0, 0); __builtin_amdgcn_s_setprio(0); } while (0)
; #define PG8_WAIT_V(n) asm volatile("s_waitcnt vmcnt(" #n ")" ::: "memory")
; #define PG8_WAIT_L(n) asm volatile("s_waitcnt lgkmcnt(" #n ")" ::: "memory")
; #define PG8_BAR __builtin_amdgcn_s_barrier()
; #define PG8_SCHED __builtin_amdgcn_sched_barrier(0)
; template <class Epi, bool HALO>
; __device__ __forceinline__ void gemm_phase(LAS unsigned char* lds, const Gemm g, const StaticOrder& S, const Epi& E) {
;     ...
;             PG8_LDA(At, 1, 1); PG8_STAGE(PG8_SB(1, 0), b3, voffB); PG8_STAGE(PG8_SB(1, 1), b3 + hstepB, voffB); PG8_STAGE(PG8_SA(1, 0), a3, voffA);
;             PG8_WAIT_V(8); PG8_WAIT_L(0); PG8_BAR; PG8_MMA(1, 0, At, B0); PG8_MMA(1, 1, At, B1); PG8_BAR; PG8_SCHED;
;         }
;         if (wr == 0) PG8_BAR;
	s_add_u32 s38, s36, 0x8000
	s_addc_u32 s39, s37, 0
	s_add_i32 s67, s67, s51
	v_lshl_add_u64 v[222:223], s[38:39], 0, v[128:129]
	s_mov_b32 m0, s67
	ds_read_b128 v[186:189], v151 offset:49152
	ds_read_b128 v[190:193], v151 offset:50176
	ds_read_b128 v[194:197], v151 offset:51200
	ds_read_b128 v[198:201], v151 offset:52224
	ds_read_b128 v[202:205], v151 offset:53248
	ds_read_b128 v[206:209], v151 offset:54272
	ds_read_b128 v[210:213], v151 offset:55296
	ds_read_b128 v[214:217], v151 offset:56320
	global_load_lds_dwordx4 v[222:223], off
	s_add_i32 m0, s67, 0x2000
	s_add_u32 s36, s36, 0xc000
	v_lshl_add_u64 v[222:223], s[38:39], 0, v[132:133]
	s_addc_u32 s37, s37, 0
	s_add_i32 s38, s68, s51
	global_load_lds_dwordx4 v[222:223], off
	v_lshl_add_u64 v[222:223], s[36:37], 0, v[128:129]
	s_mov_b32 m0, s38
	v_lshl_add_u64 v[146:147], v[146:147], 0, s[16:17]
	global_load_lds_dwordx4 v[222:223], off
	v_lshl_add_u64 v[222:223], s[36:37], 0, v[132:133]
	s_add_i32 m0, s38, 0x2000
	s_nop 0
	global_load_lds_dwordx4 v[222:223], off
	s_mov_b32 m0, s58
	s_nop 0
	global_load_lds_dwordx4 v[146:147], off
	v_lshl_add_u64 v[146:147], v[218:219], 0, s[16:17]
	s_mov_b32 m0, s59
	s_nop 0
	global_load_lds_dwordx4 v[146:147], off
	s_waitcnt vmcnt(8)
	s_waitcnt lgkmcnt(0)
	s_barrier
	s_setprio 1
	s_waitcnt lgkmcnt(0)
	v_mfma_f32_16x16x32_bf16 v[60:63], v[154:157], v[186:189], v[60:63]
	v_mfma_f32_16x16x32_bf16 v[56:59], v[162:165], v[186:189], v[56:59]
	v_mfma_f32_16x16x32_bf16 v[44:47], v[154:157], v[194:197], v[44:47]
	v_mfma_f32_16x16x32_bf16 v[40:43], v[162:165], v[194:197], v[40:43]
	v_mfma_f32_16x16x32_bf16 v[28:31], v[154:157], v[202:205], v[28:31]
	v_mfma_f32_16x16x32_bf16 v[24:27], v[162:165], v[202:205], v[24:27]
	v_mfma_f32_16x16x32_bf16 v[12:15], v[154:157], v[210:213], v[12:15]
	v_mfma_f32_16x16x32_bf16 v[8:11], v[162:165], v[210:213], v[8:11]
	v_mfma_f32_16x16x32_bf16 v[60:63], v[158:161], v[190:193], v[60:63]
	v_mfma_f32_16x16x32_bf16 v[56:59], v[166:169], v[190:193], v[56:59]
	v_mfma_f32_16x16x32_bf16 v[44:47], v[158:161], v[198:201], v[44:47]
	v_mfma_f32_16x16x32_bf16 v[40:43], v[166:169], v[198:201], v[40:43]
	v_mfma_f32_16x16x32_bf16 v[28:31], v[158:161], v[206:209], v[28:31]
	v_mfma_f32_16x16x32_bf16 v[24:27], v[166:169], v[206:209], v[24:27]
	v_mfma_f32_16x16x32_bf16 v[12:15], v[158:161], v[214:217], v[12:15]
	v_mfma_f32_16x16x32_bf16 v[8:11], v[166:169], v[214:217], v[8:11]
	s_setprio 0
	s_setprio 1
	v_mfma_f32_16x16x32_bf16 v[52:55], v[170:173], v[186:189], v[52:55]
	v_mfma_f32_16x16x32_bf16 v[48:51], v[178:181], v[186:189], v[48:51]
	v_mfma_f32_16x16x32_bf16 v[36:39], v[170:173], v[194:197], v[36:39]
	v_mfma_f32_16x16x32_bf16 v[32:35], v[178:181], v[194:197], v[32:35]
	v_mfma_f32_16x16x32_bf16 v[20:23], v[170:173], v[202:205], v[20:23]
	v_mfma_f32_16x16x32_bf16 v[16:19], v[178:181], v[202:205], v[16:19]
	v_mfma_f32_16x16x32_bf16 v[4:7], v[170:173], v[210:213], v[4:7]
	v_mfma_f32_16x16x32_bf16 v[0:3], v[178:181], v[210:213], v[0:3]
	v_mfma_f32_16x16x32_bf16 v[52:55], v[174:177], v[190:193], v[52:55]
	v_mfma_f32_16x16x32_bf16 v[48:51], v[182:185], v[190:193], v[48:51]
	v_mfma_f32_16x16x32_bf16 v[36:39], v[174:177], v[198:201], v[36:39]
	v_mfma_f32_16x16x32_bf16 v[32:35], v[182:185], v[198:201], v[32:35]
	v_mfma_f32_16x16x32_bf16 v[20:23], v[174:177], v[206:209], v[20:23]
	v_mfma_f32_16x16x32_bf16 v[16:19], v[182:185], v[206:209], v[16:19]
	s_add_i32 s66, s66, 2
	s_add_u32 s64, s64, 0x10000
	s_addc_u32 s65, s65, 0
	s_add_u32 s34, s34, 0x100
	s_addc_u32 s35, s35, 0
	s_cmp_gt_u32 s66, 13
	v_mfma_f32_16x16x32_bf16 v[4:7], v[174:177], v[214:217], v[4:7]
	v_mfma_f32_16x16x32_bf16 v[0:3], v[182:185], v[214:217], v[0:3]
	s_setprio 0
	s_barrier
	s_cbranch_scc0 .LBB0_499
	s_and_b64 vcc, exec, s[18:19]
	s_cbranch_vccz .LBB0_502
	s_barrier

; #define PG8_STAGE(bufoff, gbase, voff) do { _Pragma("unroll") for (int _i = 0; _i < 2; ++_i) \
;         __builtin_amdgcn_global_load_lds((const unsigned*)((const char*)(gbase) + (voff)[_i]), (LAS unsigned*)(lds + (bufoff) + ldsw + _i * 8192), 16, 0, 0); } while (0)
; #define PG8_LDA(dst, b, h) do { _Pragma("unroll") for (int m = 0; m < 4; ++m) _Pragma("unroll") for (int k = 0; k < 2; ++k) dst[m][k] = *(const LAS bf16x8*)(lds + PG8_SA(b, h) + aoff + m * 2048 + k * 1024); } while (0)
; #define PG8_LDB(dst, b, h) do { _Pragma("unroll") for (int n = 0; n < 2; ++n) _Pragma("unroll") for (int k = 0; k < 2; ++k) dst[n][k] = *(const LAS bf16x8*)(lds + PG8_SB(b, h) + boff + n * 2048 + k * 1024); } while (0)
; #define PG8_MMA(ai, bj, At, Bt) do { __builtin_amdgcn_s_setprio(1); _Pragma("unroll") for (int m = 0; m < 4; ++m) _Pragma("unroll") for (int n = 0; n < 2; ++n) _Pragma("unroll") for (int k = 0; k < 2; ++k) \
;         acc[ai][bj][m][n] = __builtin_amdgcn_mfma_f32_16x16x32_bf16(Bt[n][k], At[m][k], acc[ai][bj][m][n], 0, 0, 0); __builtin_amdgcn_s_setprio(0); } while (0)
; #define PG8_WAIT_V(n) asm volatile("s_waitcnt vmcnt(" #n ")" ::: "memory")
; #define PG8_WAIT_L(n) asm volatile("s_waitcnt lgkmcnt(" #n ")" ::: "memory")
; #define PG8_BAR __builtin_amdgcn_s_barrier()
; #define PG8_SCHED __builtin_amdgcn_sched_barrier(0)
; template <class Epi, bool HALO>
; __device__ __forceinline__ void gemm_phase(LAS unsigned char* lds, const Gemm g, const StaticOrder& S, const Epi& E) {
;     ...
;         for (int t = 0; t < nt; t += 2) {
;             const bool last = (t == nt - 2);
;             const char* a1 = cA + (size_t)(t + 1) * kstep;
;             const char* a2 = last ? nA : cA + (size_t)(t + 2) * kstep; const char* b2 = last ? nB : cB + (size_t)(t + 2) * kstepB;
;             const char* a3 = a2 + kstep; const char* b3 = b2 + kstepB;
;             PG8_LDB(B0, 0, 0); PG8_LDB(B1, 0, 1); PG8_SCHED; PG8_LDA(At, 0, 0); PG8_STAGE(PG8_SA(1, 1), a1 + hstepA, voffA);
;             PG8_WAIT_V(8); PG8_WAIT_L(0); PG8_BAR; PG8_MMA(0, 0, At, B0); PG8_MMA(0, 1, At, B1); PG8_BAR; PG8_SCHED;
;             PG8_LDA(At, 0, 1); PG8_STAGE(PG8_SB(0, 0), b2, voffB); PG8_STAGE(PG8_SB(0, 1), b2 + hstepB, voffB); PG8_STAGE(PG8_SA(0, 0), a2, voffA);
.Lwp5_skip:
.LBB0_596:
	ds_read_b128 v[116:119], v222
	ds_read_b128 v[120:123], v222 offset:1024
	ds_read_b128 v[132:135], v222 offset:2048
	ds_read_b128 v[136:139], v222 offset:3072
	ds_read_b128 v[144:147], v223
	ds_read_b128 v[148:151], v223 offset:1024
	ds_read_b128 v[152:155], v223 offset:2048
	ds_read_b128 v[156:159], v223 offset:3072
	s_add_u32 s10, s8, 0xfffc0080
	s_addc_u32 s11, s9, -1
	s_cmp_eq_u32 s43, 12
	s_cselect_b32 s13, s16, s11
	s_cselect_b32 s12, s17, s10
	s_cselect_b32 s11, s31, s42
	s_cselect_b32 s10, s35, s41
	v_lshl_add_u64 v[210:211], s[8:9], 0, v[186:187]
	s_add_i32 m0, s60, 0xc000
	ds_read_b128 v[160:163], v224
	ds_read_b128 v[164:167], v224 offset:1024
	ds_read_b128 v[168:171], v224 offset:2048
	ds_read_b128 v[172:175], v224 offset:3072
	ds_read_b128 v[194:197], v224 offset:4096
	ds_read_b128 v[198:201], v224 offset:5120
	ds_read_b128 v[202:205], v224 offset:6144
	ds_read_b128 v[206:209], v224 offset:7168
	global_load_lds_dwordx4 v[210:211], off
	v_lshl_add_u64 v[210:211], s[8:9], 0, v[188:189]
	s_add_i32 m0, s60, 0xe000
	s_nop 0
	global_load_lds_dwordx4 v[210:211], off
	s_waitcnt vmcnt(8)
	s_waitcnt lgkmcnt(0)
	s_barrier
	s_setprio 1
	s_waitcnt lgkmcnt(0)
	v_mfma_f32_16x16x32_bf16 v[104:107], v[116:119], v[160:163], v[104:107]
	v_mfma_f32_16x16x32_bf16 v[100:103], v[132:135], v[160:163], v[100:103]
	v_mfma_f32_16x16x32_bf16 v[140:143], v[116:119], v[168:171], v[140:143]
	v_mfma_f32_16x16x32_bf16 v[44:47], v[132:135], v[168:171], v[44:47]
	v_mfma_f32_16x16x32_bf16 v[128:131], v[116:119], v[194:197], v[128:131]
	v_mfma_f32_16x16x32_bf16 v[40:43], v[132:135], v[194:197], v[40:43]
	v_mfma_f32_16x16x32_bf16 v[108:111], v[116:119], v[202:205], v[108:111]
	v_mfma_f32_16x16x32_bf16 v[52:55], v[132:135], v[202:205], v[52:55]
	v_mfma_f32_16x16x32_bf16 v[104:107], v[120:123], v[164:167], v[104:107]
	v_mfma_f32_16x16x32_bf16 v[100:103], v[136:139], v[164:167], v[100:103]
	v_mfma_f32_16x16x32_bf16 v[140:143], v[120:123], v[172:175], v[140:143]
	v_mfma_f32_16x16x32_bf16 v[44:47], v[136:139], v[172:175], v[44:47]
	v_mfma_f32_16x16x32_bf16 v[128:131], v[120:123], v[198:201], v[128:131]
	v_mfma_f32_16x16x32_bf16 v[40:43], v[136:139], v[198:201], v[40:43]
	v_mfma_f32_16x16x32_bf16 v[108:111], v[120:123], v[206:209], v[108:111]
	v_mfma_f32_16x16x32_bf16 v[52:55], v[136:139], v[206:209], v[52:55]
	s_setprio 0
	s_setprio 1
	v_mfma_f32_16x16x32_bf16 v[96:99], v[144:147], v[160:163], v[96:99]
	v_mfma_f32_16x16x32_bf16 v[72:75], v[152:155], v[160:163], v[72:75]
	v_mfma_f32_16x16x32_bf16 v[124:127], v[144:147], v[168:171], v[124:127]
	v_mfma_f32_16x16x32_bf16 v[36:39], v[152:155], v[168:171], v[36:39]
	v_mfma_f32_16x16x32_bf16 v[112:115], v[144:147], v[194:197], v[112:115]
	v_mfma_f32_16x16x32_bf16 v[32:35], v[152:155], v[194:197], v[32:35]
	v_mfma_f32_16x16x32_bf16 v[92:95], v[144:147], v[202:205], v[92:95]
	v_mfma_f32_16x16x32_bf16 v[48:51], v[152:155], v[202:205], v[48:51]
	v_mfma_f32_16x16x32_bf16 v[96:99], v[148:151], v[164:167], v[96:99]
	v_mfma_f32_16x16x32_bf16 v[72:75], v[156:159], v[164:167], v[72:75]
	v_mfma_f32_16x16x32_bf16 v[124:127], v[148:151], v[172:175], v[124:127]
	v_mfma_f32_16x16x32_bf16 v[36:39], v[156:159], v[172:175], v[36:39]
	v_mfma_f32_16x16x32_bf16 v[112:115], v[148:151], v[198:201], v[112:115]
	v_mfma_f32_16x16x32_bf16 v[32:35], v[156:159], v[198:201], v[32:35]
	v_mfma_f32_16x16x32_bf16 v[92:95], v[148:151], v[206:209], v[92:95]
	v_mfma_f32_16x16x32_bf16 v[48:51], v[156:159], v[206:209], v[48:51]
	s_setprio 0
	s_barrier
	s_add_i32 s50, s76, s57
	v_lshl_add_u64 v[210:211], s[10:11], 0, v[176:177]
	s_mov_b32 m0, s50
	ds_read_b128 v[160:163], v224 offset:16384
	ds_read_b128 v[164:167], v224 offset:17408
	ds_read_b128 v[168:171], v224 offset:18432
	ds_read_b128 v[172:175], v224 offset:19456
	ds_read_b128 v[194:197], v224 offset:20480
	ds_read_b128 v[198:201], v224 offset:21504
	ds_read_b128 v[202:205], v224 offset:22528
	ds_read_b128 v[206:209], v224 offset:23552
	global_load_lds_dwordx4 v[210:211], off
	s_add_i32 m0, s50, 0x2000
	s_add_u32 s50, s10, 0x4000
	v_lshl_add_u64 v[210:211], s[10:11], 0, v[180:181]
	s_addc_u32 s51, s11, 0
	s_add_i32 s93, s77, s57
	global_load_lds_dwordx4 v[210:211], off
	v_lshl_add_u64 v[210:211], s[50:51], 0, v[176:177]
	s_mov_b32 m0, s93
	v_lshl_add_u64 v[212:213], s[12:13], 0, v[182:183]
	global_load_lds_dwordx4 v[210:211], off
	v_lshl_add_u64 v[210:211], s[50:51], 0, v[180:181]
	s_add_i32 m0, s93, 0x2000
	s_nop 0
	global_load_lds_dwordx4 v[210:211], off
	v_lshl_add_u64 v[210:211], s[12:13], 0, v[178:179]
	s_mov_b32 m0, s60
	s_nop 0
	global_load_lds_dwordx4 v[210:211], off
	s_mov_b32 m0, s61
	s_nop 0
	global_load_lds_dwordx4 v[212:213], off
	s_waitcnt vmcnt(8)
	s_waitcnt lgkmcnt(0)
	s_barrier
; #define PG8_STAGE(bufoff, gbase, voff) do { _Pragma("unroll") for (int _i = 0; _i < 2; ++_i) \
;         __builtin_amdgcn_global_load_lds((const unsigned*)((const char*)(gbase) + (voff)[_i]), (LAS unsigned*)(lds + (bufoff) + ldsw + _i * 8192), 16, 0, 0); } while (0)
; #define PG8_LDA(dst, b, h) do { _Pragma("unroll") for (int m = 0; m < 4; ++m) _Pragma("unroll") for (int k = 0; k < 2; ++k) dst[m][k] = *(const LAS bf16x8*)(lds + PG8_SA(b, h) + aoff + m * 2048 + k * 1024); } while (0)
; #define PG8_LDB(dst, b, h) do { _Pragma("unroll") for (int n = 0; n < 2; ++n) _Pragma("unroll") for (int k = 0; k < 2; ++k) dst[n][k] = *(const LAS bf16x8*)(lds + PG8_SB(b, h) + boff + n * 2048 + k * 1024); } while (0)
; #define PG8_MMA(ai, bj, At, Bt) do { __builtin_amdgcn_s_setprio(1); _Pragma("unroll") for (int m = 0; m < 4; ++m) _Pragma("unroll") for (int n = 0; n < 2; ++n) _Pragma("unroll") for (int k = 0; k < 2; ++k) \
;         acc[ai][bj][m][n] = __builtin_amdgcn_mfma_f32_16x16x32_bf16(Bt[n][k], At[m][k], acc[ai][bj][m][n], 0, 0, 0); __builtin_amdgcn_s_setprio(0); } while (0)
; #define PG8_WAIT_V(n) asm volatile("s_waitcnt vmcnt(" #n ")" ::: "memory")
; #define PG8_WAIT_L(n) asm volatile("s_waitcnt lgkmcnt(" #n ")" ::: "memory")
; #define PG8_BAR __builtin_amdgcn_s_barrier()
; #define PG8_SCHED __builtin_amdgcn_sched_barrier(0)
; template <class Epi, bool HALO>
; __device__ __forceinline__ void gemm_phase(LAS unsigned char* lds, const Gemm g, const StaticOrder& S, const Epi& E) {
;     ...
;             PG8_WAIT_V(8); PG8_WAIT_L(0); PG8_BAR; PG8_MMA(1, 0, At, B0); PG8_MMA(1, 1, At, B1); PG8_BAR; PG8_SCHED;
;             PG8_LDB(B0, 1, 0); PG8_LDB(B1, 1, 1); PG8_SCHED; PG8_LDA(At, 1, 0); PG8_STAGE(PG8_SA(0, 1), a2 + hstepA, voffA);
;             PG8_WAIT_V(8); PG8_WAIT_L(0); PG8_BAR; PG8_MMA(0, 0, At, B0); PG8_MMA(0, 1, At, B1); PG8_BAR; PG8_SCHED;
	s_setprio 1
	s_waitcnt lgkmcnt(0)
	v_mfma_f32_16x16x32_bf16 v[84:87], v[116:119], v[160:163], v[84:87]
	v_mfma_f32_16x16x32_bf16 v[20:23], v[132:135], v[160:163], v[20:23]
	v_mfma_f32_16x16x32_bf16 v[68:71], v[116:119], v[168:171], v[68:71]
	v_mfma_f32_16x16x32_bf16 v[12:15], v[132:135], v[168:171], v[12:15]
	v_mfma_f32_16x16x32_bf16 v[64:67], v[116:119], v[194:197], v[64:67]
	v_mfma_f32_16x16x32_bf16 v[8:11], v[132:135], v[194:197], v[8:11]
	v_mfma_f32_16x16x32_bf16 v[88:91], v[116:119], v[202:205], v[88:91]
	v_mfma_f32_16x16x32_bf16 v[28:31], v[132:135], v[202:205], v[28:31]
	v_mfma_f32_16x16x32_bf16 v[84:87], v[120:123], v[164:167], v[84:87]
	v_mfma_f32_16x16x32_bf16 v[20:23], v[136:139], v[164:167], v[20:23]
	v_mfma_f32_16x16x32_bf16 v[68:71], v[120:123], v[172:175], v[68:71]
	v_mfma_f32_16x16x32_bf16 v[12:15], v[136:139], v[172:175], v[12:15]
	v_mfma_f32_16x16x32_bf16 v[64:67], v[120:123], v[198:201], v[64:67]
	v_mfma_f32_16x16x32_bf16 v[8:11], v[136:139], v[198:201], v[8:11]
	v_mfma_f32_16x16x32_bf16 v[88:91], v[120:123], v[206:209], v[88:91]
	v_mfma_f32_16x16x32_bf16 v[28:31], v[136:139], v[206:209], v[28:31]
	s_setprio 0
	s_setprio 1
	v_mfma_f32_16x16x32_bf16 v[80:83], v[144:147], v[160:163], v[80:83]
	v_mfma_f32_16x16x32_bf16 v[16:19], v[152:155], v[160:163], v[16:19]
	v_mfma_f32_16x16x32_bf16 v[60:63], v[144:147], v[168:171], v[60:63]
	v_mfma_f32_16x16x32_bf16 v[4:7], v[152:155], v[168:171], v[4:7]
	v_mfma_f32_16x16x32_bf16 v[56:59], v[144:147], v[194:197], v[56:59]
	v_mfma_f32_16x16x32_bf16 v[0:3], v[152:155], v[194:197], v[0:3]
	v_mfma_f32_16x16x32_bf16 v[76:79], v[144:147], v[202:205], v[76:79]
	v_mfma_f32_16x16x32_bf16 v[24:27], v[152:155], v[202:205], v[24:27]
	v_mfma_f32_16x16x32_bf16 v[80:83], v[148:151], v[164:167], v[80:83]
	v_mfma_f32_16x16x32_bf16 v[16:19], v[156:159], v[164:167], v[16:19]
	v_mfma_f32_16x16x32_bf16 v[60:63], v[148:151], v[172:175], v[60:63]
	v_mfma_f32_16x16x32_bf16 v[4:7], v[156:159], v[172:175], v[4:7]
	v_mfma_f32_16x16x32_bf16 v[56:59], v[148:151], v[198:201], v[56:59]
	v_mfma_f32_16x16x32_bf16 v[0:3], v[156:159], v[198:201], v[0:3]
	v_mfma_f32_16x16x32_bf16 v[76:79], v[148:151], v[206:209], v[76:79]
	v_mfma_f32_16x16x32_bf16 v[24:27], v[156:159], v[206:209], v[24:27]
	s_setprio 0
	s_barrier
	s_add_i32 s50, 0, 0x18000
	s_add_i32 s51, 0, 0x1c000
	v_add_u32_e32 v136, s50, v221
	v_add_u32_e32 v156, s51, v221
	ds_read_b128 v[116:119], v136
	ds_read_b128 v[120:123], v136 offset:1024
	ds_read_b128 v[132:135], v136 offset:2048
	ds_read_b128 v[136:139], v136 offset:3072
	ds_read_b128 v[144:147], v156
	ds_read_b128 v[148:151], v156 offset:1024
	ds_read_b128 v[152:155], v156 offset:2048
	ds_read_b128 v[156:159], v156 offset:3072
	s_add_u32 s12, s12, 0x40000
	s_addc_u32 s13, s13, 0
	s_mov_b32 m0, s62
	v_lshl_add_u64 v[214:215], s[12:13], 0, v[178:179]
	ds_read_b128 v[160:163], v224 offset:32768
	ds_read_b128 v[164:167], v224 offset:33792
	ds_read_b128 v[168:171], v224 offset:34816
	ds_read_b128 v[172:175], v224 offset:35840
	ds_read_b128 v[194:197], v224 offset:36864
	ds_read_b128 v[198:201], v224 offset:37888
	ds_read_b128 v[202:205], v224 offset:38912
	ds_read_b128 v[206:209], v224 offset:39936
	global_load_lds_dwordx4 v[214:215], off
	v_lshl_add_u64 v[214:215], s[12:13], 0, v[182:183]
	s_mov_b32 m0, s63
	s_nop 0
	global_load_lds_dwordx4 v[214:215], off
	s_waitcnt vmcnt(8)
	s_waitcnt lgkmcnt(0)
	s_barrier
	s_setprio 1
	s_waitcnt lgkmcnt(0)
	v_mfma_f32_16x16x32_bf16 v[104:107], v[116:119], v[160:163], v[104:107]
	v_mfma_f32_16x16x32_bf16 v[100:103], v[132:135], v[160:163], v[100:103]
	v_mfma_f32_16x16x32_bf16 v[140:143], v[116:119], v[168:171], v[140:143]
	v_mfma_f32_16x16x32_bf16 v[44:47], v[132:135], v[168:171], v[44:47]
	v_mfma_f32_16x16x32_bf16 v[128:131], v[116:119], v[194:197], v[128:131]
	v_mfma_f32_16x16x32_bf16 v[40:43], v[132:135], v[194:197], v[40:43]
	v_mfma_f32_16x16x32_bf16 v[108:111], v[116:119], v[202:205], v[108:111]
	v_mfma_f32_16x16x32_bf16 v[52:55], v[132:135], v[202:205], v[52:55]
	v_mfma_f32_16x16x32_bf16 v[104:107], v[120:123], v[164:167], v[104:107]
	v_mfma_f32_16x16x32_bf16 v[100:103], v[136:139], v[164:167], v[100:103]
	v_mfma_f32_16x16x32_bf16 v[140:143], v[120:123], v[172:175], v[140:143]
	v_mfma_f32_16x16x32_bf16 v[44:47], v[136:139], v[172:175], v[44:47]
	v_mfma_f32_16x16x32_bf16 v[128:131], v[120:123], v[198:201], v[128:131]
	v_mfma_f32_16x16x32_bf16 v[40:43], v[136:139], v[198:201], v[40:43]
	v_mfma_f32_16x16x32_bf16 v[108:111], v[120:123], v[206:209], v[108:111]
	v_mfma_f32_16x16x32_bf16 v[52:55], v[136:139], v[206:209], v[52:55]
	s_setprio 0
	s_setprio 1
	v_mfma_f32_16x16x32_bf16 v[96:99], v[144:147], v[160:163], v[96:99]
	v_mfma_f32_16x16x32_bf16 v[72:75], v[152:155], v[160:163], v[72:75]
	v_mfma_f32_16x16x32_bf16 v[124:127], v[144:147], v[168:171], v[124:127]
	v_mfma_f32_16x16x32_bf16 v[36:39], v[152:155], v[168:171], v[36:39]
	v_mfma_f32_16x16x32_bf16 v[112:115], v[144:147], v[194:197], v[112:115]
	v_mfma_f32_16x16x32_bf16 v[32:35], v[152:155], v[194:197], v[32:35]
	v_mfma_f32_16x16x32_bf16 v[92:95], v[144:147], v[202:205], v[92:95]
	v_mfma_f32_16x16x32_bf16 v[48:51], v[152:155], v[202:205], v[48:51]
	v_mfma_f32_16x16x32_bf16 v[96:99], v[148:151], v[164:167], v[96:99]
	v_mfma_f32_16x16x32_bf16 v[72:75], v[156:159], v[164:167], v[72:75]
	v_mfma_f32_16x16x32_bf16 v[124:127], v[148:151], v[172:175], v[124:127]
	v_mfma_f32_16x16x32_bf16 v[36:39], v[156:159], v[172:175], v[36:39]
	v_mfma_f32_16x16x32_bf16 v[112:115], v[148:151], v[198:201], v[112:115]
	v_mfma_f32_16x16x32_bf16 v[32:35], v[156:159], v[198:201], v[32:35]
	v_mfma_f32_16x16x32_bf16 v[92:95], v[148:151], v[206:209], v[92:95]
	v_mfma_f32_16x16x32_bf16 v[48:51], v[156:159], v[206:209], v[48:51]
	s_setprio 0
	s_barrier
; #define PG8_STAGE(bufoff, gbase, voff) do { _Pragma("unroll") for (int _i = 0; _i < 2; ++_i) \
;         __builtin_amdgcn_global_load_lds((const unsigned*)((const char*)(gbase) + (voff)[_i]), (LAS unsigned*)(lds + (bufoff) + ldsw + _i * 8192), 16, 0, 0); } while (0)
; #define PG8_LDA(dst, b, h) do { _Pragma("unroll") for (int m = 0; m < 4; ++m) _Pragma("unroll") for (int k = 0; k < 2; ++k) dst[m][k] = *(const LAS bf16x8*)(lds + PG8_SA(b, h) + aoff + m * 2048 + k * 1024); } while (0)
; #define PG8_MMA(ai, bj, At, Bt) do { __builtin_amdgcn_s_setprio(1); _Pragma("unroll") for (int m = 0; m < 4; ++m) _Pragma("unroll") for (int n = 0; n < 2; ++n) _Pragma("unroll") for (int k = 0; k < 2; ++k) \
;         acc[ai][bj][m][n] = __builtin_amdgcn_mfma_f32_16x16x32_bf16(Bt[n][k], At[m][k], acc[ai][bj][m][n], 0, 0, 0); __builtin_amdgcn_s_setprio(0); } while (0)
; #define PG8_WAIT_V(n) asm volatile("s_waitcnt vmcnt(" #n ")" ::: "memory")
; #define PG8_WAIT_L(n) asm volatile("s_waitcnt lgkmcnt(" #n ")" ::: "memory")
; #define PG8_BAR __builtin_amdgcn_s_barrier()
; #define PG8_SCHED __builtin_amdgcn_sched_barrier(0)
; template <class Epi, bool HALO>
; __device__ __forceinline__ void gemm_phase(LAS unsigned char* lds, const Gemm g, const StaticOrder& S, const Epi& E) {
;     ...
;             PG8_LDA(At, 1, 1); PG8_STAGE(PG8_SB(1, 0), b3, voffB); PG8_STAGE(PG8_SB(1, 1), b3 + hstepB, voffB); PG8_STAGE(PG8_SA(1, 0), a3, voffA);
;             PG8_WAIT_V(8); PG8_WAIT_L(0); PG8_BAR; PG8_MMA(1, 0, At, B0); PG8_MMA(1, 1, At, B1); PG8_BAR; PG8_SCHED;
;         }
;         if (wr == 0) PG8_BAR;
	s_add_u32 s12, s10, 0x8000
	s_addc_u32 s13, s11, 0
	s_add_i32 s50, s50, s57
	v_lshl_add_u64 v[214:215], s[12:13], 0, v[176:177]
	s_mov_b32 m0, s50
	ds_read_b128 v[160:163], v224 offset:49152
	ds_read_b128 v[164:167], v224 offset:50176
	ds_read_b128 v[168:171], v224 offset:51200
	ds_read_b128 v[172:175], v224 offset:52224
	ds_read_b128 v[194:197], v224 offset:53248
	ds_read_b128 v[198:201], v224 offset:54272
	ds_read_b128 v[202:205], v224 offset:55296
	ds_read_b128 v[206:209], v224 offset:56320
	global_load_lds_dwordx4 v[214:215], off
	s_add_i32 m0, s50, 0x2000
	s_add_u32 s10, s10, 0xc000
	v_lshl_add_u64 v[214:215], s[12:13], 0, v[180:181]
	s_addc_u32 s11, s11, 0
	s_add_i32 s12, s51, s57
	global_load_lds_dwordx4 v[214:215], off
	v_lshl_add_u64 v[214:215], s[10:11], 0, v[176:177]
	s_mov_b32 m0, s12
	v_lshl_add_u64 v[210:211], v[210:211], 0, s[26:27]
	global_load_lds_dwordx4 v[214:215], off
	v_lshl_add_u64 v[214:215], s[10:11], 0, v[180:181]
	s_add_i32 m0, s12, 0x2000
	s_nop 0
	global_load_lds_dwordx4 v[214:215], off
	s_mov_b32 m0, s68
	s_nop 0
	global_load_lds_dwordx4 v[210:211], off
	v_lshl_add_u64 v[210:211], v[212:213], 0, s[26:27]
	s_mov_b32 m0, s69
	s_nop 0
	global_load_lds_dwordx4 v[210:211], off
	s_waitcnt vmcnt(8)
	s_waitcnt lgkmcnt(0)
	s_barrier
	s_setprio 1
	s_waitcnt lgkmcnt(0)
	v_mfma_f32_16x16x32_bf16 v[84:87], v[116:119], v[160:163], v[84:87]
	v_mfma_f32_16x16x32_bf16 v[20:23], v[132:135], v[160:163], v[20:23]
	v_mfma_f32_16x16x32_bf16 v[68:71], v[116:119], v[168:171], v[68:71]
	v_mfma_f32_16x16x32_bf16 v[12:15], v[132:135], v[168:171], v[12:15]
	v_mfma_f32_16x16x32_bf16 v[64:67], v[116:119], v[194:197], v[64:67]
	v_mfma_f32_16x16x32_bf16 v[8:11], v[132:135], v[194:197], v[8:11]
	v_mfma_f32_16x16x32_bf16 v[88:91], v[116:119], v[202:205], v[88:91]
	v_mfma_f32_16x16x32_bf16 v[28:31], v[132:135], v[202:205], v[28:31]
	v_mfma_f32_16x16x32_bf16 v[84:87], v[120:123], v[164:167], v[84:87]
	v_mfma_f32_16x16x32_bf16 v[20:23], v[136:139], v[164:167], v[20:23]
	v_mfma_f32_16x16x32_bf16 v[68:71], v[120:123], v[172:175], v[68:71]
	v_mfma_f32_16x16x32_bf16 v[12:15], v[136:139], v[172:175], v[12:15]
	v_mfma_f32_16x16x32_bf16 v[64:67], v[120:123], v[198:201], v[64:67]
	v_mfma_f32_16x16x32_bf16 v[8:11], v[136:139], v[198:201], v[8:11]
	v_mfma_f32_16x16x32_bf16 v[88:91], v[120:123], v[206:209], v[88:91]
	v_mfma_f32_16x16x32_bf16 v[28:31], v[136:139], v[206:209], v[28:31]
	s_setprio 0
	s_setprio 1
	v_mfma_f32_16x16x32_bf16 v[80:83], v[144:147], v[160:163], v[80:83]
	v_mfma_f32_16x16x32_bf16 v[16:19], v[152:155], v[160:163], v[16:19]
	v_mfma_f32_16x16x32_bf16 v[60:63], v[144:147], v[168:171], v[60:63]
	v_mfma_f32_16x16x32_bf16 v[4:7], v[152:155], v[168:171], v[4:7]
	v_mfma_f32_16x16x32_bf16 v[56:59], v[144:147], v[194:197], v[56:59]
	v_mfma_f32_16x16x32_bf16 v[0:3], v[152:155], v[194:197], v[0:3]
	v_mfma_f32_16x16x32_bf16 v[76:79], v[144:147], v[202:205], v[76:79]
	v_mfma_f32_16x16x32_bf16 v[24:27], v[152:155], v[202:205], v[24:27]
	v_mfma_f32_16x16x32_bf16 v[80:83], v[148:151], v[164:167], v[80:83]
	v_mfma_f32_16x16x32_bf16 v[16:19], v[156:159], v[164:167], v[16:19]
	v_mfma_f32_16x16x32_bf16 v[60:63], v[148:151], v[172:175], v[60:63]
	v_mfma_f32_16x16x32_bf16 v[4:7], v[156:159], v[172:175], v[4:7]
	v_mfma_f32_16x16x32_bf16 v[56:59], v[148:151], v[198:201], v[56:59]
	v_mfma_f32_16x16x32_bf16 v[0:3], v[156:159], v[198:201], v[0:3]
	s_add_i32 s43, s43, 2
	s_add_u32 s41, s41, 0x10000
	s_addc_u32 s42, s42, 0
	s_add_u32 s8, s8, 0x100
	s_addc_u32 s9, s9, 0
	s_cmp_gt_u32 s43, 13
	v_mfma_f32_16x16x32_bf16 v[76:79], v[148:151], v[206:209], v[76:79]
	v_mfma_f32_16x16x32_bf16 v[24:27], v[156:159], v[206:209], v[24:27]
	s_setprio 0
	s_barrier
	s_cbranch_scc0 .LBB0_596
	s_and_b64 vcc, exec, s[28:29]
	s_cbranch_vccz .LBB0_599
	s_barrier

; #define PG8_STAGE(bufoff, gbase, voff) do { _Pragma("unroll") for (int _i = 0; _i < 2; ++_i) \
;         __builtin_amdgcn_global_load_lds((const unsigned*)((const char*)(gbase) + (voff)[_i]), (LAS unsigned*)(lds + (bufoff) + ldsw + _i * 8192), 16, 0, 0); } while (0)
; #define PG8_LDA(dst, b, h) do { _Pragma("unroll") for (int m = 0; m < 4; ++m) _Pragma("unroll") for (int k = 0; k < 2; ++k) dst[m][k] = *(const LAS bf16x8*)(lds + PG8_SA(b, h) + aoff + m * 2048 + k * 1024); } while (0)
; #define PG8_LDB(dst, b, h) do { _Pragma("unroll") for (int n = 0; n < 2; ++n) _Pragma("unroll") for (int k = 0; k < 2; ++k) dst[n][k] = *(const LAS bf16x8*)(lds + PG8_SB(b, h) + boff + n * 2048 + k * 1024); } while (0)
; #define PG8_MMA(ai, bj, At, Bt) do { __builtin_amdgcn_s_setprio(1); _Pragma("unroll") for (int m = 0; m < 4; ++m) _Pragma("unroll") for (int n = 0; n < 2; ++n) _Pragma("unroll") for (int k = 0; k < 2; ++k) \
;         acc[ai][bj][m][n] = __builtin_amdgcn_mfma_f32_16x16x32_bf16(Bt[n][k], At[m][k], acc[ai][bj][m][n], 0, 0, 0); __builtin_amdgcn_s_setprio(0); } while (0)
; #define PG8_WAIT_V(n) asm volatile("s_waitcnt vmcnt(" #n ")" ::: "memory")
; #define PG8_WAIT_L(n) asm volatile("s_waitcnt lgkmcnt(" #n ")" ::: "memory")
; #define PG8_BAR __builtin_amdgcn_s_barrier()
; #define PG8_SCHED __builtin_amdgcn_sched_barrier(0)
; template <class Epi, bool HALO>
; __device__ __forceinline__ void gemm_phase(LAS unsigned char* lds, const Gemm g, const StaticOrder& S, const Epi& E) {
;     ...
;         for (int t = 0; t < nt; t += 2) {
;             const bool last = (t == nt - 2);
;             const char* a1 = cA + (size_t)(t + 1) * kstep;
;             const char* a2 = last ? nA : cA + (size_t)(t + 2) * kstep; const char* b2 = last ? nB : cB + (size_t)(t + 2) * kstepB;
;             const char* a3 = a2 + kstep; const char* b3 = b2 + kstepB;
;             PG8_LDB(B0, 0, 0); PG8_LDB(B1, 0, 1); PG8_SCHED; PG8_LDA(At, 0, 0); PG8_STAGE(PG8_SA(1, 1), a1 + hstepA, voffA);
;             PG8_WAIT_V(8); PG8_WAIT_L(0); PG8_BAR; PG8_MMA(0, 0, At, B0); PG8_MMA(0, 1, At, B1); PG8_BAR; PG8_SCHED;
;             PG8_LDA(At, 0, 1); PG8_STAGE(PG8_SB(0, 0), b2, voffB); PG8_STAGE(PG8_SB(0, 1), b2 + hstepB, voffB); PG8_STAGE(PG8_SA(0, 0), a2, voffA);
.LBB0_727:
	ds_read_b128 v[146:149], v141
	ds_read_b128 v[150:153], v141 offset:1024
	ds_read_b128 v[154:157], v141 offset:2048
	ds_read_b128 v[158:161], v141 offset:3072
	ds_read_b128 v[162:165], v142
	ds_read_b128 v[166:169], v142 offset:1024
	ds_read_b128 v[170:173], v142 offset:2048
	ds_read_b128 v[174:177], v142 offset:3072
	s_add_u32 s26, s24, 0x4000
	s_addc_u32 s27, s25, 0
	s_cmp_eq_u32 s62, 40
	s_cselect_b32 s30, s8, s26
	s_cselect_b32 s31, s9, s27
	s_cselect_b32 s28, s22, s60
	s_cselect_b32 s29, s23, s61
	s_add_u32 s26, s30, 0x8000
	s_addc_u32 s27, s31, 0
	v_lshl_add_u64 v[138:139], s[24:25], 0, v[128:129]
	s_add_i32 m0, s42, 0xc000
	ds_read_b128 v[178:181], v143
	ds_read_b128 v[182:185], v143 offset:1024
	ds_read_b128 v[186:189], v143 offset:2048
	ds_read_b128 v[190:193], v143 offset:3072
	ds_read_b128 v[194:197], v143 offset:4096
	ds_read_b128 v[198:201], v143 offset:5120
	ds_read_b128 v[202:205], v143 offset:6144
	ds_read_b128 v[206:209], v143 offset:7168
	global_load_lds_dwordx4 v[138:139], off
	v_lshl_add_u64 v[138:139], s[24:25], 0, v[130:131]
	s_add_i32 m0, s42, 0xe000
	s_nop 0
	global_load_lds_dwordx4 v[138:139], off
	s_waitcnt vmcnt(8)
	s_waitcnt lgkmcnt(0)
	s_barrier
	s_setprio 1
	s_waitcnt lgkmcnt(0)
	v_mfma_f32_16x16x32_bf16 v[124:127], v[146:149], v[178:181], v[124:127]
	v_mfma_f32_16x16x32_bf16 v[120:123], v[154:157], v[178:181], v[120:123]
	v_mfma_f32_16x16x32_bf16 v[108:111], v[146:149], v[186:189], v[108:111]
	v_mfma_f32_16x16x32_bf16 v[104:107], v[154:157], v[186:189], v[104:107]
	v_mfma_f32_16x16x32_bf16 v[92:95], v[146:149], v[194:197], v[92:95]
	v_mfma_f32_16x16x32_bf16 v[88:91], v[154:157], v[194:197], v[88:91]
	v_mfma_f32_16x16x32_bf16 v[76:79], v[146:149], v[202:205], v[76:79]
	v_mfma_f32_16x16x32_bf16 v[72:75], v[154:157], v[202:205], v[72:75]
	v_mfma_f32_16x16x32_bf16 v[124:127], v[150:153], v[182:185], v[124:127]
	v_mfma_f32_16x16x32_bf16 v[120:123], v[158:161], v[182:185], v[120:123]
	v_mfma_f32_16x16x32_bf16 v[108:111], v[150:153], v[190:193], v[108:111]
	v_mfma_f32_16x16x32_bf16 v[104:107], v[158:161], v[190:193], v[104:107]
	v_mfma_f32_16x16x32_bf16 v[92:95], v[150:153], v[198:201], v[92:95]
	v_mfma_f32_16x16x32_bf16 v[88:91], v[158:161], v[198:201], v[88:91]
	v_mfma_f32_16x16x32_bf16 v[76:79], v[150:153], v[206:209], v[76:79]
	v_mfma_f32_16x16x32_bf16 v[72:75], v[158:161], v[206:209], v[72:75]
	s_setprio 0
	s_setprio 1
	v_mfma_f32_16x16x32_bf16 v[116:119], v[162:165], v[178:181], v[116:119]
	v_mfma_f32_16x16x32_bf16 v[112:115], v[170:173], v[178:181], v[112:115]
	v_mfma_f32_16x16x32_bf16 v[100:103], v[162:165], v[186:189], v[100:103]
	v_mfma_f32_16x16x32_bf16 v[96:99], v[170:173], v[186:189], v[96:99]
	v_mfma_f32_16x16x32_bf16 v[84:87], v[162:165], v[194:197], v[84:87]
	v_mfma_f32_16x16x32_bf16 v[80:83], v[170:173], v[194:197], v[80:83]
	v_mfma_f32_16x16x32_bf16 v[68:71], v[162:165], v[202:205], v[68:71]
	v_mfma_f32_16x16x32_bf16 v[64:67], v[170:173], v[202:205], v[64:67]
	v_mfma_f32_16x16x32_bf16 v[116:119], v[166:169], v[182:185], v[116:119]
	v_mfma_f32_16x16x32_bf16 v[112:115], v[174:177], v[182:185], v[112:115]
	v_mfma_f32_16x16x32_bf16 v[100:103], v[166:169], v[190:193], v[100:103]
	v_mfma_f32_16x16x32_bf16 v[96:99], v[174:177], v[190:193], v[96:99]
	v_mfma_f32_16x16x32_bf16 v[84:87], v[166:169], v[198:201], v[84:87]
	v_mfma_f32_16x16x32_bf16 v[80:83], v[174:177], v[198:201], v[80:83]
	v_mfma_f32_16x16x32_bf16 v[68:71], v[166:169], v[206:209], v[68:71]
	v_mfma_f32_16x16x32_bf16 v[64:67], v[174:177], v[206:209], v[64:67]
	s_setprio 0
	s_barrier
	s_add_i32 s63, s56, s41
	v_lshl_add_u64 v[138:139], s[28:29], 0, v[128:129]
	s_mov_b32 m0, s63
	ds_read_b128 v[178:181], v143 offset:16384
	ds_read_b128 v[182:185], v143 offset:17408
	ds_read_b128 v[186:189], v143 offset:18432
	ds_read_b128 v[190:193], v143 offset:19456
	ds_read_b128 v[194:197], v143 offset:20480
	ds_read_b128 v[198:201], v143 offset:21504
	ds_read_b128 v[202:205], v143 offset:22528
	ds_read_b128 v[206:209], v143 offset:23552
	global_load_lds_dwordx4 v[138:139], off
	s_add_i32 m0, s63, 0x2000
	s_add_u32 s64, s28, 0x4000
	v_lshl_add_u64 v[138:139], s[28:29], 0, v[130:131]
	s_addc_u32 s65, s29, 0
	s_add_i32 s63, s57, s41
	global_load_lds_dwordx4 v[138:139], off
	v_lshl_add_u64 v[138:139], s[64:65], 0, v[128:129]
	s_mov_b32 m0, s63
	s_nop 0
	global_load_lds_dwordx4 v[138:139], off
	v_lshl_add_u64 v[138:139], s[64:65], 0, v[130:131]
	s_add_i32 m0, s63, 0x2000
	s_nop 0
	global_load_lds_dwordx4 v[138:139], off
	v_lshl_add_u64 v[138:139], s[30:31], 0, v[128:129]
	s_mov_b32 m0, s42
	s_nop 0
	global_load_lds_dwordx4 v[138:139], off
	v_lshl_add_u64 v[138:139], s[30:31], 0, v[130:131]
	s_mov_b32 m0, s43
	s_nop 0
	global_load_lds_dwordx4 v[138:139], off
	s_waitcnt vmcnt(8)
	s_waitcnt lgkmcnt(0)
	s_barrier
; #define PG8_STAGE(bufoff, gbase, voff) do { _Pragma("unroll") for (int _i = 0; _i < 2; ++_i) \
;         __builtin_amdgcn_global_load_lds((const unsigned*)((const char*)(gbase) + (voff)[_i]), (LAS unsigned*)(lds + (bufoff) + ldsw + _i * 8192), 16, 0, 0); } while (0)
; #define PG8_LDA(dst, b, h) do { _Pragma("unroll") for (int m = 0; m < 4; ++m) _Pragma("unroll") for (int k = 0; k < 2; ++k) dst[m][k] = *(const LAS bf16x8*)(lds + PG8_SA(b, h) + aoff + m * 2048 + k * 1024); } while (0)
; #define PG8_LDB(dst, b, h) do { _Pragma("unroll") for (int n = 0; n < 2; ++n) _Pragma("unroll") for (int k = 0; k < 2; ++k) dst[n][k] = *(const LAS bf16x8*)(lds + PG8_SB(b, h) + boff + n * 2048 + k * 1024); } while (0)
; #define PG8_MMA(ai, bj, At, Bt) do { __builtin_amdgcn_s_setprio(1); _Pragma("unroll") for (int m = 0; m < 4; ++m) _Pragma("unroll") for (int n = 0; n < 2; ++n) _Pragma("unroll") for (int k = 0; k < 2; ++k) \
;         acc[ai][bj][m][n] = __builtin_amdgcn_mfma_f32_16x16x32_bf16(Bt[n][k], At[m][k], acc[ai][bj][m][n], 0, 0, 0); __builtin_amdgcn_s_setprio(0); } while (0)
; #define PG8_WAIT_V(n) asm volatile("s_waitcnt vmcnt(" #n ")" ::: "memory")
; #define PG8_WAIT_L(n) asm volatile("s_waitcnt lgkmcnt(" #n ")" ::: "memory")
; #define PG8_BAR __builtin_amdgcn_s_barrier()
; #define PG8_SCHED __builtin_amdgcn_sched_barrier(0)
; template <class Epi, bool HALO>
; __device__ __forceinline__ void gemm_phase(LAS unsigned char* lds, const Gemm g, const StaticOrder& S, const Epi& E) {
;     ...
;             PG8_WAIT_V(8); PG8_WAIT_L(0); PG8_BAR; PG8_MMA(1, 0, At, B0); PG8_MMA(1, 1, At, B1); PG8_BAR; PG8_SCHED;
;             PG8_LDB(B0, 1, 0); PG8_LDB(B1, 1, 1); PG8_SCHED; PG8_LDA(At, 1, 0); PG8_STAGE(PG8_SA(0, 1), a2 + hstepA, voffA);
;             PG8_WAIT_V(8); PG8_WAIT_L(0); PG8_BAR; PG8_MMA(0, 0, At, B0); PG8_MMA(0, 1, At, B1); PG8_BAR; PG8_SCHED;
	s_setprio 1
	s_waitcnt lgkmcnt(0)
	v_mfma_f32_16x16x32_bf16 v[60:63], v[146:149], v[178:181], v[60:63]
	v_mfma_f32_16x16x32_bf16 v[56:59], v[154:157], v[178:181], v[56:59]
	v_mfma_f32_16x16x32_bf16 v[44:47], v[146:149], v[186:189], v[44:47]
	v_mfma_f32_16x16x32_bf16 v[40:43], v[154:157], v[186:189], v[40:43]
	v_mfma_f32_16x16x32_bf16 v[28:31], v[146:149], v[194:197], v[28:31]
	v_mfma_f32_16x16x32_bf16 v[24:27], v[154:157], v[194:197], v[24:27]
	v_mfma_f32_16x16x32_bf16 v[12:15], v[146:149], v[202:205], v[12:15]
	v_mfma_f32_16x16x32_bf16 v[8:11], v[154:157], v[202:205], v[8:11]
	v_mfma_f32_16x16x32_bf16 v[60:63], v[150:153], v[182:185], v[60:63]
	v_mfma_f32_16x16x32_bf16 v[56:59], v[158:161], v[182:185], v[56:59]
	v_mfma_f32_16x16x32_bf16 v[44:47], v[150:153], v[190:193], v[44:47]
	v_mfma_f32_16x16x32_bf16 v[40:43], v[158:161], v[190:193], v[40:43]
	v_mfma_f32_16x16x32_bf16 v[28:31], v[150:153], v[198:201], v[28:31]
	v_mfma_f32_16x16x32_bf16 v[24:27], v[158:161], v[198:201], v[24:27]
	v_mfma_f32_16x16x32_bf16 v[12:15], v[150:153], v[206:209], v[12:15]
	v_mfma_f32_16x16x32_bf16 v[8:11], v[158:161], v[206:209], v[8:11]
	s_setprio 0
	s_setprio 1
	v_mfma_f32_16x16x32_bf16 v[52:55], v[162:165], v[178:181], v[52:55]
	v_mfma_f32_16x16x32_bf16 v[48:51], v[170:173], v[178:181], v[48:51]
	v_mfma_f32_16x16x32_bf16 v[36:39], v[162:165], v[186:189], v[36:39]
	v_mfma_f32_16x16x32_bf16 v[32:35], v[170:173], v[186:189], v[32:35]
	v_mfma_f32_16x16x32_bf16 v[20:23], v[162:165], v[194:197], v[20:23]
	v_mfma_f32_16x16x32_bf16 v[16:19], v[170:173], v[194:197], v[16:19]
	v_mfma_f32_16x16x32_bf16 v[4:7], v[162:165], v[202:205], v[4:7]
	v_mfma_f32_16x16x32_bf16 v[0:3], v[170:173], v[202:205], v[0:3]
	v_mfma_f32_16x16x32_bf16 v[52:55], v[166:169], v[182:185], v[52:55]
	v_mfma_f32_16x16x32_bf16 v[48:51], v[174:177], v[182:185], v[48:51]
	v_mfma_f32_16x16x32_bf16 v[36:39], v[166:169], v[190:193], v[36:39]
	v_mfma_f32_16x16x32_bf16 v[32:35], v[174:177], v[190:193], v[32:35]
	v_mfma_f32_16x16x32_bf16 v[20:23], v[166:169], v[198:201], v[20:23]
	v_mfma_f32_16x16x32_bf16 v[16:19], v[174:177], v[198:201], v[16:19]
	v_mfma_f32_16x16x32_bf16 v[4:7], v[166:169], v[206:209], v[4:7]
	v_mfma_f32_16x16x32_bf16 v[0:3], v[174:177], v[206:209], v[0:3]
	s_setprio 0
	s_barrier
	s_add_i32 s63, 0, 0x18000
	v_add_u32_e32 v132, s63, v140
	s_add_i32 s64, 0, 0x1c000
	ds_read_b128 v[146:149], v132
	ds_read_b128 v[150:153], v132 offset:1024
	ds_read_b128 v[154:157], v132 offset:2048
	ds_read_b128 v[158:161], v132 offset:3072
	v_add_u32_e32 v132, s64, v140
	ds_read_b128 v[162:165], v132
	ds_read_b128 v[166:169], v132 offset:1024
	ds_read_b128 v[170:173], v132 offset:2048
	ds_read_b128 v[174:177], v132 offset:3072
	s_add_u32 s30, s30, 0x4000
	s_addc_u32 s31, s31, 0
	s_mov_b32 m0, s50
	v_lshl_add_u64 v[138:139], s[30:31], 0, v[128:129]
	ds_read_b128 v[178:181], v143 offset:32768
	ds_read_b128 v[182:185], v143 offset:33792
	ds_read_b128 v[186:189], v143 offset:34816
	ds_read_b128 v[190:193], v143 offset:35840
	ds_read_b128 v[194:197], v143 offset:36864
	ds_read_b128 v[198:201], v143 offset:37888
	ds_read_b128 v[202:205], v143 offset:38912
	ds_read_b128 v[206:209], v143 offset:39936
	global_load_lds_dwordx4 v[138:139], off
	v_lshl_add_u64 v[138:139], s[30:31], 0, v[130:131]
	s_mov_b32 m0, s51
	s_nop 0
	global_load_lds_dwordx4 v[138:139], off
	s_waitcnt vmcnt(8)
	s_waitcnt lgkmcnt(0)
	s_barrier
	s_setprio 1
	s_waitcnt lgkmcnt(0)
	v_mfma_f32_16x16x32_bf16 v[124:127], v[146:149], v[178:181], v[124:127]
	v_mfma_f32_16x16x32_bf16 v[120:123], v[154:157], v[178:181], v[120:123]
	v_mfma_f32_16x16x32_bf16 v[108:111], v[146:149], v[186:189], v[108:111]
	v_mfma_f32_16x16x32_bf16 v[104:107], v[154:157], v[186:189], v[104:107]
	v_mfma_f32_16x16x32_bf16 v[92:95], v[146:149], v[194:197], v[92:95]
	v_mfma_f32_16x16x32_bf16 v[88:91], v[154:157], v[194:197], v[88:91]
	v_mfma_f32_16x16x32_bf16 v[76:79], v[146:149], v[202:205], v[76:79]
	v_mfma_f32_16x16x32_bf16 v[72:75], v[154:157], v[202:205], v[72:75]
	v_mfma_f32_16x16x32_bf16 v[124:127], v[150:153], v[182:185], v[124:127]
	v_mfma_f32_16x16x32_bf16 v[120:123], v[158:161], v[182:185], v[120:123]
	v_mfma_f32_16x16x32_bf16 v[108:111], v[150:153], v[190:193], v[108:111]
	v_mfma_f32_16x16x32_bf16 v[104:107], v[158:161], v[190:193], v[104:107]
	v_mfma_f32_16x16x32_bf16 v[92:95], v[150:153], v[198:201], v[92:95]
	v_mfma_f32_16x16x32_bf16 v[88:91], v[158:161], v[198:201], v[88:91]
	v_mfma_f32_16x16x32_bf16 v[76:79], v[150:153], v[206:209], v[76:79]
	v_mfma_f32_16x16x32_bf16 v[72:75], v[158:161], v[206:209], v[72:75]
	s_setprio 0
	s_setprio 1
	v_mfma_f32_16x16x32_bf16 v[116:119], v[162:165], v[178:181], v[116:119]
	v_mfma_f32_16x16x32_bf16 v[112:115], v[170:173], v[178:181], v[112:115]
	v_mfma_f32_16x16x32_bf16 v[100:103], v[162:165], v[186:189], v[100:103]
	v_mfma_f32_16x16x32_bf16 v[96:99], v[170:173], v[186:189], v[96:99]
	v_mfma_f32_16x16x32_bf16 v[84:87], v[162:165], v[194:197], v[84:87]
	v_mfma_f32_16x16x32_bf16 v[80:83], v[170:173], v[194:197], v[80:83]
	v_mfma_f32_16x16x32_bf16 v[68:71], v[162:165], v[202:205], v[68:71]
	v_mfma_f32_16x16x32_bf16 v[64:67], v[170:173], v[202:205], v[64:67]
	v_mfma_f32_16x16x32_bf16 v[116:119], v[166:169], v[182:185], v[116:119]
	v_mfma_f32_16x16x32_bf16 v[112:115], v[174:177], v[182:185], v[112:115]
	v_mfma_f32_16x16x32_bf16 v[100:103], v[166:169], v[190:193], v[100:103]
	v_mfma_f32_16x16x32_bf16 v[96:99], v[174:177], v[190:193], v[96:99]
	v_mfma_f32_16x16x32_bf16 v[84:87], v[166:169], v[198:201], v[84:87]
	v_mfma_f32_16x16x32_bf16 v[80:83], v[174:177], v[198:201], v[80:83]
	v_mfma_f32_16x16x32_bf16 v[68:71], v[166:169], v[206:209], v[68:71]
	v_mfma_f32_16x16x32_bf16 v[64:67], v[174:177], v[206:209], v[64:67]
	s_setprio 0
	s_barrier
; #define PG8_STAGE(bufoff, gbase, voff) do { _Pragma("unroll") for (int _i = 0; _i < 2; ++_i) \
;         __builtin_amdgcn_global_load_lds((const unsigned*)((const char*)(gbase) + (voff)[_i]), (LAS unsigned*)(lds + (bufoff) + ldsw + _i * 8192), 16, 0, 0); } while (0)
; #define PG8_LDA(dst, b, h) do { _Pragma("unroll") for (int m = 0; m < 4; ++m) _Pragma("unroll") for (int k = 0; k < 2; ++k) dst[m][k] = *(const LAS bf16x8*)(lds + PG8_SA(b, h) + aoff + m * 2048 + k * 1024); } while (0)
; #define PG8_MMA(ai, bj, At, Bt) do { __builtin_amdgcn_s_setprio(1); _Pragma("unroll") for (int m = 0; m < 4; ++m) _Pragma("unroll") for (int n = 0; n < 2; ++n) _Pragma("unroll") for (int k = 0; k < 2; ++k) \
;         acc[ai][bj][m][n] = __builtin_amdgcn_mfma_f32_16x16x32_bf16(Bt[n][k], At[m][k], acc[ai][bj][m][n], 0, 0, 0); __builtin_amdgcn_s_setprio(0); } while (0)
; #define PG8_WAIT_V(n) asm volatile("s_waitcnt vmcnt(" #n ")" ::: "memory")
; #define PG8_WAIT_L(n) asm volatile("s_waitcnt lgkmcnt(" #n ")" ::: "memory")
; #define PG8_BAR __builtin_amdgcn_s_barrier()
; #define PG8_SCHED __builtin_amdgcn_sched_barrier(0)
; template <class Epi, bool HALO>
; __device__ __forceinline__ void gemm_phase(LAS unsigned char* lds, const Gemm g, const StaticOrder& S, const Epi& E) {
;     ...
;             PG8_LDA(At, 1, 1); PG8_STAGE(PG8_SB(1, 0), b3, voffB); PG8_STAGE(PG8_SB(1, 1), b3 + hstepB, voffB); PG8_STAGE(PG8_SA(1, 0), a3, voffA);
;             PG8_WAIT_V(8); PG8_WAIT_L(0); PG8_BAR; PG8_MMA(1, 0, At, B0); PG8_MMA(1, 1, At, B1); PG8_BAR; PG8_SCHED;
;         }
;         if (wr == 0) PG8_BAR;
	s_add_u32 s30, s28, 0x8000
	s_addc_u32 s31, s29, 0
	s_add_i32 s63, s63, s41
	v_lshl_add_u64 v[138:139], s[30:31], 0, v[128:129]
	s_mov_b32 m0, s63
	ds_read_b128 v[178:181], v143 offset:49152
	ds_read_b128 v[182:185], v143 offset:50176
	ds_read_b128 v[186:189], v143 offset:51200
	ds_read_b128 v[190:193], v143 offset:52224
	ds_read_b128 v[194:197], v143 offset:53248
	ds_read_b128 v[198:201], v143 offset:54272
	ds_read_b128 v[202:205], v143 offset:55296
	ds_read_b128 v[206:209], v143 offset:56320
	global_load_lds_dwordx4 v[138:139], off
	s_add_i32 m0, s63, 0x2000
	s_add_u32 s28, s28, 0xc000
	v_lshl_add_u64 v[138:139], s[30:31], 0, v[130:131]
	s_addc_u32 s29, s29, 0
	s_add_i32 s30, s64, s41
	global_load_lds_dwordx4 v[138:139], off
	v_lshl_add_u64 v[138:139], s[28:29], 0, v[128:129]
	s_mov_b32 m0, s30
	s_nop 0
	global_load_lds_dwordx4 v[138:139], off
	v_lshl_add_u64 v[138:139], s[28:29], 0, v[130:131]
	s_add_i32 m0, s30, 0x2000
	s_nop 0
	global_load_lds_dwordx4 v[138:139], off
	v_lshl_add_u64 v[138:139], s[26:27], 0, v[128:129]
	s_mov_b32 m0, s54
	s_nop 0
	global_load_lds_dwordx4 v[138:139], off
	v_lshl_add_u64 v[138:139], s[26:27], 0, v[130:131]
	s_mov_b32 m0, s55
	s_nop 0
	global_load_lds_dwordx4 v[138:139], off
	s_waitcnt vmcnt(8)
	s_waitcnt lgkmcnt(0)
	s_barrier
	s_setprio 1
	s_waitcnt lgkmcnt(0)
	v_mfma_f32_16x16x32_bf16 v[60:63], v[146:149], v[178:181], v[60:63]
	v_mfma_f32_16x16x32_bf16 v[56:59], v[154:157], v[178:181], v[56:59]
	v_mfma_f32_16x16x32_bf16 v[44:47], v[146:149], v[186:189], v[44:47]
	v_mfma_f32_16x16x32_bf16 v[40:43], v[154:157], v[186:189], v[40:43]
	v_mfma_f32_16x16x32_bf16 v[28:31], v[146:149], v[194:197], v[28:31]
	v_mfma_f32_16x16x32_bf16 v[24:27], v[154:157], v[194:197], v[24:27]
	v_mfma_f32_16x16x32_bf16 v[12:15], v[146:149], v[202:205], v[12:15]
	v_mfma_f32_16x16x32_bf16 v[8:11], v[154:157], v[202:205], v[8:11]
	v_mfma_f32_16x16x32_bf16 v[60:63], v[150:153], v[182:185], v[60:63]
	v_mfma_f32_16x16x32_bf16 v[56:59], v[158:161], v[182:185], v[56:59]
	v_mfma_f32_16x16x32_bf16 v[44:47], v[150:153], v[190:193], v[44:47]
	v_mfma_f32_16x16x32_bf16 v[40:43], v[158:161], v[190:193], v[40:43]
	v_mfma_f32_16x16x32_bf16 v[28:31], v[150:153], v[198:201], v[28:31]
	v_mfma_f32_16x16x32_bf16 v[24:27], v[158:161], v[198:201], v[24:27]
	v_mfma_f32_16x16x32_bf16 v[12:15], v[150:153], v[206:209], v[12:15]
	v_mfma_f32_16x16x32_bf16 v[8:11], v[158:161], v[206:209], v[8:11]
	s_setprio 0
	s_setprio 1
	v_mfma_f32_16x16x32_bf16 v[52:55], v[162:165], v[178:181], v[52:55]
	v_mfma_f32_16x16x32_bf16 v[48:51], v[170:173], v[178:181], v[48:51]
	v_mfma_f32_16x16x32_bf16 v[36:39], v[162:165], v[186:189], v[36:39]
	v_mfma_f32_16x16x32_bf16 v[32:35], v[170:173], v[186:189], v[32:35]
	v_mfma_f32_16x16x32_bf16 v[20:23], v[162:165], v[194:197], v[20:23]
	v_mfma_f32_16x16x32_bf16 v[16:19], v[170:173], v[194:197], v[16:19]
	v_mfma_f32_16x16x32_bf16 v[4:7], v[162:165], v[202:205], v[4:7]
	v_mfma_f32_16x16x32_bf16 v[0:3], v[170:173], v[202:205], v[0:3]
	v_mfma_f32_16x16x32_bf16 v[52:55], v[166:169], v[182:185], v[52:55]
	v_mfma_f32_16x16x32_bf16 v[48:51], v[174:177], v[182:185], v[48:51]
	v_mfma_f32_16x16x32_bf16 v[36:39], v[166:169], v[190:193], v[36:39]
	v_mfma_f32_16x16x32_bf16 v[32:35], v[174:177], v[190:193], v[32:35]
	v_mfma_f32_16x16x32_bf16 v[20:23], v[166:169], v[198:201], v[20:23]
	v_mfma_f32_16x16x32_bf16 v[16:19], v[174:177], v[198:201], v[16:19]
	s_add_i32 s62, s62, 2
	s_add_u32 s24, s24, 0x10000
	s_addc_u32 s25, s25, 0
	s_add_u32 s60, s60, 0x10000
	s_addc_u32 s61, s61, 0
	s_cmp_gt_u32 s62, 41
	v_mfma_f32_16x16x32_bf16 v[4:7], v[166:169], v[206:209], v[4:7]
	v_mfma_f32_16x16x32_bf16 v[0:3], v[174:177], v[206:209], v[0:3]
	s_setprio 0
	s_barrier
	s_cbranch_scc0 .LBB0_727
	s_and_b64 vcc, exec, s[20:21]
	s_cbranch_vccz .LBB0_730
	s_barrier

; #define PG8_STAGE(bufoff, gbase, voff) do { _Pragma("unroll") for (int _i = 0; _i < 2; ++_i) \
;         __builtin_amdgcn_global_load_lds((const unsigned*)((const char*)(gbase) + (voff)[_i]), (LAS unsigned*)(lds + (bufoff) + ldsw + _i * 8192), 16, 0, 0); } while (0)
; #define PG8_LDA(dst, b, h) do { _Pragma("unroll") for (int m = 0; m < 4; ++m) _Pragma("unroll") for (int k = 0; k < 2; ++k) dst[m][k] = *(const LAS bf16x8*)(lds + PG8_SA(b, h) + aoff + m * 2048 + k * 1024); } while (0)
; #define PG8_LDB(dst, b, h) do { _Pragma("unroll") for (int n = 0; n < 2; ++n) _Pragma("unroll") for (int k = 0; k < 2; ++k) dst[n][k] = *(const LAS bf16x8*)(lds + PG8_SB(b, h) + boff + n * 2048 + k * 1024); } while (0)
; #define PG8_MMA(ai, bj, At, Bt) do { __builtin_amdgcn_s_setprio(1); _Pragma("unroll") for (int m = 0; m < 4; ++m) _Pragma("unroll") for (int n = 0; n < 2; ++n) _Pragma("unroll") for (int k = 0; k < 2; ++k) \
;         acc[ai][bj][m][n] = __builtin_amdgcn_mfma_f32_16x16x32_bf16(Bt[n][k], At[m][k], acc[ai][bj][m][n], 0, 0, 0); __builtin_amdgcn_s_setprio(0); } while (0)
; #define PG8_WAIT_V(n) asm volatile("s_waitcnt vmcnt(" #n ")" ::: "memory")
; #define PG8_WAIT_L(n) asm volatile("s_waitcnt lgkmcnt(" #n ")" ::: "memory")
; #define PG8_BAR __builtin_amdgcn_s_barrier()
; #define PG8_SCHED __builtin_amdgcn_sched_barrier(0)
; template <class Epi, bool HALO>
; __device__ __forceinline__ void gemm_phase(LAS unsigned char* lds, const Gemm g, const StaticOrder& S, const Epi& E) {
;     ...
;         for (int t = 0; t < nt; t += 2) {
;             const bool last = (t == nt - 2);
;             const char* a1 = cA + (size_t)(t + 1) * kstep;
;             const char* a2 = last ? nA : cA + (size_t)(t + 2) * kstep; const char* b2 = last ? nB : cB + (size_t)(t + 2) * kstepB;
;             const char* a3 = a2 + kstep; const char* b3 = b2 + kstepB;
;             PG8_LDB(B0, 0, 0); PG8_LDB(B1, 0, 1); PG8_SCHED; PG8_LDA(At, 0, 0); PG8_STAGE(PG8_SA(1, 1), a1 + hstepA, voffA);
;             PG8_WAIT_V(8); PG8_WAIT_L(0); PG8_BAR; PG8_MMA(0, 0, At, B0); PG8_MMA(0, 1, At, B1); PG8_BAR; PG8_SCHED;
;             PG8_LDA(At, 0, 1); PG8_STAGE(PG8_SB(0, 0), b2, voffB); PG8_STAGE(PG8_SB(0, 1), b2 + hstepB, voffB); PG8_STAGE(PG8_SA(0, 0), a2, voffA);
.LBB0_824:
	ds_read_b128 v[146:149], v154
	ds_read_b128 v[158:161], v154 offset:1024
	ds_read_b128 v[162:165], v154 offset:2048
	ds_read_b128 v[166:169], v154 offset:3072
	ds_read_b128 v[170:173], v155
	ds_read_b128 v[174:177], v155 offset:1024
	ds_read_b128 v[178:181], v155 offset:2048
	ds_read_b128 v[182:185], v155 offset:3072
	s_add_u32 s40, s12, 0xfffc0080
	s_addc_u32 s41, s13, -1
	s_cmp_eq_u32 s52, 12
	s_cselect_b32 s43, s11, s41
	s_cselect_b32 s42, s16, s40
	s_cselect_b32 s41, s31, s51
	s_cselect_b32 s40, s35, s50
	v_lshl_add_u64 v[152:153], s[12:13], 0, v[138:139]
	s_add_i32 m0, s62, 0xc000
	ds_read_b128 v[186:189], v156
	ds_read_b128 v[190:193], v156 offset:1024
	ds_read_b128 v[194:197], v156 offset:2048
	ds_read_b128 v[198:201], v156 offset:3072
	ds_read_b128 v[202:205], v156 offset:4096
	ds_read_b128 v[206:209], v156 offset:5120
	ds_read_b128 v[210:213], v156 offset:6144
	ds_read_b128 v[214:217], v156 offset:7168
	global_load_lds_dwordx4 v[152:153], off
	v_lshl_add_u64 v[152:153], s[12:13], 0, v[140:141]
	s_add_i32 m0, s62, 0xe000
	s_nop 0
	global_load_lds_dwordx4 v[152:153], off
	s_waitcnt vmcnt(8)
	s_waitcnt lgkmcnt(0)
	s_barrier
	s_setprio 1
	s_waitcnt lgkmcnt(0)
	v_mfma_f32_16x16x32_bf16 v[124:127], v[146:149], v[186:189], v[124:127]
	v_mfma_f32_16x16x32_bf16 v[120:123], v[162:165], v[186:189], v[120:123]
	v_mfma_f32_16x16x32_bf16 v[108:111], v[146:149], v[194:197], v[108:111]
	v_mfma_f32_16x16x32_bf16 v[104:107], v[162:165], v[194:197], v[104:107]
	v_mfma_f32_16x16x32_bf16 v[92:95], v[146:149], v[202:205], v[92:95]
	v_mfma_f32_16x16x32_bf16 v[88:91], v[162:165], v[202:205], v[88:91]
	v_mfma_f32_16x16x32_bf16 v[76:79], v[146:149], v[210:213], v[76:79]
	v_mfma_f32_16x16x32_bf16 v[72:75], v[162:165], v[210:213], v[72:75]
	v_mfma_f32_16x16x32_bf16 v[124:127], v[158:161], v[190:193], v[124:127]
	v_mfma_f32_16x16x32_bf16 v[120:123], v[166:169], v[190:193], v[120:123]
	v_mfma_f32_16x16x32_bf16 v[108:111], v[158:161], v[198:201], v[108:111]
	v_mfma_f32_16x16x32_bf16 v[104:107], v[166:169], v[198:201], v[104:107]
	v_mfma_f32_16x16x32_bf16 v[92:95], v[158:161], v[206:209], v[92:95]
	v_mfma_f32_16x16x32_bf16 v[88:91], v[166:169], v[206:209], v[88:91]
	v_mfma_f32_16x16x32_bf16 v[76:79], v[158:161], v[214:217], v[76:79]
	v_mfma_f32_16x16x32_bf16 v[72:75], v[166:169], v[214:217], v[72:75]
	s_setprio 0
	s_setprio 1
	v_mfma_f32_16x16x32_bf16 v[116:119], v[170:173], v[186:189], v[116:119]
	v_mfma_f32_16x16x32_bf16 v[112:115], v[178:181], v[186:189], v[112:115]
	v_mfma_f32_16x16x32_bf16 v[100:103], v[170:173], v[194:197], v[100:103]
	v_mfma_f32_16x16x32_bf16 v[96:99], v[178:181], v[194:197], v[96:99]
	v_mfma_f32_16x16x32_bf16 v[84:87], v[170:173], v[202:205], v[84:87]
	v_mfma_f32_16x16x32_bf16 v[80:83], v[178:181], v[202:205], v[80:83]
	v_mfma_f32_16x16x32_bf16 v[68:71], v[170:173], v[210:213], v[68:71]
	v_mfma_f32_16x16x32_bf16 v[64:67], v[178:181], v[210:213], v[64:67]
	v_mfma_f32_16x16x32_bf16 v[116:119], v[174:177], v[190:193], v[116:119]
	v_mfma_f32_16x16x32_bf16 v[112:115], v[182:185], v[190:193], v[112:115]
	v_mfma_f32_16x16x32_bf16 v[100:103], v[174:177], v[198:201], v[100:103]
	v_mfma_f32_16x16x32_bf16 v[96:99], v[182:185], v[198:201], v[96:99]
	v_mfma_f32_16x16x32_bf16 v[84:87], v[174:177], v[206:209], v[84:87]
	v_mfma_f32_16x16x32_bf16 v[80:83], v[182:185], v[206:209], v[80:83]
	v_mfma_f32_16x16x32_bf16 v[68:71], v[174:177], v[214:217], v[68:71]
	v_mfma_f32_16x16x32_bf16 v[64:67], v[182:185], v[214:217], v[64:67]
	s_setprio 0
	s_barrier
	s_add_i32 s53, s86, s59
	v_lshl_add_u64 v[152:153], s[40:41], 0, v[128:129]
	s_mov_b32 m0, s53
	ds_read_b128 v[186:189], v156 offset:16384
	ds_read_b128 v[190:193], v156 offset:17408
	ds_read_b128 v[194:197], v156 offset:18432
	ds_read_b128 v[198:201], v156 offset:19456
	ds_read_b128 v[202:205], v156 offset:20480
	ds_read_b128 v[206:209], v156 offset:21504
	ds_read_b128 v[210:213], v156 offset:22528
	ds_read_b128 v[214:217], v156 offset:23552
	global_load_lds_dwordx4 v[152:153], off
	s_add_i32 m0, s53, 0x2000
	s_add_u32 s94, s40, 0x4000
	v_lshl_add_u64 v[152:153], s[40:41], 0, v[132:133]
	s_addc_u32 s95, s41, 0
	s_add_i32 s53, s87, s59
	global_load_lds_dwordx4 v[152:153], off
	v_lshl_add_u64 v[152:153], s[94:95], 0, v[128:129]
	s_mov_b32 m0, s53
	v_lshl_add_u64 v[218:219], s[42:43], 0, v[134:135]
	global_load_lds_dwordx4 v[152:153], off
	v_lshl_add_u64 v[152:153], s[94:95], 0, v[132:133]
	s_add_i32 m0, s53, 0x2000
	s_nop 0
	global_load_lds_dwordx4 v[152:153], off
	v_lshl_add_u64 v[152:153], s[42:43], 0, v[130:131]
	s_mov_b32 m0, s62
	s_nop 0
	global_load_lds_dwordx4 v[152:153], off
	s_mov_b32 m0, s63
	s_nop 0
	global_load_lds_dwordx4 v[218:219], off
	s_waitcnt vmcnt(8)
	s_waitcnt lgkmcnt(0)
	s_barrier
; #define PG8_STAGE(bufoff, gbase, voff) do { _Pragma("unroll") for (int _i = 0; _i < 2; ++_i) \
;         __builtin_amdgcn_global_load_lds((const unsigned*)((const char*)(gbase) + (voff)[_i]), (LAS unsigned*)(lds + (bufoff) + ldsw + _i * 8192), 16, 0, 0); } while (0)
; #define PG8_LDA(dst, b, h) do { _Pragma("unroll") for (int m = 0; m < 4; ++m) _Pragma("unroll") for (int k = 0; k < 2; ++k) dst[m][k] = *(const LAS bf16x8*)(lds + PG8_SA(b, h) + aoff + m * 2048 + k * 1024); } while (0)
; #define PG8_LDB(dst, b, h) do { _Pragma("unroll") for (int n = 0; n < 2; ++n) _Pragma("unroll") for (int k = 0; k < 2; ++k) dst[n][k] = *(const LAS bf16x8*)(lds + PG8_SB(b, h) + boff + n * 2048 + k * 1024); } while (0)
; #define PG8_MMA(ai, bj, At, Bt) do { __builtin_amdgcn_s_setprio(1); _Pragma("unroll") for (int m = 0; m < 4; ++m) _Pragma("unroll") for (int n = 0; n < 2; ++n) _Pragma("unroll") for (int k = 0; k < 2; ++k) \
;         acc[ai][bj][m][n] = __builtin_amdgcn_mfma_f32_16x16x32_bf16(Bt[n][k], At[m][k], acc[ai][bj][m][n], 0, 0, 0); __builtin_amdgcn_s_setprio(0); } while (0)
; #define PG8_WAIT_V(n) asm volatile("s_waitcnt vmcnt(" #n ")" ::: "memory")
; #define PG8_WAIT_L(n) asm volatile("s_waitcnt lgkmcnt(" #n ")" ::: "memory")
; #define PG8_BAR __builtin_amdgcn_s_barrier()
; #define PG8_SCHED __builtin_amdgcn_sched_barrier(0)
; template <class Epi, bool HALO>
; __device__ __forceinline__ void gemm_phase(LAS unsigned char* lds, const Gemm g, const StaticOrder& S, const Epi& E) {
;     ...
;             PG8_WAIT_V(8); PG8_WAIT_L(0); PG8_BAR; PG8_MMA(1, 0, At, B0); PG8_MMA(1, 1, At, B1); PG8_BAR; PG8_SCHED;
;             PG8_LDB(B0, 1, 0); PG8_LDB(B1, 1, 1); PG8_SCHED; PG8_LDA(At, 1, 0); PG8_STAGE(PG8_SA(0, 1), a2 + hstepA, voffA);
;             PG8_WAIT_V(8); PG8_WAIT_L(0); PG8_BAR; PG8_MMA(0, 0, At, B0); PG8_MMA(0, 1, At, B1); PG8_BAR; PG8_SCHED;
	s_setprio 1
	s_waitcnt lgkmcnt(0)
	v_mfma_f32_16x16x32_bf16 v[60:63], v[146:149], v[186:189], v[60:63]
	v_mfma_f32_16x16x32_bf16 v[56:59], v[162:165], v[186:189], v[56:59]
	v_mfma_f32_16x16x32_bf16 v[44:47], v[146:149], v[194:197], v[44:47]
	v_mfma_f32_16x16x32_bf16 v[40:43], v[162:165], v[194:197], v[40:43]
	v_mfma_f32_16x16x32_bf16 v[28:31], v[146:149], v[202:205], v[28:31]
	v_mfma_f32_16x16x32_bf16 v[24:27], v[162:165], v[202:205], v[24:27]
	v_mfma_f32_16x16x32_bf16 v[12:15], v[146:149], v[210:213], v[12:15]
	v_mfma_f32_16x16x32_bf16 v[8:11], v[162:165], v[210:213], v[8:11]
	v_mfma_f32_16x16x32_bf16 v[60:63], v[158:161], v[190:193], v[60:63]
	v_mfma_f32_16x16x32_bf16 v[56:59], v[166:169], v[190:193], v[56:59]
	v_mfma_f32_16x16x32_bf16 v[44:47], v[158:161], v[198:201], v[44:47]
	v_mfma_f32_16x16x32_bf16 v[40:43], v[166:169], v[198:201], v[40:43]
	v_mfma_f32_16x16x32_bf16 v[28:31], v[158:161], v[206:209], v[28:31]
	v_mfma_f32_16x16x32_bf16 v[24:27], v[166:169], v[206:209], v[24:27]
	v_mfma_f32_16x16x32_bf16 v[12:15], v[158:161], v[214:217], v[12:15]
	v_mfma_f32_16x16x32_bf16 v[8:11], v[166:169], v[214:217], v[8:11]
	s_setprio 0
	s_setprio 1
	v_mfma_f32_16x16x32_bf16 v[52:55], v[170:173], v[186:189], v[52:55]
	v_mfma_f32_16x16x32_bf16 v[48:51], v[178:181], v[186:189], v[48:51]
	v_mfma_f32_16x16x32_bf16 v[36:39], v[170:173], v[194:197], v[36:39]
	v_mfma_f32_16x16x32_bf16 v[32:35], v[178:181], v[194:197], v[32:35]
	v_mfma_f32_16x16x32_bf16 v[20:23], v[170:173], v[202:205], v[20:23]
	v_mfma_f32_16x16x32_bf16 v[16:19], v[178:181], v[202:205], v[16:19]
	v_mfma_f32_16x16x32_bf16 v[4:7], v[170:173], v[210:213], v[4:7]
	v_mfma_f32_16x16x32_bf16 v[0:3], v[178:181], v[210:213], v[0:3]
	v_mfma_f32_16x16x32_bf16 v[52:55], v[174:177], v[190:193], v[52:55]
	v_mfma_f32_16x16x32_bf16 v[48:51], v[182:185], v[190:193], v[48:51]
	v_mfma_f32_16x16x32_bf16 v[36:39], v[174:177], v[198:201], v[36:39]
	v_mfma_f32_16x16x32_bf16 v[32:35], v[182:185], v[198:201], v[32:35]
	v_mfma_f32_16x16x32_bf16 v[20:23], v[174:177], v[206:209], v[20:23]
	v_mfma_f32_16x16x32_bf16 v[16:19], v[182:185], v[206:209], v[16:19]
	v_mfma_f32_16x16x32_bf16 v[4:7], v[174:177], v[214:217], v[4:7]
	v_mfma_f32_16x16x32_bf16 v[0:3], v[182:185], v[214:217], v[0:3]
	s_setprio 0
	s_barrier
	s_add_i32 s53, 0, 0x18000
	v_add_u32_e32 v136, s53, v151
	s_add_i32 s93, 0, 0x1c000
	ds_read_b128 v[146:149], v136
	ds_read_b128 v[158:161], v136 offset:1024
	ds_read_b128 v[162:165], v136 offset:2048
	ds_read_b128 v[166:169], v136 offset:3072
	v_add_u32_e32 v136, s93, v151
	ds_read_b128 v[170:173], v136
	ds_read_b128 v[174:177], v136 offset:1024
	ds_read_b128 v[178:181], v136 offset:2048
	ds_read_b128 v[182:185], v136 offset:3072
	s_add_u32 s42, s42, 0x40000
	s_addc_u32 s43, s43, 0
	s_mov_b32 m0, s64
	v_lshl_add_u64 v[222:223], s[42:43], 0, v[130:131]
	ds_read_b128 v[186:189], v156 offset:32768
	ds_read_b128 v[190:193], v156 offset:33792
	ds_read_b128 v[194:197], v156 offset:34816
	ds_read_b128 v[198:201], v156 offset:35840
	ds_read_b128 v[202:205], v156 offset:36864
	ds_read_b128 v[206:209], v156 offset:37888
	ds_read_b128 v[210:213], v156 offset:38912
	ds_read_b128 v[214:217], v156 offset:39936
	global_load_lds_dwordx4 v[222:223], off
	v_lshl_add_u64 v[222:223], s[42:43], 0, v[134:135]
	s_mov_b32 m0, s65
	s_nop 0
	global_load_lds_dwordx4 v[222:223], off
	s_waitcnt vmcnt(8)
	s_waitcnt lgkmcnt(0)
	s_barrier
	s_setprio 1
	s_waitcnt lgkmcnt(0)
	v_mfma_f32_16x16x32_bf16 v[124:127], v[146:149], v[186:189], v[124:127]
	v_mfma_f32_16x16x32_bf16 v[120:123], v[162:165], v[186:189], v[120:123]
	v_mfma_f32_16x16x32_bf16 v[108:111], v[146:149], v[194:197], v[108:111]
	v_mfma_f32_16x16x32_bf16 v[104:107], v[162:165], v[194:197], v[104:107]
	v_mfma_f32_16x16x32_bf16 v[92:95], v[146:149], v[202:205], v[92:95]
	v_mfma_f32_16x16x32_bf16 v[88:91], v[162:165], v[202:205], v[88:91]
	v_mfma_f32_16x16x32_bf16 v[76:79], v[146:149], v[210:213], v[76:79]
	v_mfma_f32_16x16x32_bf16 v[72:75], v[162:165], v[210:213], v[72:75]
	v_mfma_f32_16x16x32_bf16 v[124:127], v[158:161], v[190:193], v[124:127]
	v_mfma_f32_16x16x32_bf16 v[120:123], v[166:169], v[190:193], v[120:123]
	v_mfma_f32_16x16x32_bf16 v[108:111], v[158:161], v[198:201], v[108:111]
	v_mfma_f32_16x16x32_bf16 v[104:107], v[166:169], v[198:201], v[104:107]
	v_mfma_f32_16x16x32_bf16 v[92:95], v[158:161], v[206:209], v[92:95]
	v_mfma_f32_16x16x32_bf16 v[88:91], v[166:169], v[206:209], v[88:91]
	v_mfma_f32_16x16x32_bf16 v[76:79], v[158:161], v[214:217], v[76:79]
	v_mfma_f32_16x16x32_bf16 v[72:75], v[166:169], v[214:217], v[72:75]
	s_setprio 0
	s_setprio 1
	v_mfma_f32_16x16x32_bf16 v[116:119], v[170:173], v[186:189], v[116:119]
	v_mfma_f32_16x16x32_bf16 v[112:115], v[178:181], v[186:189], v[112:115]
	v_mfma_f32_16x16x32_bf16 v[100:103], v[170:173], v[194:197], v[100:103]
	v_mfma_f32_16x16x32_bf16 v[96:99], v[178:181], v[194:197], v[96:99]
	v_mfma_f32_16x16x32_bf16 v[84:87], v[170:173], v[202:205], v[84:87]
	v_mfma_f32_16x16x32_bf16 v[80:83], v[178:181], v[202:205], v[80:83]
	v_mfma_f32_16x16x32_bf16 v[68:71], v[170:173], v[210:213], v[68:71]
	v_mfma_f32_16x16x32_bf16 v[64:67], v[178:181], v[210:213], v[64:67]
	v_mfma_f32_16x16x32_bf16 v[116:119], v[174:177], v[190:193], v[116:119]
	v_mfma_f32_16x16x32_bf16 v[112:115], v[182:185], v[190:193], v[112:115]
	v_mfma_f32_16x16x32_bf16 v[100:103], v[174:177], v[198:201], v[100:103]
	v_mfma_f32_16x16x32_bf16 v[96:99], v[182:185], v[198:201], v[96:99]
	v_mfma_f32_16x16x32_bf16 v[84:87], v[174:177], v[206:209], v[84:87]
	v_mfma_f32_16x16x32_bf16 v[80:83], v[182:185], v[206:209], v[80:83]
	v_mfma_f32_16x16x32_bf16 v[68:71], v[174:177], v[214:217], v[68:71]
	v_mfma_f32_16x16x32_bf16 v[64:67], v[182:185], v[214:217], v[64:67]
	s_setprio 0
	s_barrier
; #define PG8_STAGE(bufoff, gbase, voff) do { _Pragma("unroll") for (int _i = 0; _i < 2; ++_i) \
;         __builtin_amdgcn_global_load_lds((const unsigned*)((const char*)(gbase) + (voff)[_i]), (LAS unsigned*)(lds + (bufoff) + ldsw + _i * 8192), 16, 0, 0); } while (0)
; #define PG8_LDA(dst, b, h) do { _Pragma("unroll") for (int m = 0; m < 4; ++m) _Pragma("unroll") for (int k = 0; k < 2; ++k) dst[m][k] = *(const LAS bf16x8*)(lds + PG8_SA(b, h) + aoff + m * 2048 + k * 1024); } while (0)
; #define PG8_MMA(ai, bj, At, Bt) do { __builtin_amdgcn_s_setprio(1); _Pragma("unroll") for (int m = 0; m < 4; ++m) _Pragma("unroll") for (int n = 0; n < 2; ++n) _Pragma("unroll") for (int k = 0; k < 2; ++k) \
;         acc[ai][bj][m][n] = __builtin_amdgcn_mfma_f32_16x16x32_bf16(Bt[n][k], At[m][k], acc[ai][bj][m][n], 0, 0, 0); __builtin_amdgcn_s_setprio(0); } while (0)
; #define PG8_WAIT_V(n) asm volatile("s_waitcnt vmcnt(" #n ")" ::: "memory")
; #define PG8_WAIT_L(n) asm volatile("s_waitcnt lgkmcnt(" #n ")" ::: "memory")
; #define PG8_BAR __builtin_amdgcn_s_barrier()
; #define PG8_SCHED __builtin_amdgcn_sched_barrier(0)
; template <class Epi, bool HALO>
; __device__ __forceinline__ void gemm_phase(LAS unsigned char* lds, const Gemm g, const StaticOrder& S, const Epi& E) {
;     ...
;             PG8_LDA(At, 1, 1); PG8_STAGE(PG8_SB(1, 0), b3, voffB); PG8_STAGE(PG8_SB(1, 1), b3 + hstepB, voffB); PG8_STAGE(PG8_SA(1, 0), a3, voffA);
;             PG8_WAIT_V(8); PG8_WAIT_L(0); PG8_BAR; PG8_MMA(1, 0, At, B0); PG8_MMA(1, 1, At, B1); PG8_BAR; PG8_SCHED;
;         }
;         if (wr == 0) PG8_BAR;
	s_add_u32 s42, s40, 0x8000
	s_addc_u32 s43, s41, 0
	s_add_i32 s53, s53, s59
	v_lshl_add_u64 v[222:223], s[42:43], 0, v[128:129]
	s_mov_b32 m0, s53
	ds_read_b128 v[186:189], v156 offset:49152
	ds_read_b128 v[190:193], v156 offset:50176
	ds_read_b128 v[194:197], v156 offset:51200
	ds_read_b128 v[198:201], v156 offset:52224
	ds_read_b128 v[202:205], v156 offset:53248
	ds_read_b128 v[206:209], v156 offset:54272
	ds_read_b128 v[210:213], v156 offset:55296
	ds_read_b128 v[214:217], v156 offset:56320
	global_load_lds_dwordx4 v[222:223], off
	s_add_i32 m0, s53, 0x2000
	s_add_u32 s40, s40, 0xc000
	v_lshl_add_u64 v[222:223], s[42:43], 0, v[132:133]
	s_addc_u32 s41, s41, 0
	s_add_i32 s42, s93, s59
	global_load_lds_dwordx4 v[222:223], off
	v_lshl_add_u64 v[222:223], s[40:41], 0, v[128:129]
	s_mov_b32 m0, s42
	v_lshl_add_u64 v[152:153], v[152:153], 0, s[26:27]
	global_load_lds_dwordx4 v[222:223], off
	v_lshl_add_u64 v[222:223], s[40:41], 0, v[132:133]
	s_add_i32 m0, s42, 0x2000
	s_nop 0
	global_load_lds_dwordx4 v[222:223], off
	s_mov_b32 m0, s71
	s_nop 0
	global_load_lds_dwordx4 v[152:153], off
	v_lshl_add_u64 v[152:153], v[218:219], 0, s[26:27]
	s_mov_b32 m0, s76
	s_nop 0
	global_load_lds_dwordx4 v[152:153], off
	s_waitcnt vmcnt(8)
	s_waitcnt lgkmcnt(0)
	s_barrier
	s_setprio 1
	s_waitcnt lgkmcnt(0)
	v_mfma_f32_16x16x32_bf16 v[60:63], v[146:149], v[186:189], v[60:63]
	v_mfma_f32_16x16x32_bf16 v[56:59], v[162:165], v[186:189], v[56:59]
	v_mfma_f32_16x16x32_bf16 v[44:47], v[146:149], v[194:197], v[44:47]
	v_mfma_f32_16x16x32_bf16 v[40:43], v[162:165], v[194:197], v[40:43]
	v_mfma_f32_16x16x32_bf16 v[28:31], v[146:149], v[202:205], v[28:31]
	v_mfma_f32_16x16x32_bf16 v[24:27], v[162:165], v[202:205], v[24:27]
	v_mfma_f32_16x16x32_bf16 v[12:15], v[146:149], v[210:213], v[12:15]
	v_mfma_f32_16x16x32_bf16 v[8:11], v[162:165], v[210:213], v[8:11]
	v_mfma_f32_16x16x32_bf16 v[60:63], v[158:161], v[190:193], v[60:63]
	v_mfma_f32_16x16x32_bf16 v[56:59], v[166:169], v[190:193], v[56:59]
	v_mfma_f32_16x16x32_bf16 v[44:47], v[158:161], v[198:201], v[44:47]
	v_mfma_f32_16x16x32_bf16 v[40:43], v[166:169], v[198:201], v[40:43]
	v_mfma_f32_16x16x32_bf16 v[28:31], v[158:161], v[206:209], v[28:31]
	v_mfma_f32_16x16x32_bf16 v[24:27], v[166:169], v[206:209], v[24:27]
	v_mfma_f32_16x16x32_bf16 v[12:15], v[158:161], v[214:217], v[12:15]
	v_mfma_f32_16x16x32_bf16 v[8:11], v[166:169], v[214:217], v[8:11]
	s_setprio 0
	s_setprio 1
	v_mfma_f32_16x16x32_bf16 v[52:55], v[170:173], v[186:189], v[52:55]
	v_mfma_f32_16x16x32_bf16 v[48:51], v[178:181], v[186:189], v[48:51]
	v_mfma_f32_16x16x32_bf16 v[36:39], v[170:173], v[194:197], v[36:39]
	v_mfma_f32_16x16x32_bf16 v[32:35], v[178:181], v[194:197], v[32:35]
	v_mfma_f32_16x16x32_bf16 v[20:23], v[170:173], v[202:205], v[20:23]
	v_mfma_f32_16x16x32_bf16 v[16:19], v[178:181], v[202:205], v[16:19]
	v_mfma_f32_16x16x32_bf16 v[4:7], v[170:173], v[210:213], v[4:7]
	v_mfma_f32_16x16x32_bf16 v[0:3], v[178:181], v[210:213], v[0:3]
	v_mfma_f32_16x16x32_bf16 v[52:55], v[174:177], v[190:193], v[52:55]
	v_mfma_f32_16x16x32_bf16 v[48:51], v[182:185], v[190:193], v[48:51]
	v_mfma_f32_16x16x32_bf16 v[36:39], v[174:177], v[198:201], v[36:39]
	v_mfma_f32_16x16x32_bf16 v[32:35], v[182:185], v[198:201], v[32:35]
	v_mfma_f32_16x16x32_bf16 v[20:23], v[174:177], v[206:209], v[20:23]
	v_mfma_f32_16x16x32_bf16 v[16:19], v[182:185], v[206:209], v[16:19]
	s_add_i32 s52, s52, 2
	s_add_u32 s50, s50, 0x10000
	s_addc_u32 s51, s51, 0
	s_add_u32 s12, s12, 0x100
	s_addc_u32 s13, s13, 0
	s_cmp_gt_u32 s52, 13
	v_mfma_f32_16x16x32_bf16 v[4:7], v[174:177], v[214:217], v[4:7]
	v_mfma_f32_16x16x32_bf16 v[0:3], v[182:185], v[214:217], v[0:3]
	s_setprio 0
	s_barrier
	s_cbranch_scc0 .LBB0_824
	s_and_b64 vcc, exec, s[28:29]
	s_cbranch_vccz .LBB0_827
	s_barrier

; #define PG8_STAGE(bufoff, gbase, voff) do { _Pragma("unroll") for (int _i = 0; _i < 2; ++_i) \
;         __builtin_amdgcn_global_load_lds((const unsigned*)((const char*)(gbase) + (voff)[_i]), (LAS unsigned*)(lds + (bufoff) + ldsw + _i * 8192), 16, 0, 0); } while (0)
; #define PG8_LDA(dst, b, h) do { _Pragma("unroll") for (int m = 0; m < 4; ++m) _Pragma("unroll") for (int k = 0; k < 2; ++k) dst[m][k] = *(const LAS bf16x8*)(lds + PG8_SA(b, h) + aoff + m * 2048 + k * 1024); } while (0)
; #define PG8_LDB(dst, b, h) do { _Pragma("unroll") for (int n = 0; n < 2; ++n) _Pragma("unroll") for (int k = 0; k < 2; ++k) dst[n][k] = *(const LAS bf16x8*)(lds + PG8_SB(b, h) + boff + n * 2048 + k * 1024); } while (0)
; #define PG8_MMA(ai, bj, At, Bt) do { __builtin_amdgcn_s_setprio(1); _Pragma("unroll") for (int m = 0; m < 4; ++m) _Pragma("unroll") for (int n = 0; n < 2; ++n) _Pragma("unroll") for (int k = 0; k < 2; ++k) \
;         acc[ai][bj][m][n] = __builtin_amdgcn_mfma_f32_16x16x32_bf16(Bt[n][k], At[m][k], acc[ai][bj][m][n], 0, 0, 0); __builtin_amdgcn_s_setprio(0); } while (0)
; #define PG8_WAIT_V(n) asm volatile("s_waitcnt vmcnt(" #n ")" ::: "memory")
; #define PG8_WAIT_L(n) asm volatile("s_waitcnt lgkmcnt(" #n ")" ::: "memory")
; #define PG8_BAR __builtin_amdgcn_s_barrier()
; #define PG8_SCHED __builtin_amdgcn_sched_barrier(0)
; template <class Epi, bool HALO>
; __device__ __forceinline__ void gemm_phase(LAS unsigned char* lds, const Gemm g, const StaticOrder& S, const Epi& E) {
;     ...
;         for (int t = 0; t < nt; t += 2) {
;             const bool last = (t == nt - 2);
;             const char* a1 = cA + (size_t)(t + 1) * kstep;
;             const char* a2 = last ? nA : cA + (size_t)(t + 2) * kstep; const char* b2 = last ? nB : cB + (size_t)(t + 2) * kstepB;
;             const char* a3 = a2 + kstep; const char* b3 = b2 + kstepB;
;             PG8_LDB(B0, 0, 0); PG8_LDB(B1, 0, 1); PG8_SCHED; PG8_LDA(At, 0, 0); PG8_STAGE(PG8_SA(1, 1), a1 + hstepA, voffA);
;             PG8_WAIT_V(8); PG8_WAIT_L(0); PG8_BAR; PG8_MMA(0, 0, At, B0); PG8_MMA(0, 1, At, B1); PG8_BAR; PG8_SCHED;
;             PG8_LDA(At, 0, 1); PG8_STAGE(PG8_SB(0, 0), b2, voffB); PG8_STAGE(PG8_SB(0, 1), b2 + hstepB, voffB); PG8_STAGE(PG8_SA(0, 0), a2, voffA);
.LBB0_1181:
	ds_read_b128 v[154:157], v149
	ds_read_b128 v[158:161], v149 offset:1024
	ds_read_b128 v[162:165], v149 offset:2048
	ds_read_b128 v[166:169], v149 offset:3072
	ds_read_b128 v[170:173], v150
	ds_read_b128 v[174:177], v150 offset:1024
	ds_read_b128 v[178:181], v150 offset:2048
	ds_read_b128 v[182:185], v150 offset:3072
	s_add_u32 s36, s34, 0xfffc0080
	s_addc_u32 s37, s35, -1
	s_cmp_eq_u32 s60, 12
	s_cselect_b32 s39, s23, s37
	s_cselect_b32 s38, s29, s36
	s_cselect_b32 s37, s21, s59
	s_cselect_b32 s36, s31, s58
	v_lshl_add_u64 v[146:147], s[34:35], 0, v[138:139]
	s_add_i32 m0, s46, 0xc000
	ds_read_b128 v[186:189], v151
	ds_read_b128 v[190:193], v151 offset:1024
	ds_read_b128 v[194:197], v151 offset:2048
	ds_read_b128 v[198:201], v151 offset:3072
	ds_read_b128 v[202:205], v151 offset:4096
	ds_read_b128 v[206:209], v151 offset:5120
	ds_read_b128 v[210:213], v151 offset:6144
	ds_read_b128 v[214:217], v151 offset:7168
	global_load_lds_dwordx4 v[146:147], off
	v_lshl_add_u64 v[146:147], s[34:35], 0, v[140:141]
	s_add_i32 m0, s46, 0xe000
	s_nop 0
	global_load_lds_dwordx4 v[146:147], off
	s_waitcnt vmcnt(8)
	s_waitcnt lgkmcnt(0)
	s_barrier
	s_setprio 1
	s_waitcnt lgkmcnt(0)
	v_mfma_f32_16x16x32_bf16 v[124:127], v[154:157], v[186:189], v[124:127]
	v_mfma_f32_16x16x32_bf16 v[120:123], v[162:165], v[186:189], v[120:123]
	v_mfma_f32_16x16x32_bf16 v[108:111], v[154:157], v[194:197], v[108:111]
	v_mfma_f32_16x16x32_bf16 v[104:107], v[162:165], v[194:197], v[104:107]
	v_mfma_f32_16x16x32_bf16 v[92:95], v[154:157], v[202:205], v[92:95]
	v_mfma_f32_16x16x32_bf16 v[88:91], v[162:165], v[202:205], v[88:91]
	v_mfma_f32_16x16x32_bf16 v[76:79], v[154:157], v[210:213], v[76:79]
	v_mfma_f32_16x16x32_bf16 v[72:75], v[162:165], v[210:213], v[72:75]
	v_mfma_f32_16x16x32_bf16 v[124:127], v[158:161], v[190:193], v[124:127]
	v_mfma_f32_16x16x32_bf16 v[120:123], v[166:169], v[190:193], v[120:123]
	v_mfma_f32_16x16x32_bf16 v[108:111], v[158:161], v[198:201], v[108:111]
	v_mfma_f32_16x16x32_bf16 v[104:107], v[166:169], v[198:201], v[104:107]
	v_mfma_f32_16x16x32_bf16 v[92:95], v[158:161], v[206:209], v[92:95]
	v_mfma_f32_16x16x32_bf16 v[88:91], v[166:169], v[206:209], v[88:91]
	v_mfma_f32_16x16x32_bf16 v[76:79], v[158:161], v[214:217], v[76:79]
	v_mfma_f32_16x16x32_bf16 v[72:75], v[166:169], v[214:217], v[72:75]
	s_setprio 0
	s_setprio 1
	v_mfma_f32_16x16x32_bf16 v[116:119], v[170:173], v[186:189], v[116:119]
	v_mfma_f32_16x16x32_bf16 v[112:115], v[178:181], v[186:189], v[112:115]
	v_mfma_f32_16x16x32_bf16 v[100:103], v[170:173], v[194:197], v[100:103]
	v_mfma_f32_16x16x32_bf16 v[96:99], v[178:181], v[194:197], v[96:99]
	v_mfma_f32_16x16x32_bf16 v[84:87], v[170:173], v[202:205], v[84:87]
	v_mfma_f32_16x16x32_bf16 v[80:83], v[178:181], v[202:205], v[80:83]
	v_mfma_f32_16x16x32_bf16 v[68:71], v[170:173], v[210:213], v[68:71]
	v_mfma_f32_16x16x32_bf16 v[64:67], v[178:181], v[210:213], v[64:67]
	v_mfma_f32_16x16x32_bf16 v[116:119], v[174:177], v[190:193], v[116:119]
	v_mfma_f32_16x16x32_bf16 v[112:115], v[182:185], v[190:193], v[112:115]
	v_mfma_f32_16x16x32_bf16 v[100:103], v[174:177], v[198:201], v[100:103]
	v_mfma_f32_16x16x32_bf16 v[96:99], v[182:185], v[198:201], v[96:99]
	v_mfma_f32_16x16x32_bf16 v[84:87], v[174:177], v[206:209], v[84:87]
	v_mfma_f32_16x16x32_bf16 v[80:83], v[182:185], v[206:209], v[80:83]
	v_mfma_f32_16x16x32_bf16 v[68:71], v[174:177], v[214:217], v[68:71]
	v_mfma_f32_16x16x32_bf16 v[64:67], v[182:185], v[214:217], v[64:67]
	s_setprio 0
	s_barrier
	s_add_i32 s61, s56, s45
	v_lshl_add_u64 v[146:147], s[36:37], 0, v[128:129]
	s_mov_b32 m0, s61
	ds_read_b128 v[186:189], v151 offset:16384
	ds_read_b128 v[190:193], v151 offset:17408
	ds_read_b128 v[194:197], v151 offset:18432
	ds_read_b128 v[198:201], v151 offset:19456
	ds_read_b128 v[202:205], v151 offset:20480
	ds_read_b128 v[206:209], v151 offset:21504
	ds_read_b128 v[210:213], v151 offset:22528
	ds_read_b128 v[214:217], v151 offset:23552
	global_load_lds_dwordx4 v[146:147], off
	s_add_i32 m0, s61, 0x2000
	s_add_u32 s62, s36, 0x4000
	v_lshl_add_u64 v[146:147], s[36:37], 0, v[132:133]
	s_addc_u32 s63, s37, 0
	s_add_i32 s61, s57, s45
	global_load_lds_dwordx4 v[146:147], off
	v_lshl_add_u64 v[146:147], s[62:63], 0, v[128:129]
	s_mov_b32 m0, s61
	v_lshl_add_u64 v[218:219], s[38:39], 0, v[134:135]
	global_load_lds_dwordx4 v[146:147], off
	v_lshl_add_u64 v[146:147], s[62:63], 0, v[132:133]
	s_add_i32 m0, s61, 0x2000
	s_nop 0
	global_load_lds_dwordx4 v[146:147], off
	v_lshl_add_u64 v[146:147], s[38:39], 0, v[130:131]
	s_mov_b32 m0, s46
	s_nop 0
	global_load_lds_dwordx4 v[146:147], off
	s_mov_b32 m0, s47
	s_nop 0
	global_load_lds_dwordx4 v[218:219], off
	s_waitcnt vmcnt(8)
	s_waitcnt lgkmcnt(0)
	s_barrier
; #define PG8_STAGE(bufoff, gbase, voff) do { _Pragma("unroll") for (int _i = 0; _i < 2; ++_i) \
;         __builtin_amdgcn_global_load_lds((const unsigned*)((const char*)(gbase) + (voff)[_i]), (LAS unsigned*)(lds + (bufoff) + ldsw + _i * 8192), 16, 0, 0); } while (0)
; #define PG8_LDA(dst, b, h) do { _Pragma("unroll") for (int m = 0; m < 4; ++m) _Pragma("unroll") for (int k = 0; k < 2; ++k) dst[m][k] = *(const LAS bf16x8*)(lds + PG8_SA(b, h) + aoff + m * 2048 + k * 1024); } while (0)
; #define PG8_LDB(dst, b, h) do { _Pragma("unroll") for (int n = 0; n < 2; ++n) _Pragma("unroll") for (int k = 0; k < 2; ++k) dst[n][k] = *(const LAS bf16x8*)(lds + PG8_SB(b, h) + boff + n * 2048 + k * 1024); } while (0)
; #define PG8_MMA(ai, bj, At, Bt) do { __builtin_amdgcn_s_setprio(1); _Pragma("unroll") for (int m = 0; m < 4; ++m) _Pragma("unroll") for (int n = 0; n < 2; ++n) _Pragma("unroll") for (int k = 0; k < 2; ++k) \
;         acc[ai][bj][m][n] = __builtin_amdgcn_mfma_f32_16x16x32_bf16(Bt[n][k], At[m][k], acc[ai][bj][m][n], 0, 0, 0); __builtin_amdgcn_s_setprio(0); } while (0)
; #define PG8_WAIT_V(n) asm volatile("s_waitcnt vmcnt(" #n ")" ::: "memory")
; #define PG8_WAIT_L(n) asm volatile("s_waitcnt lgkmcnt(" #n ")" ::: "memory")
; #define PG8_BAR __builtin_amdgcn_s_barrier()
; #define PG8_SCHED __builtin_amdgcn_sched_barrier(0)
; template <class Epi, bool HALO>
; __device__ __forceinline__ void gemm_phase(LAS unsigned char* lds, const Gemm g, const StaticOrder& S, const Epi& E) {
;     ...
;             PG8_WAIT_V(8); PG8_WAIT_L(0); PG8_BAR; PG8_MMA(1, 0, At, B0); PG8_MMA(1, 1, At, B1); PG8_BAR; PG8_SCHED;
;             PG8_LDB(B0, 1, 0); PG8_LDB(B1, 1, 1); PG8_SCHED; PG8_LDA(At, 1, 0); PG8_STAGE(PG8_SA(0, 1), a2 + hstepA, voffA);
;             PG8_WAIT_V(8); PG8_WAIT_L(0); PG8_BAR; PG8_MMA(0, 0, At, B0); PG8_MMA(0, 1, At, B1); PG8_BAR; PG8_SCHED;
	s_setprio 1
	s_waitcnt lgkmcnt(0)
	v_mfma_f32_16x16x32_bf16 v[60:63], v[154:157], v[186:189], v[60:63]
	v_mfma_f32_16x16x32_bf16 v[56:59], v[162:165], v[186:189], v[56:59]
	v_mfma_f32_16x16x32_bf16 v[44:47], v[154:157], v[194:197], v[44:47]
	v_mfma_f32_16x16x32_bf16 v[40:43], v[162:165], v[194:197], v[40:43]
	v_mfma_f32_16x16x32_bf16 v[28:31], v[154:157], v[202:205], v[28:31]
	v_mfma_f32_16x16x32_bf16 v[24:27], v[162:165], v[202:205], v[24:27]
	v_mfma_f32_16x16x32_bf16 v[12:15], v[154:157], v[210:213], v[12:15]
	v_mfma_f32_16x16x32_bf16 v[8:11], v[162:165], v[210:213], v[8:11]
	v_mfma_f32_16x16x32_bf16 v[60:63], v[158:161], v[190:193], v[60:63]
	v_mfma_f32_16x16x32_bf16 v[56:59], v[166:169], v[190:193], v[56:59]
	v_mfma_f32_16x16x32_bf16 v[44:47], v[158:161], v[198:201], v[44:47]
	v_mfma_f32_16x16x32_bf16 v[40:43], v[166:169], v[198:201], v[40:43]
	v_mfma_f32_16x16x32_bf16 v[28:31], v[158:161], v[206:209], v[28:31]
	v_mfma_f32_16x16x32_bf16 v[24:27], v[166:169], v[206:209], v[24:27]
	v_mfma_f32_16x16x32_bf16 v[12:15], v[158:161], v[214:217], v[12:15]
	v_mfma_f32_16x16x32_bf16 v[8:11], v[166:169], v[214:217], v[8:11]
	s_setprio 0
	s_setprio 1
	v_mfma_f32_16x16x32_bf16 v[52:55], v[170:173], v[186:189], v[52:55]
	v_mfma_f32_16x16x32_bf16 v[48:51], v[178:181], v[186:189], v[48:51]
	v_mfma_f32_16x16x32_bf16 v[36:39], v[170:173], v[194:197], v[36:39]
	v_mfma_f32_16x16x32_bf16 v[32:35], v[178:181], v[194:197], v[32:35]
	v_mfma_f32_16x16x32_bf16 v[20:23], v[170:173], v[202:205], v[20:23]
	v_mfma_f32_16x16x32_bf16 v[16:19], v[178:181], v[202:205], v[16:19]
	v_mfma_f32_16x16x32_bf16 v[4:7], v[170:173], v[210:213], v[4:7]
	v_mfma_f32_16x16x32_bf16 v[0:3], v[178:181], v[210:213], v[0:3]
	v_mfma_f32_16x16x32_bf16 v[52:55], v[174:177], v[190:193], v[52:55]
	v_mfma_f32_16x16x32_bf16 v[48:51], v[182:185], v[190:193], v[48:51]
	v_mfma_f32_16x16x32_bf16 v[36:39], v[174:177], v[198:201], v[36:39]
	v_mfma_f32_16x16x32_bf16 v[32:35], v[182:185], v[198:201], v[32:35]
	v_mfma_f32_16x16x32_bf16 v[20:23], v[174:177], v[206:209], v[20:23]
	v_mfma_f32_16x16x32_bf16 v[16:19], v[182:185], v[206:209], v[16:19]
	v_mfma_f32_16x16x32_bf16 v[4:7], v[174:177], v[214:217], v[4:7]
	v_mfma_f32_16x16x32_bf16 v[0:3], v[182:185], v[214:217], v[0:3]
	s_setprio 0
	s_barrier
	s_add_i32 s61, 0, 0x18000
	v_add_u32_e32 v136, s61, v148
	s_add_i32 s62, 0, 0x1c000
	ds_read_b128 v[154:157], v136
	ds_read_b128 v[158:161], v136 offset:1024
	ds_read_b128 v[162:165], v136 offset:2048
	ds_read_b128 v[166:169], v136 offset:3072
	v_add_u32_e32 v136, s62, v148
	ds_read_b128 v[170:173], v136
	ds_read_b128 v[174:177], v136 offset:1024
	ds_read_b128 v[178:181], v136 offset:2048
	ds_read_b128 v[182:185], v136 offset:3072
	s_add_u32 s38, s38, 0x40000
	s_addc_u32 s39, s39, 0
	s_mov_b32 m0, s48
	v_lshl_add_u64 v[222:223], s[38:39], 0, v[130:131]
	ds_read_b128 v[186:189], v151 offset:32768
	ds_read_b128 v[190:193], v151 offset:33792
	ds_read_b128 v[194:197], v151 offset:34816
	ds_read_b128 v[198:201], v151 offset:35840
	ds_read_b128 v[202:205], v151 offset:36864
	ds_read_b128 v[206:209], v151 offset:37888
	ds_read_b128 v[210:213], v151 offset:38912
	ds_read_b128 v[214:217], v151 offset:39936
	global_load_lds_dwordx4 v[222:223], off
	v_lshl_add_u64 v[222:223], s[38:39], 0, v[134:135]
	s_mov_b32 m0, s49
	s_nop 0
	global_load_lds_dwordx4 v[222:223], off
	s_waitcnt vmcnt(8)
	s_waitcnt lgkmcnt(0)
	s_barrier
	s_setprio 1
	s_waitcnt lgkmcnt(0)
	v_mfma_f32_16x16x32_bf16 v[124:127], v[154:157], v[186:189], v[124:127]
	v_mfma_f32_16x16x32_bf16 v[120:123], v[162:165], v[186:189], v[120:123]
	v_mfma_f32_16x16x32_bf16 v[108:111], v[154:157], v[194:197], v[108:111]
	v_mfma_f32_16x16x32_bf16 v[104:107], v[162:165], v[194:197], v[104:107]
	v_mfma_f32_16x16x32_bf16 v[92:95], v[154:157], v[202:205], v[92:95]
	v_mfma_f32_16x16x32_bf16 v[88:91], v[162:165], v[202:205], v[88:91]
	v_mfma_f32_16x16x32_bf16 v[76:79], v[154:157], v[210:213], v[76:79]
	v_mfma_f32_16x16x32_bf16 v[72:75], v[162:165], v[210:213], v[72:75]
	v_mfma_f32_16x16x32_bf16 v[124:127], v[158:161], v[190:193], v[124:127]
	v_mfma_f32_16x16x32_bf16 v[120:123], v[166:169], v[190:193], v[120:123]
	v_mfma_f32_16x16x32_bf16 v[108:111], v[158:161], v[198:201], v[108:111]
	v_mfma_f32_16x16x32_bf16 v[104:107], v[166:169], v[198:201], v[104:107]
	v_mfma_f32_16x16x32_bf16 v[92:95], v[158:161], v[206:209], v[92:95]
	v_mfma_f32_16x16x32_bf16 v[88:91], v[166:169], v[206:209], v[88:91]
	v_mfma_f32_16x16x32_bf16 v[76:79], v[158:161], v[214:217], v[76:79]
	v_mfma_f32_16x16x32_bf16 v[72:75], v[166:169], v[214:217], v[72:75]
	s_setprio 0
	s_setprio 1
	v_mfma_f32_16x16x32_bf16 v[116:119], v[170:173], v[186:189], v[116:119]
	v_mfma_f32_16x16x32_bf16 v[112:115], v[178:181], v[186:189], v[112:115]
	v_mfma_f32_16x16x32_bf16 v[100:103], v[170:173], v[194:197], v[100:103]
	v_mfma_f32_16x16x32_bf16 v[96:99], v[178:181], v[194:197], v[96:99]
	v_mfma_f32_16x16x32_bf16 v[84:87], v[170:173], v[202:205], v[84:87]
	v_mfma_f32_16x16x32_bf16 v[80:83], v[178:181], v[202:205], v[80:83]
	v_mfma_f32_16x16x32_bf16 v[68:71], v[170:173], v[210:213], v[68:71]
	v_mfma_f32_16x16x32_bf16 v[64:67], v[178:181], v[210:213], v[64:67]
	v_mfma_f32_16x16x32_bf16 v[116:119], v[174:177], v[190:193], v[116:119]
	v_mfma_f32_16x16x32_bf16 v[112:115], v[182:185], v[190:193], v[112:115]
	v_mfma_f32_16x16x32_bf16 v[100:103], v[174:177], v[198:201], v[100:103]
	v_mfma_f32_16x16x32_bf16 v[96:99], v[182:185], v[198:201], v[96:99]
	v_mfma_f32_16x16x32_bf16 v[84:87], v[174:177], v[206:209], v[84:87]
	v_mfma_f32_16x16x32_bf16 v[80:83], v[182:185], v[206:209], v[80:83]
	v_mfma_f32_16x16x32_bf16 v[68:71], v[174:177], v[214:217], v[68:71]
	v_mfma_f32_16x16x32_bf16 v[64:67], v[182:185], v[214:217], v[64:67]
	s_setprio 0
	s_barrier
; #define PG8_STAGE(bufoff, gbase, voff) do { _Pragma("unroll") for (int _i = 0; _i < 2; ++_i) \
;         __builtin_amdgcn_global_load_lds((const unsigned*)((const char*)(gbase) + (voff)[_i]), (LAS unsigned*)(lds + (bufoff) + ldsw + _i * 8192), 16, 0, 0); } while (0)
; #define PG8_LDA(dst, b, h) do { _Pragma("unroll") for (int m = 0; m < 4; ++m) _Pragma("unroll") for (int k = 0; k < 2; ++k) dst[m][k] = *(const LAS bf16x8*)(lds + PG8_SA(b, h) + aoff + m * 2048 + k * 1024); } while (0)
; #define PG8_MMA(ai, bj, At, Bt) do { __builtin_amdgcn_s_setprio(1); _Pragma("unroll") for (int m = 0; m < 4; ++m) _Pragma("unroll") for (int n = 0; n < 2; ++n) _Pragma("unroll") for (int k = 0; k < 2; ++k) \
;         acc[ai][bj][m][n] = __builtin_amdgcn_mfma_f32_16x16x32_bf16(Bt[n][k], At[m][k], acc[ai][bj][m][n], 0, 0, 0); __builtin_amdgcn_s_setprio(0); } while (0)
; #define PG8_WAIT_V(n) asm volatile("s_waitcnt vmcnt(" #n ")" ::: "memory")
; #define PG8_WAIT_L(n) asm volatile("s_waitcnt lgkmcnt(" #n ")" ::: "memory")
; #define PG8_BAR __builtin_amdgcn_s_barrier()
; #define PG8_SCHED __builtin_amdgcn_sched_barrier(0)
; template <class Epi, bool HALO>
; __device__ __forceinline__ void gemm_phase(LAS unsigned char* lds, const Gemm g, const StaticOrder& S, const Epi& E) {
;     ...
;             PG8_LDA(At, 1, 1); PG8_STAGE(PG8_SB(1, 0), b3, voffB); PG8_STAGE(PG8_SB(1, 1), b3 + hstepB, voffB); PG8_STAGE(PG8_SA(1, 0), a3, voffA);
;             PG8_WAIT_V(8); PG8_WAIT_L(0); PG8_BAR; PG8_MMA(1, 0, At, B0); PG8_MMA(1, 1, At, B1); PG8_BAR; PG8_SCHED;
;         }
;         if (wr == 0) PG8_BAR;
	s_add_u32 s38, s36, 0x8000
	s_addc_u32 s39, s37, 0
	s_add_i32 s61, s61, s45
	v_lshl_add_u64 v[222:223], s[38:39], 0, v[128:129]
	s_mov_b32 m0, s61
	ds_read_b128 v[186:189], v151 offset:49152
	ds_read_b128 v[190:193], v151 offset:50176
	ds_read_b128 v[194:197], v151 offset:51200
	ds_read_b128 v[198:201], v151 offset:52224
	ds_read_b128 v[202:205], v151 offset:53248
	ds_read_b128 v[206:209], v151 offset:54272
	ds_read_b128 v[210:213], v151 offset:55296
	ds_read_b128 v[214:217], v151 offset:56320
	global_load_lds_dwordx4 v[222:223], off
	s_add_i32 m0, s61, 0x2000
	s_add_u32 s36, s36, 0xc000
	v_lshl_add_u64 v[222:223], s[38:39], 0, v[132:133]
	s_addc_u32 s37, s37, 0
	s_add_i32 s38, s62, s45
	global_load_lds_dwordx4 v[222:223], off
	v_lshl_add_u64 v[222:223], s[36:37], 0, v[128:129]
	s_mov_b32 m0, s38
	v_lshl_add_u64 v[146:147], v[146:147], 0, s[16:17]
	global_load_lds_dwordx4 v[222:223], off
	v_lshl_add_u64 v[222:223], s[36:37], 0, v[132:133]
	s_add_i32 m0, s38, 0x2000
	s_nop 0
	global_load_lds_dwordx4 v[222:223], off
	s_mov_b32 m0, s52
	s_nop 0
	global_load_lds_dwordx4 v[146:147], off
	v_lshl_add_u64 v[146:147], v[218:219], 0, s[16:17]
	s_mov_b32 m0, s53
	s_nop 0
	global_load_lds_dwordx4 v[146:147], off
	s_waitcnt vmcnt(8)
	s_waitcnt lgkmcnt(0)
	s_barrier
	s_setprio 1
	s_waitcnt lgkmcnt(0)
	v_mfma_f32_16x16x32_bf16 v[60:63], v[154:157], v[186:189], v[60:63]
	v_mfma_f32_16x16x32_bf16 v[56:59], v[162:165], v[186:189], v[56:59]
	v_mfma_f32_16x16x32_bf16 v[44:47], v[154:157], v[194:197], v[44:47]
	v_mfma_f32_16x16x32_bf16 v[40:43], v[162:165], v[194:197], v[40:43]
	v_mfma_f32_16x16x32_bf16 v[28:31], v[154:157], v[202:205], v[28:31]
	v_mfma_f32_16x16x32_bf16 v[24:27], v[162:165], v[202:205], v[24:27]
	v_mfma_f32_16x16x32_bf16 v[12:15], v[154:157], v[210:213], v[12:15]
	v_mfma_f32_16x16x32_bf16 v[8:11], v[162:165], v[210:213], v[8:11]
	v_mfma_f32_16x16x32_bf16 v[60:63], v[158:161], v[190:193], v[60:63]
	v_mfma_f32_16x16x32_bf16 v[56:59], v[166:169], v[190:193], v[56:59]
	v_mfma_f32_16x16x32_bf16 v[44:47], v[158:161], v[198:201], v[44:47]
	v_mfma_f32_16x16x32_bf16 v[40:43], v[166:169], v[198:201], v[40:43]
	v_mfma_f32_16x16x32_bf16 v[28:31], v[158:161], v[206:209], v[28:31]
	v_mfma_f32_16x16x32_bf16 v[24:27], v[166:169], v[206:209], v[24:27]
	v_mfma_f32_16x16x32_bf16 v[12:15], v[158:161], v[214:217], v[12:15]
	v_mfma_f32_16x16x32_bf16 v[8:11], v[166:169], v[214:217], v[8:11]
	s_setprio 0
	s_setprio 1
	v_mfma_f32_16x16x32_bf16 v[52:55], v[170:173], v[186:189], v[52:55]
	v_mfma_f32_16x16x32_bf16 v[48:51], v[178:181], v[186:189], v[48:51]
	v_mfma_f32_16x16x32_bf16 v[36:39], v[170:173], v[194:197], v[36:39]
	v_mfma_f32_16x16x32_bf16 v[32:35], v[178:181], v[194:197], v[32:35]
	v_mfma_f32_16x16x32_bf16 v[20:23], v[170:173], v[202:205], v[20:23]
	v_mfma_f32_16x16x32_bf16 v[16:19], v[178:181], v[202:205], v[16:19]
	v_mfma_f32_16x16x32_bf16 v[4:7], v[170:173], v[210:213], v[4:7]
	v_mfma_f32_16x16x32_bf16 v[0:3], v[178:181], v[210:213], v[0:3]
	v_mfma_f32_16x16x32_bf16 v[52:55], v[174:177], v[190:193], v[52:55]
	v_mfma_f32_16x16x32_bf16 v[48:51], v[182:185], v[190:193], v[48:51]
	v_mfma_f32_16x16x32_bf16 v[36:39], v[174:177], v[198:201], v[36:39]
	v_mfma_f32_16x16x32_bf16 v[32:35], v[182:185], v[198:201], v[32:35]
	v_mfma_f32_16x16x32_bf16 v[20:23], v[174:177], v[206:209], v[20:23]
	v_mfma_f32_16x16x32_bf16 v[16:19], v[182:185], v[206:209], v[16:19]
	s_add_i32 s60, s60, 2
	s_add_u32 s58, s58, 0x10000
	s_addc_u32 s59, s59, 0
	s_add_u32 s34, s34, 0x100
	s_addc_u32 s35, s35, 0
	s_cmp_gt_u32 s60, 13
	v_mfma_f32_16x16x32_bf16 v[4:7], v[174:177], v[214:217], v[4:7]
	v_mfma_f32_16x16x32_bf16 v[0:3], v[182:185], v[214:217], v[0:3]
	s_setprio 0
	s_barrier
	s_cbranch_scc0 .LBB0_1181
	s_and_b64 vcc, exec, s[18:19]
	s_cbranch_vccz .LBB0_1184
	s_barrier

; #define PG8_STAGE(bufoff, gbase, voff) do { _Pragma("unroll") for (int _i = 0; _i < 2; ++_i) \
;         __builtin_amdgcn_global_load_lds((const unsigned*)((const char*)(gbase) + (voff)[_i]), (LAS unsigned*)(lds + (bufoff) + ldsw + _i * 8192), 16, 0, 0); } while (0)
; #define PG8_LDA(dst, b, h) do { _Pragma("unroll") for (int m = 0; m < 4; ++m) _Pragma("unroll") for (int k = 0; k < 2; ++k) dst[m][k] = *(const LAS bf16x8*)(lds + PG8_SA(b, h) + aoff + m * 2048 + k * 1024); } while (0)
; #define PG8_LDB(dst, b, h) do { _Pragma("unroll") for (int n = 0; n < 2; ++n) _Pragma("unroll") for (int k = 0; k < 2; ++k) dst[n][k] = *(const LAS bf16x8*)(lds + PG8_SB(b, h) + boff + n * 2048 + k * 1024); } while (0)
; #define PG8_MMA(ai, bj, At, Bt) do { __builtin_amdgcn_s_setprio(1); _Pragma("unroll") for (int m = 0; m < 4; ++m) _Pragma("unroll") for (int n = 0; n < 2; ++n) _Pragma("unroll") for (int k = 0; k < 2; ++k) \
;         acc[ai][bj][m][n] = __builtin_amdgcn_mfma_f32_16x16x32_bf16(Bt[n][k], At[m][k], acc[ai][bj][m][n], 0, 0, 0); __builtin_amdgcn_s_setprio(0); } while (0)
; #define PG8_WAIT_V(n) asm volatile("s_waitcnt vmcnt(" #n ")" ::: "memory")
; #define PG8_WAIT_L(n) asm volatile("s_waitcnt lgkmcnt(" #n ")" ::: "memory")
; #define PG8_BAR __builtin_amdgcn_s_barrier()
; #define PG8_SCHED __builtin_amdgcn_sched_barrier(0)
; template <class Epi, bool HALO>
; __device__ __forceinline__ void gemm_phase(LAS unsigned char* lds, const Gemm g, const StaticOrder& S, const Epi& E) {
;     ...
;         for (int t = 0; t < nt; t += 2) {
;             const bool last = (t == nt - 2);
;             const char* a1 = cA + (size_t)(t + 1) * kstep;
;             const char* a2 = last ? nA : cA + (size_t)(t + 2) * kstep; const char* b2 = last ? nB : cB + (size_t)(t + 2) * kstepB;
;             const char* a3 = a2 + kstep; const char* b3 = b2 + kstepB;
;             PG8_LDB(B0, 0, 0); PG8_LDB(B1, 0, 1); PG8_SCHED; PG8_LDA(At, 0, 0); PG8_STAGE(PG8_SA(1, 1), a1 + hstepA, voffA);
;             PG8_WAIT_V(8); PG8_WAIT_L(0); PG8_BAR; PG8_MMA(0, 0, At, B0); PG8_MMA(0, 1, At, B1); PG8_BAR; PG8_SCHED;
;             PG8_LDA(At, 0, 1); PG8_STAGE(PG8_SB(0, 0), b2, voffB); PG8_STAGE(PG8_SB(0, 1), b2 + hstepB, voffB); PG8_STAGE(PG8_SA(0, 0), a2, voffA);
.Lwp12_skip:
.LBB0_1278:
	ds_read_b128 v[116:119], v222
	ds_read_b128 v[120:123], v222 offset:1024
	ds_read_b128 v[132:135], v222 offset:2048
	ds_read_b128 v[136:139], v222 offset:3072
	ds_read_b128 v[144:147], v223
	ds_read_b128 v[148:151], v223 offset:1024
	ds_read_b128 v[152:155], v223 offset:2048
	ds_read_b128 v[156:159], v223 offset:3072
	s_add_u32 s10, s8, 0xfffc0080
	s_addc_u32 s11, s9, -1
	s_cmp_eq_u32 s43, 12
	s_cselect_b32 s13, s16, s11
	s_cselect_b32 s12, s17, s10
	s_cselect_b32 s11, s31, s42
	s_cselect_b32 s10, s35, s41
	v_lshl_add_u64 v[210:211], s[8:9], 0, v[186:187]
	s_add_i32 m0, s54, 0xc000
	ds_read_b128 v[160:163], v224
	ds_read_b128 v[164:167], v224 offset:1024
	ds_read_b128 v[168:171], v224 offset:2048
	ds_read_b128 v[172:175], v224 offset:3072
	ds_read_b128 v[194:197], v224 offset:4096
	ds_read_b128 v[198:201], v224 offset:5120
	ds_read_b128 v[202:205], v224 offset:6144
	ds_read_b128 v[206:209], v224 offset:7168
	global_load_lds_dwordx4 v[210:211], off
	v_lshl_add_u64 v[210:211], s[8:9], 0, v[188:189]
	s_add_i32 m0, s54, 0xe000
	s_nop 0
	global_load_lds_dwordx4 v[210:211], off
	s_waitcnt vmcnt(8)
	s_waitcnt lgkmcnt(0)
	s_barrier
	s_setprio 1
	s_waitcnt lgkmcnt(0)
	v_mfma_f32_16x16x32_bf16 v[104:107], v[116:119], v[160:163], v[104:107]
	v_mfma_f32_16x16x32_bf16 v[100:103], v[132:135], v[160:163], v[100:103]
	v_mfma_f32_16x16x32_bf16 v[140:143], v[116:119], v[168:171], v[140:143]
	v_mfma_f32_16x16x32_bf16 v[44:47], v[132:135], v[168:171], v[44:47]
	v_mfma_f32_16x16x32_bf16 v[128:131], v[116:119], v[194:197], v[128:131]
	v_mfma_f32_16x16x32_bf16 v[40:43], v[132:135], v[194:197], v[40:43]
	v_mfma_f32_16x16x32_bf16 v[108:111], v[116:119], v[202:205], v[108:111]
	v_mfma_f32_16x16x32_bf16 v[52:55], v[132:135], v[202:205], v[52:55]
	v_mfma_f32_16x16x32_bf16 v[104:107], v[120:123], v[164:167], v[104:107]
	v_mfma_f32_16x16x32_bf16 v[100:103], v[136:139], v[164:167], v[100:103]
	v_mfma_f32_16x16x32_bf16 v[140:143], v[120:123], v[172:175], v[140:143]
	v_mfma_f32_16x16x32_bf16 v[44:47], v[136:139], v[172:175], v[44:47]
	v_mfma_f32_16x16x32_bf16 v[128:131], v[120:123], v[198:201], v[128:131]
	v_mfma_f32_16x16x32_bf16 v[40:43], v[136:139], v[198:201], v[40:43]
	v_mfma_f32_16x16x32_bf16 v[108:111], v[120:123], v[206:209], v[108:111]
	v_mfma_f32_16x16x32_bf16 v[52:55], v[136:139], v[206:209], v[52:55]
	s_setprio 0
	s_setprio 1
	v_mfma_f32_16x16x32_bf16 v[96:99], v[144:147], v[160:163], v[96:99]
	v_mfma_f32_16x16x32_bf16 v[72:75], v[152:155], v[160:163], v[72:75]
	v_mfma_f32_16x16x32_bf16 v[124:127], v[144:147], v[168:171], v[124:127]
	v_mfma_f32_16x16x32_bf16 v[36:39], v[152:155], v[168:171], v[36:39]
	v_mfma_f32_16x16x32_bf16 v[112:115], v[144:147], v[194:197], v[112:115]
	v_mfma_f32_16x16x32_bf16 v[32:35], v[152:155], v[194:197], v[32:35]
	v_mfma_f32_16x16x32_bf16 v[92:95], v[144:147], v[202:205], v[92:95]
	v_mfma_f32_16x16x32_bf16 v[48:51], v[152:155], v[202:205], v[48:51]
	v_mfma_f32_16x16x32_bf16 v[96:99], v[148:151], v[164:167], v[96:99]
	v_mfma_f32_16x16x32_bf16 v[72:75], v[156:159], v[164:167], v[72:75]
	v_mfma_f32_16x16x32_bf16 v[124:127], v[148:151], v[172:175], v[124:127]
	v_mfma_f32_16x16x32_bf16 v[36:39], v[156:159], v[172:175], v[36:39]
	v_mfma_f32_16x16x32_bf16 v[112:115], v[148:151], v[198:201], v[112:115]
	v_mfma_f32_16x16x32_bf16 v[32:35], v[156:159], v[198:201], v[32:35]
	v_mfma_f32_16x16x32_bf16 v[92:95], v[148:151], v[206:209], v[92:95]
	v_mfma_f32_16x16x32_bf16 v[48:51], v[156:159], v[206:209], v[48:51]
	s_setprio 0
	s_barrier
	s_add_i32 s44, s70, s51
	v_lshl_add_u64 v[210:211], s[10:11], 0, v[176:177]
	s_mov_b32 m0, s44
	ds_read_b128 v[160:163], v224 offset:16384
	ds_read_b128 v[164:167], v224 offset:17408
	ds_read_b128 v[168:171], v224 offset:18432
	ds_read_b128 v[172:175], v224 offset:19456
	ds_read_b128 v[194:197], v224 offset:20480
	ds_read_b128 v[198:201], v224 offset:21504
	ds_read_b128 v[202:205], v224 offset:22528
	ds_read_b128 v[206:209], v224 offset:23552
	global_load_lds_dwordx4 v[210:211], off
	s_add_i32 m0, s44, 0x2000
	s_add_u32 s44, s10, 0x4000
	v_lshl_add_u64 v[210:211], s[10:11], 0, v[180:181]
	s_addc_u32 s45, s11, 0
	s_add_i32 s91, s71, s51
	global_load_lds_dwordx4 v[210:211], off
	v_lshl_add_u64 v[210:211], s[44:45], 0, v[176:177]
	s_mov_b32 m0, s91
	v_lshl_add_u64 v[212:213], s[12:13], 0, v[182:183]
	global_load_lds_dwordx4 v[210:211], off
	v_lshl_add_u64 v[210:211], s[44:45], 0, v[180:181]
	s_add_i32 m0, s91, 0x2000
	s_nop 0
	global_load_lds_dwordx4 v[210:211], off
	v_lshl_add_u64 v[210:211], s[12:13], 0, v[178:179]
	s_mov_b32 m0, s54
	s_nop 0
	global_load_lds_dwordx4 v[210:211], off
	s_mov_b32 m0, s55
	s_nop 0
	global_load_lds_dwordx4 v[212:213], off
	s_waitcnt vmcnt(8)
	s_waitcnt lgkmcnt(0)
	s_barrier
; #define PG8_STAGE(bufoff, gbase, voff) do { _Pragma("unroll") for (int _i = 0; _i < 2; ++_i) \
;         __builtin_amdgcn_global_load_lds((const unsigned*)((const char*)(gbase) + (voff)[_i]), (LAS unsigned*)(lds + (bufoff) + ldsw + _i * 8192), 16, 0, 0); } while (0)
; #define PG8_LDA(dst, b, h) do { _Pragma("unroll") for (int m = 0; m < 4; ++m) _Pragma("unroll") for (int k = 0; k < 2; ++k) dst[m][k] = *(const LAS bf16x8*)(lds + PG8_SA(b, h) + aoff + m * 2048 + k * 1024); } while (0)
; #define PG8_LDB(dst, b, h) do { _Pragma("unroll") for (int n = 0; n < 2; ++n) _Pragma("unroll") for (int k = 0; k < 2; ++k) dst[n][k] = *(const LAS bf16x8*)(lds + PG8_SB(b, h) + boff + n * 2048 + k * 1024); } while (0)
; #define PG8_MMA(ai, bj, At, Bt) do { __builtin_amdgcn_s_setprio(1); _Pragma("unroll") for (int m = 0; m < 4; ++m) _Pragma("unroll") for (int n = 0; n < 2; ++n) _Pragma("unroll") for (int k = 0; k < 2; ++k) \
;         acc[ai][bj][m][n] = __builtin_amdgcn_mfma_f32_16x16x32_bf16(Bt[n][k], At[m][k], acc[ai][bj][m][n], 0, 0, 0); __builtin_amdgcn_s_setprio(0); } while (0)
; #define PG8_WAIT_V(n) asm volatile("s_waitcnt vmcnt(" #n ")" ::: "memory")
; #define PG8_WAIT_L(n) asm volatile("s_waitcnt lgkmcnt(" #n ")" ::: "memory")
; #define PG8_BAR __builtin_amdgcn_s_barrier()
; #define PG8_SCHED __builtin_amdgcn_sched_barrier(0)
; template <class Epi, bool HALO>
; __device__ __forceinline__ void gemm_phase(LAS unsigned char* lds, const Gemm g, const StaticOrder& S, const Epi& E) {
;     ...
;             PG8_WAIT_V(8); PG8_WAIT_L(0); PG8_BAR; PG8_MMA(1, 0, At, B0); PG8_MMA(1, 1, At, B1); PG8_BAR; PG8_SCHED;
;             PG8_LDB(B0, 1, 0); PG8_LDB(B1, 1, 1); PG8_SCHED; PG8_LDA(At, 1, 0); PG8_STAGE(PG8_SA(0, 1), a2 + hstepA, voffA);
;             PG8_WAIT_V(8); PG8_WAIT_L(0); PG8_BAR; PG8_MMA(0, 0, At, B0); PG8_MMA(0, 1, At, B1); PG8_BAR; PG8_SCHED;
	s_setprio 1
	s_waitcnt lgkmcnt(0)
	v_mfma_f32_16x16x32_bf16 v[84:87], v[116:119], v[160:163], v[84:87]
	v_mfma_f32_16x16x32_bf16 v[20:23], v[132:135], v[160:163], v[20:23]
	v_mfma_f32_16x16x32_bf16 v[68:71], v[116:119], v[168:171], v[68:71]
	v_mfma_f32_16x16x32_bf16 v[12:15], v[132:135], v[168:171], v[12:15]
	v_mfma_f32_16x16x32_bf16 v[64:67], v[116:119], v[194:197], v[64:67]
	v_mfma_f32_16x16x32_bf16 v[8:11], v[132:135], v[194:197], v[8:11]
	v_mfma_f32_16x16x32_bf16 v[88:91], v[116:119], v[202:205], v[88:91]
	v_mfma_f32_16x16x32_bf16 v[28:31], v[132:135], v[202:205], v[28:31]
	v_mfma_f32_16x16x32_bf16 v[84:87], v[120:123], v[164:167], v[84:87]
	v_mfma_f32_16x16x32_bf16 v[20:23], v[136:139], v[164:167], v[20:23]
	v_mfma_f32_16x16x32_bf16 v[68:71], v[120:123], v[172:175], v[68:71]
	v_mfma_f32_16x16x32_bf16 v[12:15], v[136:139], v[172:175], v[12:15]
	v_mfma_f32_16x16x32_bf16 v[64:67], v[120:123], v[198:201], v[64:67]
	v_mfma_f32_16x16x32_bf16 v[8:11], v[136:139], v[198:201], v[8:11]
	v_mfma_f32_16x16x32_bf16 v[88:91], v[120:123], v[206:209], v[88:91]
	v_mfma_f32_16x16x32_bf16 v[28:31], v[136:139], v[206:209], v[28:31]
	s_setprio 0
	s_setprio 1
	v_mfma_f32_16x16x32_bf16 v[80:83], v[144:147], v[160:163], v[80:83]
	v_mfma_f32_16x16x32_bf16 v[16:19], v[152:155], v[160:163], v[16:19]
	v_mfma_f32_16x16x32_bf16 v[60:63], v[144:147], v[168:171], v[60:63]
	v_mfma_f32_16x16x32_bf16 v[4:7], v[152:155], v[168:171], v[4:7]
	v_mfma_f32_16x16x32_bf16 v[56:59], v[144:147], v[194:197], v[56:59]
	v_mfma_f32_16x16x32_bf16 v[0:3], v[152:155], v[194:197], v[0:3]
	v_mfma_f32_16x16x32_bf16 v[76:79], v[144:147], v[202:205], v[76:79]
	v_mfma_f32_16x16x32_bf16 v[24:27], v[152:155], v[202:205], v[24:27]
	v_mfma_f32_16x16x32_bf16 v[80:83], v[148:151], v[164:167], v[80:83]
	v_mfma_f32_16x16x32_bf16 v[16:19], v[156:159], v[164:167], v[16:19]
	v_mfma_f32_16x16x32_bf16 v[60:63], v[148:151], v[172:175], v[60:63]
	v_mfma_f32_16x16x32_bf16 v[4:7], v[156:159], v[172:175], v[4:7]
	v_mfma_f32_16x16x32_bf16 v[56:59], v[148:151], v[198:201], v[56:59]
	v_mfma_f32_16x16x32_bf16 v[0:3], v[156:159], v[198:201], v[0:3]
	v_mfma_f32_16x16x32_bf16 v[76:79], v[148:151], v[206:209], v[76:79]
	v_mfma_f32_16x16x32_bf16 v[24:27], v[156:159], v[206:209], v[24:27]
	s_setprio 0
	s_barrier
	s_add_i32 s44, 0, 0x18000
	s_add_i32 s45, 0, 0x1c000
	v_add_u32_e32 v136, s44, v221
	v_add_u32_e32 v156, s45, v221
	ds_read_b128 v[116:119], v136
	ds_read_b128 v[120:123], v136 offset:1024
	ds_read_b128 v[132:135], v136 offset:2048
	ds_read_b128 v[136:139], v136 offset:3072
	ds_read_b128 v[144:147], v156
	ds_read_b128 v[148:151], v156 offset:1024
	ds_read_b128 v[152:155], v156 offset:2048
	ds_read_b128 v[156:159], v156 offset:3072
	s_add_u32 s12, s12, 0x40000
	s_addc_u32 s13, s13, 0
	s_mov_b32 m0, s56
	v_lshl_add_u64 v[214:215], s[12:13], 0, v[178:179]
	ds_read_b128 v[160:163], v224 offset:32768
	ds_read_b128 v[164:167], v224 offset:33792
	ds_read_b128 v[168:171], v224 offset:34816
	ds_read_b128 v[172:175], v224 offset:35840
	ds_read_b128 v[194:197], v224 offset:36864
	ds_read_b128 v[198:201], v224 offset:37888
	ds_read_b128 v[202:205], v224 offset:38912
	ds_read_b128 v[206:209], v224 offset:39936
	global_load_lds_dwordx4 v[214:215], off
	v_lshl_add_u64 v[214:215], s[12:13], 0, v[182:183]
	s_mov_b32 m0, s57
	s_nop 0
	global_load_lds_dwordx4 v[214:215], off
	s_waitcnt vmcnt(8)
	s_waitcnt lgkmcnt(0)
	s_barrier
	s_setprio 1
	s_waitcnt lgkmcnt(0)
	v_mfma_f32_16x16x32_bf16 v[104:107], v[116:119], v[160:163], v[104:107]
	v_mfma_f32_16x16x32_bf16 v[100:103], v[132:135], v[160:163], v[100:103]
	v_mfma_f32_16x16x32_bf16 v[140:143], v[116:119], v[168:171], v[140:143]
	v_mfma_f32_16x16x32_bf16 v[44:47], v[132:135], v[168:171], v[44:47]
	v_mfma_f32_16x16x32_bf16 v[128:131], v[116:119], v[194:197], v[128:131]
	v_mfma_f32_16x16x32_bf16 v[40:43], v[132:135], v[194:197], v[40:43]
	v_mfma_f32_16x16x32_bf16 v[108:111], v[116:119], v[202:205], v[108:111]
	v_mfma_f32_16x16x32_bf16 v[52:55], v[132:135], v[202:205], v[52:55]
	v_mfma_f32_16x16x32_bf16 v[104:107], v[120:123], v[164:167], v[104:107]
	v_mfma_f32_16x16x32_bf16 v[100:103], v[136:139], v[164:167], v[100:103]
	v_mfma_f32_16x16x32_bf16 v[140:143], v[120:123], v[172:175], v[140:143]
	v_mfma_f32_16x16x32_bf16 v[44:47], v[136:139], v[172:175], v[44:47]
	v_mfma_f32_16x16x32_bf16 v[128:131], v[120:123], v[198:201], v[128:131]
	v_mfma_f32_16x16x32_bf16 v[40:43], v[136:139], v[198:201], v[40:43]
	v_mfma_f32_16x16x32_bf16 v[108:111], v[120:123], v[206:209], v[108:111]
	v_mfma_f32_16x16x32_bf16 v[52:55], v[136:139], v[206:209], v[52:55]
	s_setprio 0
	s_setprio 1
	v_mfma_f32_16x16x32_bf16 v[96:99], v[144:147], v[160:163], v[96:99]
	v_mfma_f32_16x16x32_bf16 v[72:75], v[152:155], v[160:163], v[72:75]
	v_mfma_f32_16x16x32_bf16 v[124:127], v[144:147], v[168:171], v[124:127]
	v_mfma_f32_16x16x32_bf16 v[36:39], v[152:155], v[168:171], v[36:39]
	v_mfma_f32_16x16x32_bf16 v[112:115], v[144:147], v[194:197], v[112:115]
	v_mfma_f32_16x16x32_bf16 v[32:35], v[152:155], v[194:197], v[32:35]
	v_mfma_f32_16x16x32_bf16 v[92:95], v[144:147], v[202:205], v[92:95]
	v_mfma_f32_16x16x32_bf16 v[48:51], v[152:155], v[202:205], v[48:51]
	v_mfma_f32_16x16x32_bf16 v[96:99], v[148:151], v[164:167], v[96:99]
	v_mfma_f32_16x16x32_bf16 v[72:75], v[156:159], v[164:167], v[72:75]
	v_mfma_f32_16x16x32_bf16 v[124:127], v[148:151], v[172:175], v[124:127]
	v_mfma_f32_16x16x32_bf16 v[36:39], v[156:159], v[172:175], v[36:39]
	v_mfma_f32_16x16x32_bf16 v[112:115], v[148:151], v[198:201], v[112:115]
	v_mfma_f32_16x16x32_bf16 v[32:35], v[156:159], v[198:201], v[32:35]
	v_mfma_f32_16x16x32_bf16 v[92:95], v[148:151], v[206:209], v[92:95]
	v_mfma_f32_16x16x32_bf16 v[48:51], v[156:159], v[206:209], v[48:51]
	s_setprio 0
	s_barrier
; #define PG8_STAGE(bufoff, gbase, voff) do { _Pragma("unroll") for (int _i = 0; _i < 2; ++_i) \
;         __builtin_amdgcn_global_load_lds((const unsigned*)((const char*)(gbase) + (voff)[_i]), (LAS unsigned*)(lds + (bufoff) + ldsw + _i * 8192), 16, 0, 0); } while (0)
; #define PG8_LDA(dst, b, h) do { _Pragma("unroll") for (int m = 0; m < 4; ++m) _Pragma("unroll") for (int k = 0; k < 2; ++k) dst[m][k] = *(const LAS bf16x8*)(lds + PG8_SA(b, h) + aoff + m * 2048 + k * 1024); } while (0)
; #define PG8_MMA(ai, bj, At, Bt) do { __builtin_amdgcn_s_setprio(1); _Pragma("unroll") for (int m = 0; m < 4; ++m) _Pragma("unroll") for (int n = 0; n < 2; ++n) _Pragma("unroll") for (int k = 0; k < 2; ++k) \
;         acc[ai][bj][m][n] = __builtin_amdgcn_mfma_f32_16x16x32_bf16(Bt[n][k], At[m][k], acc[ai][bj][m][n], 0, 0, 0); __builtin_amdgcn_s_setprio(0); } while (0)
; #define PG8_WAIT_V(n) asm volatile("s_waitcnt vmcnt(" #n ")" ::: "memory")
; #define PG8_WAIT_L(n) asm volatile("s_waitcnt lgkmcnt(" #n ")" ::: "memory")
; #define PG8_BAR __builtin_amdgcn_s_barrier()
; #define PG8_SCHED __builtin_amdgcn_sched_barrier(0)
; template <class Epi, bool HALO>
; __device__ __forceinline__ void gemm_phase(LAS unsigned char* lds, const Gemm g, const StaticOrder& S, const Epi& E) {
;     ...
;             PG8_LDA(At, 1, 1); PG8_STAGE(PG8_SB(1, 0), b3, voffB); PG8_STAGE(PG8_SB(1, 1), b3 + hstepB, voffB); PG8_STAGE(PG8_SA(1, 0), a3, voffA);
;             PG8_WAIT_V(8); PG8_WAIT_L(0); PG8_BAR; PG8_MMA(1, 0, At, B0); PG8_MMA(1, 1, At, B1); PG8_BAR; PG8_SCHED;
;         }
;         if (wr == 0) PG8_BAR;
	s_add_u32 s12, s10, 0x8000
	s_addc_u32 s13, s11, 0
	s_add_i32 s44, s44, s51
	v_lshl_add_u64 v[214:215], s[12:13], 0, v[176:177]
	s_mov_b32 m0, s44
	ds_read_b128 v[160:163], v224 offset:49152
	ds_read_b128 v[164:167], v224 offset:50176
	ds_read_b128 v[168:171], v224 offset:51200
	ds_read_b128 v[172:175], v224 offset:52224
	ds_read_b128 v[194:197], v224 offset:53248
	ds_read_b128 v[198:201], v224 offset:54272
	ds_read_b128 v[202:205], v224 offset:55296
	ds_read_b128 v[206:209], v224 offset:56320
	global_load_lds_dwordx4 v[214:215], off
	s_add_i32 m0, s44, 0x2000
	s_add_u32 s10, s10, 0xc000
	v_lshl_add_u64 v[214:215], s[12:13], 0, v[180:181]
	s_addc_u32 s11, s11, 0
	s_add_i32 s12, s45, s51
	global_load_lds_dwordx4 v[214:215], off
	v_lshl_add_u64 v[214:215], s[10:11], 0, v[176:177]
	s_mov_b32 m0, s12
	v_lshl_add_u64 v[210:211], v[210:211], 0, s[26:27]
	global_load_lds_dwordx4 v[214:215], off
	v_lshl_add_u64 v[214:215], s[10:11], 0, v[180:181]
	s_add_i32 m0, s12, 0x2000
	s_nop 0
	global_load_lds_dwordx4 v[214:215], off
	s_mov_b32 m0, s66
	s_nop 0
	global_load_lds_dwordx4 v[210:211], off
	v_lshl_add_u64 v[210:211], v[212:213], 0, s[26:27]
	s_mov_b32 m0, s67
	s_nop 0
	global_load_lds_dwordx4 v[210:211], off
	s_waitcnt vmcnt(8)
	s_waitcnt lgkmcnt(0)
	s_barrier
	s_setprio 1
	s_waitcnt lgkmcnt(0)
	v_mfma_f32_16x16x32_bf16 v[84:87], v[116:119], v[160:163], v[84:87]
	v_mfma_f32_16x16x32_bf16 v[20:23], v[132:135], v[160:163], v[20:23]
	v_mfma_f32_16x16x32_bf16 v[68:71], v[116:119], v[168:171], v[68:71]
	v_mfma_f32_16x16x32_bf16 v[12:15], v[132:135], v[168:171], v[12:15]
	v_mfma_f32_16x16x32_bf16 v[64:67], v[116:119], v[194:197], v[64:67]
	v_mfma_f32_16x16x32_bf16 v[8:11], v[132:135], v[194:197], v[8:11]
	v_mfma_f32_16x16x32_bf16 v[88:91], v[116:119], v[202:205], v[88:91]
	v_mfma_f32_16x16x32_bf16 v[28:31], v[132:135], v[202:205], v[28:31]
	v_mfma_f32_16x16x32_bf16 v[84:87], v[120:123], v[164:167], v[84:87]
	v_mfma_f32_16x16x32_bf16 v[20:23], v[136:139], v[164:167], v[20:23]
	v_mfma_f32_16x16x32_bf16 v[68:71], v[120:123], v[172:175], v[68:71]
	v_mfma_f32_16x16x32_bf16 v[12:15], v[136:139], v[172:175], v[12:15]
	v_mfma_f32_16x16x32_bf16 v[64:67], v[120:123], v[198:201], v[64:67]
	v_mfma_f32_16x16x32_bf16 v[8:11], v[136:139], v[198:201], v[8:11]
	v_mfma_f32_16x16x32_bf16 v[88:91], v[120:123], v[206:209], v[88:91]
	v_mfma_f32_16x16x32_bf16 v[28:31], v[136:139], v[206:209], v[28:31]
	s_setprio 0
	s_setprio 1
	v_mfma_f32_16x16x32_bf16 v[80:83], v[144:147], v[160:163], v[80:83]
	v_mfma_f32_16x16x32_bf16 v[16:19], v[152:155], v[160:163], v[16:19]
	v_mfma_f32_16x16x32_bf16 v[60:63], v[144:147], v[168:171], v[60:63]
	v_mfma_f32_16x16x32_bf16 v[4:7], v[152:155], v[168:171], v[4:7]
	v_mfma_f32_16x16x32_bf16 v[56:59], v[144:147], v[194:197], v[56:59]
	v_mfma_f32_16x16x32_bf16 v[0:3], v[152:155], v[194:197], v[0:3]
	v_mfma_f32_16x16x32_bf16 v[76:79], v[144:147], v[202:205], v[76:79]
	v_mfma_f32_16x16x32_bf16 v[24:27], v[152:155], v[202:205], v[24:27]
	v_mfma_f32_16x16x32_bf16 v[80:83], v[148:151], v[164:167], v[80:83]
	v_mfma_f32_16x16x32_bf16 v[16:19], v[156:159], v[164:167], v[16:19]
	v_mfma_f32_16x16x32_bf16 v[60:63], v[148:151], v[172:175], v[60:63]
	v_mfma_f32_16x16x32_bf16 v[4:7], v[156:159], v[172:175], v[4:7]
	v_mfma_f32_16x16x32_bf16 v[56:59], v[148:151], v[198:201], v[56:59]
	v_mfma_f32_16x16x32_bf16 v[0:3], v[156:159], v[198:201], v[0:3]
	s_add_i32 s43, s43, 2
	s_add_u32 s41, s41, 0x10000
	s_addc_u32 s42, s42, 0
	s_add_u32 s8, s8, 0x100
	s_addc_u32 s9, s9, 0
	s_cmp_gt_u32 s43, 13
	v_mfma_f32_16x16x32_bf16 v[76:79], v[148:151], v[206:209], v[76:79]
	v_mfma_f32_16x16x32_bf16 v[24:27], v[156:159], v[206:209], v[24:27]
	s_setprio 0
	s_barrier
	s_cbranch_scc0 .LBB0_1278
	s_and_b64 vcc, exec, s[28:29]
	s_cbranch_vccz .LBB0_1281
	s_barrier

; #define PG8_STAGE(bufoff, gbase, voff) do { _Pragma("unroll") for (int _i = 0; _i < 2; ++_i) \
;         __builtin_amdgcn_global_load_lds((const unsigned*)((const char*)(gbase) + (voff)[_i]), (LAS unsigned*)(lds + (bufoff) + ldsw + _i * 8192), 16, 0, 0); } while (0)
; #define PG8_LDA(dst, b, h) do { _Pragma("unroll") for (int m = 0; m < 4; ++m) _Pragma("unroll") for (int k = 0; k < 2; ++k) dst[m][k] = *(const LAS bf16x8*)(lds + PG8_SA(b, h) + aoff + m * 2048 + k * 1024); } while (0)
; #define PG8_LDB(dst, b, h) do { _Pragma("unroll") for (int n = 0; n < 2; ++n) _Pragma("unroll") for (int k = 0; k < 2; ++k) dst[n][k] = *(const LAS bf16x8*)(lds + PG8_SB(b, h) + boff + n * 2048 + k * 1024); } while (0)
; #define PG8_MMA(ai, bj, At, Bt) do { __builtin_amdgcn_s_setprio(1); _Pragma("unroll") for (int m = 0; m < 4; ++m) _Pragma("unroll") for (int n = 0; n < 2; ++n) _Pragma("unroll") for (int k = 0; k < 2; ++k) \
;         acc[ai][bj][m][n] = __builtin_amdgcn_mfma_f32_16x16x32_bf16(Bt[n][k], At[m][k], acc[ai][bj][m][n], 0, 0, 0); __builtin_amdgcn_s_setprio(0); } while (0)
; #define PG8_WAIT_V(n) asm volatile("s_waitcnt vmcnt(" #n ")" ::: "memory")
; #define PG8_WAIT_L(n) asm volatile("s_waitcnt lgkmcnt(" #n ")" ::: "memory")
; #define PG8_BAR __builtin_amdgcn_s_barrier()
; #define PG8_SCHED __builtin_amdgcn_sched_barrier(0)
; template <class Epi, bool HALO>
; __device__ __forceinline__ void gemm_phase(LAS unsigned char* lds, const Gemm g, const StaticOrder& S, const Epi& E) {
;     ...
;         for (int t = 0; t < nt; t += 2) {
;             const bool last = (t == nt - 2);
;             const char* a1 = cA + (size_t)(t + 1) * kstep;
;             const char* a2 = last ? nA : cA + (size_t)(t + 2) * kstep; const char* b2 = last ? nB : cB + (size_t)(t + 2) * kstepB;
;             const char* a3 = a2 + kstep; const char* b3 = b2 + kstepB;
;             PG8_LDB(B0, 0, 0); PG8_LDB(B1, 0, 1); PG8_SCHED; PG8_LDA(At, 0, 0); PG8_STAGE(PG8_SA(1, 1), a1 + hstepA, voffA);
;             PG8_WAIT_V(8); PG8_WAIT_L(0); PG8_BAR; PG8_MMA(0, 0, At, B0); PG8_MMA(0, 1, At, B1); PG8_BAR; PG8_SCHED;
;             PG8_LDA(At, 0, 1); PG8_STAGE(PG8_SB(0, 0), b2, voffB); PG8_STAGE(PG8_SB(0, 1), b2 + hstepB, voffB); PG8_STAGE(PG8_SA(0, 0), a2, voffA);
.LBB0_1407:
	ds_read_b128 v[136:139], v141
	ds_read_b128 v[144:147], v141 offset:1024
	ds_read_b128 v[148:151], v141 offset:2048
	ds_read_b128 v[152:155], v141 offset:3072
	ds_read_b128 v[156:159], v142
	ds_read_b128 v[160:163], v142 offset:1024
	ds_read_b128 v[164:167], v142 offset:2048
	ds_read_b128 v[168:171], v142 offset:3072
	s_add_u32 s18, s16, 0x4000
	s_addc_u32 s19, s17, 0
	s_cmp_eq_u32 s47, 40
	s_cselect_b32 s22, s4, s18
	s_cselect_b32 s23, s5, s19
	s_cselect_b32 s20, s14, s45
	s_cselect_b32 s21, s15, s46
	s_add_u32 s18, s22, 0x8000
	s_addc_u32 s19, s23, 0
	v_lshl_add_u64 v[204:205], s[16:17], 0, v[128:129]
	s_add_i32 m0, s30, 0xc000
	ds_read_b128 v[172:175], v143
	ds_read_b128 v[176:179], v143 offset:1024
	ds_read_b128 v[180:183], v143 offset:2048
	ds_read_b128 v[184:187], v143 offset:3072
	ds_read_b128 v[188:191], v143 offset:4096
	ds_read_b128 v[192:195], v143 offset:5120
	ds_read_b128 v[196:199], v143 offset:6144
	ds_read_b128 v[200:203], v143 offset:7168
	global_load_lds_dwordx4 v[204:205], off
	v_lshl_add_u64 v[204:205], s[16:17], 0, v[130:131]
	s_add_i32 m0, s30, 0xe000
	s_nop 0
	global_load_lds_dwordx4 v[204:205], off
	s_waitcnt vmcnt(8)
	s_waitcnt lgkmcnt(0)
	s_barrier
	s_setprio 1
	s_waitcnt lgkmcnt(0)
	v_mfma_f32_16x16x32_bf16 v[124:127], v[136:139], v[172:175], v[124:127]
	v_mfma_f32_16x16x32_bf16 v[120:123], v[148:151], v[172:175], v[120:123]
	v_mfma_f32_16x16x32_bf16 v[108:111], v[136:139], v[180:183], v[108:111]
	v_mfma_f32_16x16x32_bf16 v[104:107], v[148:151], v[180:183], v[104:107]
	v_mfma_f32_16x16x32_bf16 v[92:95], v[136:139], v[188:191], v[92:95]
	v_mfma_f32_16x16x32_bf16 v[88:91], v[148:151], v[188:191], v[88:91]
	v_mfma_f32_16x16x32_bf16 v[76:79], v[136:139], v[196:199], v[76:79]
	v_mfma_f32_16x16x32_bf16 v[72:75], v[148:151], v[196:199], v[72:75]
	v_mfma_f32_16x16x32_bf16 v[124:127], v[144:147], v[176:179], v[124:127]
	v_mfma_f32_16x16x32_bf16 v[120:123], v[152:155], v[176:179], v[120:123]
	v_mfma_f32_16x16x32_bf16 v[108:111], v[144:147], v[184:187], v[108:111]
	v_mfma_f32_16x16x32_bf16 v[104:107], v[152:155], v[184:187], v[104:107]
	v_mfma_f32_16x16x32_bf16 v[92:95], v[144:147], v[192:195], v[92:95]
	v_mfma_f32_16x16x32_bf16 v[88:91], v[152:155], v[192:195], v[88:91]
	v_mfma_f32_16x16x32_bf16 v[76:79], v[144:147], v[200:203], v[76:79]
	v_mfma_f32_16x16x32_bf16 v[72:75], v[152:155], v[200:203], v[72:75]
	s_setprio 0
	s_setprio 1
	v_mfma_f32_16x16x32_bf16 v[116:119], v[156:159], v[172:175], v[116:119]
	v_mfma_f32_16x16x32_bf16 v[112:115], v[164:167], v[172:175], v[112:115]
	v_mfma_f32_16x16x32_bf16 v[100:103], v[156:159], v[180:183], v[100:103]
	v_mfma_f32_16x16x32_bf16 v[96:99], v[164:167], v[180:183], v[96:99]
	v_mfma_f32_16x16x32_bf16 v[84:87], v[156:159], v[188:191], v[84:87]
	v_mfma_f32_16x16x32_bf16 v[80:83], v[164:167], v[188:191], v[80:83]
	v_mfma_f32_16x16x32_bf16 v[68:71], v[156:159], v[196:199], v[68:71]
	v_mfma_f32_16x16x32_bf16 v[64:67], v[164:167], v[196:199], v[64:67]
	v_mfma_f32_16x16x32_bf16 v[116:119], v[160:163], v[176:179], v[116:119]
	v_mfma_f32_16x16x32_bf16 v[112:115], v[168:171], v[176:179], v[112:115]
	v_mfma_f32_16x16x32_bf16 v[100:103], v[160:163], v[184:187], v[100:103]
	v_mfma_f32_16x16x32_bf16 v[96:99], v[168:171], v[184:187], v[96:99]
	v_mfma_f32_16x16x32_bf16 v[84:87], v[160:163], v[192:195], v[84:87]
	v_mfma_f32_16x16x32_bf16 v[80:83], v[168:171], v[192:195], v[80:83]
	v_mfma_f32_16x16x32_bf16 v[68:71], v[160:163], v[200:203], v[68:71]
	v_mfma_f32_16x16x32_bf16 v[64:67], v[168:171], v[200:203], v[64:67]
	s_setprio 0
	s_barrier
	s_add_i32 s48, s39, s29
	v_lshl_add_u64 v[204:205], s[20:21], 0, v[128:129]
	s_mov_b32 m0, s48
	ds_read_b128 v[172:175], v143 offset:16384
	ds_read_b128 v[176:179], v143 offset:17408
	ds_read_b128 v[180:183], v143 offset:18432
	ds_read_b128 v[184:187], v143 offset:19456
	ds_read_b128 v[188:191], v143 offset:20480
	ds_read_b128 v[192:195], v143 offset:21504
	ds_read_b128 v[196:199], v143 offset:22528
	ds_read_b128 v[200:203], v143 offset:23552
	global_load_lds_dwordx4 v[204:205], off
	s_add_i32 m0, s48, 0x2000
	s_add_u32 s48, s20, 0x4000
	v_lshl_add_u64 v[204:205], s[20:21], 0, v[130:131]
	s_addc_u32 s49, s21, 0
	s_add_i32 s50, s40, s29
	global_load_lds_dwordx4 v[204:205], off
	v_lshl_add_u64 v[204:205], s[48:49], 0, v[128:129]
	s_mov_b32 m0, s50
	s_nop 0
	global_load_lds_dwordx4 v[204:205], off
	v_lshl_add_u64 v[204:205], s[48:49], 0, v[130:131]
	s_add_i32 m0, s50, 0x2000
	s_nop 0
	global_load_lds_dwordx4 v[204:205], off
	v_lshl_add_u64 v[204:205], s[22:23], 0, v[128:129]
	s_mov_b32 m0, s30
	s_nop 0
	global_load_lds_dwordx4 v[204:205], off
	v_lshl_add_u64 v[204:205], s[22:23], 0, v[130:131]
	s_mov_b32 m0, s31
	s_nop 0
	global_load_lds_dwordx4 v[204:205], off
	s_waitcnt vmcnt(8)
	s_waitcnt lgkmcnt(0)
	s_barrier
; #define PG8_STAGE(bufoff, gbase, voff) do { _Pragma("unroll") for (int _i = 0; _i < 2; ++_i) \
;         __builtin_amdgcn_global_load_lds((const unsigned*)((const char*)(gbase) + (voff)[_i]), (LAS unsigned*)(lds + (bufoff) + ldsw + _i * 8192), 16, 0, 0); } while (0)
; #define PG8_LDA(dst, b, h) do { _Pragma("unroll") for (int m = 0; m < 4; ++m) _Pragma("unroll") for (int k = 0; k < 2; ++k) dst[m][k] = *(const LAS bf16x8*)(lds + PG8_SA(b, h) + aoff + m * 2048 + k * 1024); } while (0)
; #define PG8_LDB(dst, b, h) do { _Pragma("unroll") for (int n = 0; n < 2; ++n) _Pragma("unroll") for (int k = 0; k < 2; ++k) dst[n][k] = *(const LAS bf16x8*)(lds + PG8_SB(b, h) + boff + n * 2048 + k * 1024); } while (0)
; #define PG8_MMA(ai, bj, At, Bt) do { __builtin_amdgcn_s_setprio(1); _Pragma("unroll") for (int m = 0; m < 4; ++m) _Pragma("unroll") for (int n = 0; n < 2; ++n) _Pragma("unroll") for (int k = 0; k < 2; ++k) \
;         acc[ai][bj][m][n] = __builtin_amdgcn_mfma_f32_16x16x32_bf16(Bt[n][k], At[m][k], acc[ai][bj][m][n], 0, 0, 0); __builtin_amdgcn_s_setprio(0); } while (0)
; #define PG8_WAIT_V(n) asm volatile("s_waitcnt vmcnt(" #n ")" ::: "memory")
; #define PG8_WAIT_L(n) asm volatile("s_waitcnt lgkmcnt(" #n ")" ::: "memory")
; #define PG8_BAR __builtin_amdgcn_s_barrier()
; #define PG8_SCHED __builtin_amdgcn_sched_barrier(0)
; template <class Epi, bool HALO>
; __device__ __forceinline__ void gemm_phase(LAS unsigned char* lds, const Gemm g, const StaticOrder& S, const Epi& E) {
;     ...
;             PG8_WAIT_V(8); PG8_WAIT_L(0); PG8_BAR; PG8_MMA(1, 0, At, B0); PG8_MMA(1, 1, At, B1); PG8_BAR; PG8_SCHED;
;             PG8_LDB(B0, 1, 0); PG8_LDB(B1, 1, 1); PG8_SCHED; PG8_LDA(At, 1, 0); PG8_STAGE(PG8_SA(0, 1), a2 + hstepA, voffA);
;             PG8_WAIT_V(8); PG8_WAIT_L(0); PG8_BAR; PG8_MMA(0, 0, At, B0); PG8_MMA(0, 1, At, B1); PG8_BAR; PG8_SCHED;
	s_setprio 1
	s_waitcnt lgkmcnt(0)
	v_mfma_f32_16x16x32_bf16 v[60:63], v[136:139], v[172:175], v[60:63]
	v_mfma_f32_16x16x32_bf16 v[56:59], v[148:151], v[172:175], v[56:59]
	v_mfma_f32_16x16x32_bf16 v[44:47], v[136:139], v[180:183], v[44:47]
	v_mfma_f32_16x16x32_bf16 v[40:43], v[148:151], v[180:183], v[40:43]
	v_mfma_f32_16x16x32_bf16 v[28:31], v[136:139], v[188:191], v[28:31]
	v_mfma_f32_16x16x32_bf16 v[24:27], v[148:151], v[188:191], v[24:27]
	v_mfma_f32_16x16x32_bf16 v[12:15], v[136:139], v[196:199], v[12:15]
	v_mfma_f32_16x16x32_bf16 v[8:11], v[148:151], v[196:199], v[8:11]
	v_mfma_f32_16x16x32_bf16 v[60:63], v[144:147], v[176:179], v[60:63]
	v_mfma_f32_16x16x32_bf16 v[56:59], v[152:155], v[176:179], v[56:59]
	v_mfma_f32_16x16x32_bf16 v[44:47], v[144:147], v[184:187], v[44:47]
	v_mfma_f32_16x16x32_bf16 v[40:43], v[152:155], v[184:187], v[40:43]
	v_mfma_f32_16x16x32_bf16 v[28:31], v[144:147], v[192:195], v[28:31]
	v_mfma_f32_16x16x32_bf16 v[24:27], v[152:155], v[192:195], v[24:27]
	v_mfma_f32_16x16x32_bf16 v[12:15], v[144:147], v[200:203], v[12:15]
	v_mfma_f32_16x16x32_bf16 v[8:11], v[152:155], v[200:203], v[8:11]
	s_setprio 0
	s_setprio 1
	v_mfma_f32_16x16x32_bf16 v[52:55], v[156:159], v[172:175], v[52:55]
	v_mfma_f32_16x16x32_bf16 v[48:51], v[164:167], v[172:175], v[48:51]
	v_mfma_f32_16x16x32_bf16 v[36:39], v[156:159], v[180:183], v[36:39]
	v_mfma_f32_16x16x32_bf16 v[32:35], v[164:167], v[180:183], v[32:35]
	v_mfma_f32_16x16x32_bf16 v[20:23], v[156:159], v[188:191], v[20:23]
	v_mfma_f32_16x16x32_bf16 v[16:19], v[164:167], v[188:191], v[16:19]
	v_mfma_f32_16x16x32_bf16 v[4:7], v[156:159], v[196:199], v[4:7]
	v_mfma_f32_16x16x32_bf16 v[0:3], v[164:167], v[196:199], v[0:3]
	v_mfma_f32_16x16x32_bf16 v[52:55], v[160:163], v[176:179], v[52:55]
	v_mfma_f32_16x16x32_bf16 v[48:51], v[168:171], v[176:179], v[48:51]
	v_mfma_f32_16x16x32_bf16 v[36:39], v[160:163], v[184:187], v[36:39]
	v_mfma_f32_16x16x32_bf16 v[32:35], v[168:171], v[184:187], v[32:35]
	v_mfma_f32_16x16x32_bf16 v[20:23], v[160:163], v[192:195], v[20:23]
	v_mfma_f32_16x16x32_bf16 v[16:19], v[168:171], v[192:195], v[16:19]
	v_mfma_f32_16x16x32_bf16 v[4:7], v[160:163], v[200:203], v[4:7]
	v_mfma_f32_16x16x32_bf16 v[0:3], v[168:171], v[200:203], v[0:3]
	s_setprio 0
	s_barrier
	s_add_i32 s48, 0, 0x18000
	s_add_i32 s49, 0, 0x1c000
	v_add_u32_e32 v152, s48, v140
	v_add_u32_e32 v168, s49, v140
	ds_read_b128 v[136:139], v152
	ds_read_b128 v[144:147], v152 offset:1024
	ds_read_b128 v[148:151], v152 offset:2048
	ds_read_b128 v[152:155], v152 offset:3072
	ds_read_b128 v[156:159], v168
	ds_read_b128 v[160:163], v168 offset:1024
	ds_read_b128 v[164:167], v168 offset:2048
	ds_read_b128 v[168:171], v168 offset:3072
	s_add_u32 s22, s22, 0x4000
	s_addc_u32 s23, s23, 0
	s_mov_b32 m0, s33
	v_lshl_add_u64 v[204:205], s[22:23], 0, v[128:129]
	ds_read_b128 v[172:175], v143 offset:32768
	ds_read_b128 v[176:179], v143 offset:33792
	ds_read_b128 v[180:183], v143 offset:34816
	ds_read_b128 v[184:187], v143 offset:35840
	ds_read_b128 v[188:191], v143 offset:36864
	ds_read_b128 v[192:195], v143 offset:37888
	ds_read_b128 v[196:199], v143 offset:38912
	ds_read_b128 v[200:203], v143 offset:39936
	global_load_lds_dwordx4 v[204:205], off
	v_lshl_add_u64 v[204:205], s[22:23], 0, v[130:131]
	s_mov_b32 m0, s34
	s_nop 0
	global_load_lds_dwordx4 v[204:205], off
	s_waitcnt vmcnt(8)
	s_waitcnt lgkmcnt(0)
	s_barrier
	s_setprio 1
	s_waitcnt lgkmcnt(0)
	v_mfma_f32_16x16x32_bf16 v[124:127], v[136:139], v[172:175], v[124:127]
	v_mfma_f32_16x16x32_bf16 v[120:123], v[148:151], v[172:175], v[120:123]
	v_mfma_f32_16x16x32_bf16 v[108:111], v[136:139], v[180:183], v[108:111]
	v_mfma_f32_16x16x32_bf16 v[104:107], v[148:151], v[180:183], v[104:107]
	v_mfma_f32_16x16x32_bf16 v[92:95], v[136:139], v[188:191], v[92:95]
	v_mfma_f32_16x16x32_bf16 v[88:91], v[148:151], v[188:191], v[88:91]
	v_mfma_f32_16x16x32_bf16 v[76:79], v[136:139], v[196:199], v[76:79]
	v_mfma_f32_16x16x32_bf16 v[72:75], v[148:151], v[196:199], v[72:75]
	v_mfma_f32_16x16x32_bf16 v[124:127], v[144:147], v[176:179], v[124:127]
	v_mfma_f32_16x16x32_bf16 v[120:123], v[152:155], v[176:179], v[120:123]
	v_mfma_f32_16x16x32_bf16 v[108:111], v[144:147], v[184:187], v[108:111]
	v_mfma_f32_16x16x32_bf16 v[104:107], v[152:155], v[184:187], v[104:107]
	v_mfma_f32_16x16x32_bf16 v[92:95], v[144:147], v[192:195], v[92:95]
	v_mfma_f32_16x16x32_bf16 v[88:91], v[152:155], v[192:195], v[88:91]
	v_mfma_f32_16x16x32_bf16 v[76:79], v[144:147], v[200:203], v[76:79]
	v_mfma_f32_16x16x32_bf16 v[72:75], v[152:155], v[200:203], v[72:75]
	s_setprio 0
	s_setprio 1
	v_mfma_f32_16x16x32_bf16 v[116:119], v[156:159], v[172:175], v[116:119]
	v_mfma_f32_16x16x32_bf16 v[112:115], v[164:167], v[172:175], v[112:115]
	v_mfma_f32_16x16x32_bf16 v[100:103], v[156:159], v[180:183], v[100:103]
	v_mfma_f32_16x16x32_bf16 v[96:99], v[164:167], v[180:183], v[96:99]
	v_mfma_f32_16x16x32_bf16 v[84:87], v[156:159], v[188:191], v[84:87]
	v_mfma_f32_16x16x32_bf16 v[80:83], v[164:167], v[188:191], v[80:83]
	v_mfma_f32_16x16x32_bf16 v[68:71], v[156:159], v[196:199], v[68:71]
	v_mfma_f32_16x16x32_bf16 v[64:67], v[164:167], v[196:199], v[64:67]
	v_mfma_f32_16x16x32_bf16 v[116:119], v[160:163], v[176:179], v[116:119]
	v_mfma_f32_16x16x32_bf16 v[112:115], v[168:171], v[176:179], v[112:115]
	v_mfma_f32_16x16x32_bf16 v[100:103], v[160:163], v[184:187], v[100:103]
	v_mfma_f32_16x16x32_bf16 v[96:99], v[168:171], v[184:187], v[96:99]
	v_mfma_f32_16x16x32_bf16 v[84:87], v[160:163], v[192:195], v[84:87]
	v_mfma_f32_16x16x32_bf16 v[80:83], v[168:171], v[192:195], v[80:83]
	v_mfma_f32_16x16x32_bf16 v[68:71], v[160:163], v[200:203], v[68:71]
	v_mfma_f32_16x16x32_bf16 v[64:67], v[168:171], v[200:203], v[64:67]
	s_setprio 0
	s_barrier
; #define PG8_STAGE(bufoff, gbase, voff) do { _Pragma("unroll") for (int _i = 0; _i < 2; ++_i) \
;         __builtin_amdgcn_global_load_lds((const unsigned*)((const char*)(gbase) + (voff)[_i]), (LAS unsigned*)(lds + (bufoff) + ldsw + _i * 8192), 16, 0, 0); } while (0)
; #define PG8_LDA(dst, b, h) do { _Pragma("unroll") for (int m = 0; m < 4; ++m) _Pragma("unroll") for (int k = 0; k < 2; ++k) dst[m][k] = *(const LAS bf16x8*)(lds + PG8_SA(b, h) + aoff + m * 2048 + k * 1024); } while (0)
; #define PG8_MMA(ai, bj, At, Bt) do { __builtin_amdgcn_s_setprio(1); _Pragma("unroll") for (int m = 0; m < 4; ++m) _Pragma("unroll") for (int n = 0; n < 2; ++n) _Pragma("unroll") for (int k = 0; k < 2; ++k) \
;         acc[ai][bj][m][n] = __builtin_amdgcn_mfma_f32_16x16x32_bf16(Bt[n][k], At[m][k], acc[ai][bj][m][n], 0, 0, 0); __builtin_amdgcn_s_setprio(0); } while (0)
; #define PG8_WAIT_V(n) asm volatile("s_waitcnt vmcnt(" #n ")" ::: "memory")
; #define PG8_WAIT_L(n) asm volatile("s_waitcnt lgkmcnt(" #n ")" ::: "memory")
; #define PG8_BAR __builtin_amdgcn_s_barrier()
; #define PG8_SCHED __builtin_amdgcn_sched_barrier(0)
; template <class Epi, bool HALO>
; __device__ __forceinline__ void gemm_phase(LAS unsigned char* lds, const Gemm g, const StaticOrder& S, const Epi& E) {
;     ...
;             PG8_LDA(At, 1, 1); PG8_STAGE(PG8_SB(1, 0), b3, voffB); PG8_STAGE(PG8_SB(1, 1), b3 + hstepB, voffB); PG8_STAGE(PG8_SA(1, 0), a3, voffA);
;             PG8_WAIT_V(8); PG8_WAIT_L(0); PG8_BAR; PG8_MMA(1, 0, At, B0); PG8_MMA(1, 1, At, B1); PG8_BAR; PG8_SCHED;
;         }
;         if (wr == 0) PG8_BAR;
	s_add_u32 s22, s20, 0x8000
	s_addc_u32 s23, s21, 0
	s_add_i32 s48, s48, s29
	v_lshl_add_u64 v[204:205], s[22:23], 0, v[128:129]
	s_mov_b32 m0, s48
	ds_read_b128 v[172:175], v143 offset:49152
	ds_read_b128 v[176:179], v143 offset:50176
	ds_read_b128 v[180:183], v143 offset:51200
	ds_read_b128 v[184:187], v143 offset:52224
	ds_read_b128 v[188:191], v143 offset:53248
	ds_read_b128 v[192:195], v143 offset:54272
	ds_read_b128 v[196:199], v143 offset:55296
	ds_read_b128 v[200:203], v143 offset:56320
	global_load_lds_dwordx4 v[204:205], off
	s_add_i32 m0, s48, 0x2000
	s_add_u32 s20, s20, 0xc000
	v_lshl_add_u64 v[204:205], s[22:23], 0, v[130:131]
	s_addc_u32 s21, s21, 0
	s_add_i32 s22, s49, s29
	global_load_lds_dwordx4 v[204:205], off
	v_lshl_add_u64 v[204:205], s[20:21], 0, v[128:129]
	s_mov_b32 m0, s22
	s_nop 0
	global_load_lds_dwordx4 v[204:205], off
	v_lshl_add_u64 v[204:205], s[20:21], 0, v[130:131]
	s_add_i32 m0, s22, 0x2000
	s_nop 0
	global_load_lds_dwordx4 v[204:205], off
	v_lshl_add_u64 v[204:205], s[18:19], 0, v[128:129]
	s_mov_b32 m0, s37
	s_nop 0
	global_load_lds_dwordx4 v[204:205], off
	v_lshl_add_u64 v[204:205], s[18:19], 0, v[130:131]
	s_mov_b32 m0, s38
	s_nop 0
	global_load_lds_dwordx4 v[204:205], off
	s_waitcnt vmcnt(8)
	s_waitcnt lgkmcnt(0)
	s_barrier
	s_setprio 1
	s_waitcnt lgkmcnt(0)
	v_mfma_f32_16x16x32_bf16 v[60:63], v[136:139], v[172:175], v[60:63]
	v_mfma_f32_16x16x32_bf16 v[56:59], v[148:151], v[172:175], v[56:59]
	v_mfma_f32_16x16x32_bf16 v[44:47], v[136:139], v[180:183], v[44:47]
	v_mfma_f32_16x16x32_bf16 v[40:43], v[148:151], v[180:183], v[40:43]
	v_mfma_f32_16x16x32_bf16 v[28:31], v[136:139], v[188:191], v[28:31]
	v_mfma_f32_16x16x32_bf16 v[24:27], v[148:151], v[188:191], v[24:27]
	v_mfma_f32_16x16x32_bf16 v[12:15], v[136:139], v[196:199], v[12:15]
	v_mfma_f32_16x16x32_bf16 v[8:11], v[148:151], v[196:199], v[8:11]
	v_mfma_f32_16x16x32_bf16 v[60:63], v[144:147], v[176:179], v[60:63]
	v_mfma_f32_16x16x32_bf16 v[56:59], v[152:155], v[176:179], v[56:59]
	v_mfma_f32_16x16x32_bf16 v[44:47], v[144:147], v[184:187], v[44:47]
	v_mfma_f32_16x16x32_bf16 v[40:43], v[152:155], v[184:187], v[40:43]
	v_mfma_f32_16x16x32_bf16 v[28:31], v[144:147], v[192:195], v[28:31]
	v_mfma_f32_16x16x32_bf16 v[24:27], v[152:155], v[192:195], v[24:27]
	v_mfma_f32_16x16x32_bf16 v[12:15], v[144:147], v[200:203], v[12:15]
	v_mfma_f32_16x16x32_bf16 v[8:11], v[152:155], v[200:203], v[8:11]
	s_setprio 0
	s_setprio 1
	v_mfma_f32_16x16x32_bf16 v[52:55], v[156:159], v[172:175], v[52:55]
	v_mfma_f32_16x16x32_bf16 v[48:51], v[164:167], v[172:175], v[48:51]
	v_mfma_f32_16x16x32_bf16 v[36:39], v[156:159], v[180:183], v[36:39]
	v_mfma_f32_16x16x32_bf16 v[32:35], v[164:167], v[180:183], v[32:35]
	v_mfma_f32_16x16x32_bf16 v[20:23], v[156:159], v[188:191], v[20:23]
	v_mfma_f32_16x16x32_bf16 v[16:19], v[164:167], v[188:191], v[16:19]
	v_mfma_f32_16x16x32_bf16 v[4:7], v[156:159], v[196:199], v[4:7]
	v_mfma_f32_16x16x32_bf16 v[0:3], v[164:167], v[196:199], v[0:3]
	v_mfma_f32_16x16x32_bf16 v[52:55], v[160:163], v[176:179], v[52:55]
	v_mfma_f32_16x16x32_bf16 v[48:51], v[168:171], v[176:179], v[48:51]
	v_mfma_f32_16x16x32_bf16 v[36:39], v[160:163], v[184:187], v[36:39]
	v_mfma_f32_16x16x32_bf16 v[32:35], v[168:171], v[184:187], v[32:35]
	v_mfma_f32_16x16x32_bf16 v[20:23], v[160:163], v[192:195], v[20:23]
	v_mfma_f32_16x16x32_bf16 v[16:19], v[168:171], v[192:195], v[16:19]
	s_add_i32 s47, s47, 2
	s_add_u32 s16, s16, 0x10000
	s_addc_u32 s17, s17, 0
	s_add_u32 s45, s45, 0x10000
	s_addc_u32 s46, s46, 0
	s_cmp_gt_u32 s47, 41
	v_mfma_f32_16x16x32_bf16 v[4:7], v[160:163], v[200:203], v[4:7]
	v_mfma_f32_16x16x32_bf16 v[0:3], v[168:171], v[200:203], v[0:3]
	s_setprio 0
	s_barrier
	s_cbranch_scc0 .LBB0_1407
	s_and_b64 vcc, exec, s[12:13]
	s_cbranch_vccz .LBB0_1410
	s_barrier
